# GEMM K-loops: s_setprio 0 moved from the end of each MFMA segment to just after its closing s_barrier
# baseline (speedup 1.0000x reference)
.LBB0_338:
	v_add_u32_e32 v138, s61, v1
	ds_read_b128 v[148:151], v138
	ds_read_b128 v[152:155], v138 offset:1024
	ds_read_b128 v[156:159], v138 offset:2048
	ds_read_b128 v[160:163], v138 offset:3072
	v_add_u32_e32 v138, s62, v1
	ds_read_b128 v[164:167], v138
	ds_read_b128 v[170:173], v138 offset:1024
	ds_read_b128 v[174:177], v138 offset:2048
	ds_read_b128 v[178:181], v138 offset:3072
	s_add_i32 s44, s4, 2
	s_add_u32 s45, s2, 0x80
	s_addc_u32 s5, s3, 0
	s_cmp_eq_u32 s54, s4
	s_cselect_b32 s4, s36, s45
	s_cselect_b32 s5, s37, s5
	s_cselect_b32 s49, s39, s43
	s_cselect_b32 s48, s38, s42
	v_lshl_add_u64 v[198:199], s[2:3], 0, v[140:141]
	s_add_i32 m0, s81, 0xc000
	ds_read_b128 v[182:185], v169
	ds_read_b128 v[186:189], v169 offset:1024
	ds_read_b128 v[190:193], v169 offset:2048
	ds_read_b128 v[194:197], v169 offset:3072
	ds_read_b128 v[202:205], v169 offset:4096
	ds_read_b128 v[206:209], v169 offset:5120
	ds_read_b128 v[210:213], v169 offset:6144
	ds_read_b128 v[214:217], v169 offset:7168
	global_load_lds_dwordx4 v[198:199], off
	v_lshl_add_u64 v[198:199], s[2:3], 0, v[142:143]
	s_add_i32 m0, s81, 0xe000
	s_nop 0
	global_load_lds_dwordx4 v[198:199], off
	s_waitcnt vmcnt(8)
	s_waitcnt lgkmcnt(0)
	s_barrier
	s_setprio 1
	v_mfma_i32_16x16x64_i8 v[126:129], v[148:151], v[182:185], v[126:129]
	v_mfma_i32_16x16x64_i8 v[122:125], v[156:159], v[182:185], v[122:125]
	v_mfma_i32_16x16x64_i8 v[118:121], v[148:151], v[190:193], v[118:121]
	v_mfma_i32_16x16x64_i8 v[114:117], v[156:159], v[190:193], v[114:117]
	v_mfma_i32_16x16x64_i8 v[106:109], v[148:151], v[202:205], v[106:109]
	v_mfma_i32_16x16x64_i8 v[98:101], v[156:159], v[202:205], v[98:101]
	v_mfma_i32_16x16x64_i8 v[90:93], v[148:151], v[210:213], v[90:93]
	v_mfma_i32_16x16x64_i8 v[82:85], v[156:159], v[210:213], v[82:85]
	v_mfma_i32_16x16x64_i8 v[126:129], v[152:155], v[186:189], v[126:129]
	v_mfma_i32_16x16x64_i8 v[122:125], v[160:163], v[186:189], v[122:125]
	v_mfma_i32_16x16x64_i8 v[118:121], v[152:155], v[194:197], v[118:121]
	v_mfma_i32_16x16x64_i8 v[114:117], v[160:163], v[194:197], v[114:117]
	v_mfma_i32_16x16x64_i8 v[106:109], v[152:155], v[206:209], v[106:109]
	v_mfma_i32_16x16x64_i8 v[98:101], v[160:163], v[206:209], v[98:101]
	v_mfma_i32_16x16x64_i8 v[90:93], v[152:155], v[214:217], v[90:93]
	v_mfma_i32_16x16x64_i8 v[82:85], v[160:163], v[214:217], v[82:85]
	v_mfma_i32_16x16x64_i8 v[110:113], v[164:167], v[182:185], v[110:113]
	v_mfma_i32_16x16x64_i8 v[102:105], v[174:177], v[182:185], v[102:105]
	v_mfma_i32_16x16x64_i8 v[94:97], v[164:167], v[190:193], v[94:97]
	v_mfma_i32_16x16x64_i8 v[86:89], v[174:177], v[190:193], v[86:89]
	v_mfma_i32_16x16x64_i8 v[78:81], v[164:167], v[202:205], v[78:81]
	v_mfma_i32_16x16x64_i8 v[74:77], v[174:177], v[202:205], v[74:77]
	v_mfma_i32_16x16x64_i8 v[70:73], v[164:167], v[210:213], v[70:73]
	v_mfma_i32_16x16x64_i8 v[66:69], v[174:177], v[210:213], v[66:69]
	v_mfma_i32_16x16x64_i8 v[110:113], v[170:173], v[186:189], v[110:113]
	v_mfma_i32_16x16x64_i8 v[102:105], v[178:181], v[186:189], v[102:105]
	v_mfma_i32_16x16x64_i8 v[94:97], v[170:173], v[194:197], v[94:97]
	v_mfma_i32_16x16x64_i8 v[86:89], v[178:181], v[194:197], v[86:89]
	v_mfma_i32_16x16x64_i8 v[78:81], v[170:173], v[206:209], v[78:81]
	v_mfma_i32_16x16x64_i8 v[74:77], v[178:181], v[206:209], v[74:77]
	v_mfma_i32_16x16x64_i8 v[70:73], v[170:173], v[214:217], v[70:73]
	v_mfma_i32_16x16x64_i8 v[66:69], v[178:181], v[214:217], v[66:69]
	s_barrier
	s_setprio 0
	s_add_i32 s45, s61, s67
	v_lshl_add_u64 v[198:199], s[48:49], 0, v[132:133]
	s_mov_b32 m0, s45
	ds_read_b128 v[182:185], v169 offset:16384
	ds_read_b128 v[186:189], v169 offset:17408
	ds_read_b128 v[190:193], v169 offset:18432
	ds_read_b128 v[194:197], v169 offset:19456
	ds_read_b128 v[202:205], v169 offset:20480
	ds_read_b128 v[206:209], v169 offset:21504
	ds_read_b128 v[210:213], v169 offset:22528
	ds_read_b128 v[214:217], v169 offset:23552
	global_load_lds_dwordx4 v[198:199], off
	s_add_i32 m0, s45, 0x2000
	v_lshl_add_u64 v[218:219], s[48:49], 0, v[136:137]
	s_add_u32 s48, s48, s16
	s_addc_u32 s49, s49, s17
	s_add_i32 s45, s62, s67
	global_load_lds_dwordx4 v[218:219], off
	v_lshl_add_u64 v[220:221], s[48:49], 0, v[132:133]
	s_mov_b32 m0, s45
	v_lshl_add_u64 v[222:223], s[48:49], 0, v[136:137]
	global_load_lds_dwordx4 v[220:221], off
	s_add_i32 m0, s45, 0x2000
	v_lshl_add_u64 v[224:225], s[4:5], 0, v[130:131]
	global_load_lds_dwordx4 v[222:223], off
	s_mov_b32 m0, s81
	v_lshl_add_u64 v[226:227], s[4:5], 0, v[134:135]
	global_load_lds_dwordx4 v[224:225], off
	s_mov_b32 m0, s90
	s_nop 0
	global_load_lds_dwordx4 v[226:227], off
	s_waitcnt vmcnt(8)
	s_waitcnt lgkmcnt(0)
	s_barrier
	s_setprio 1
	v_mfma_i32_16x16x64_i8 v[62:65], v[148:151], v[182:185], v[62:65]
	v_mfma_i32_16x16x64_i8 v[58:61], v[156:159], v[182:185], v[58:61]
	v_mfma_i32_16x16x64_i8 v[54:57], v[148:151], v[190:193], v[54:57]
	v_mfma_i32_16x16x64_i8 v[50:53], v[156:159], v[190:193], v[50:53]
	v_mfma_i32_16x16x64_i8 v[42:45], v[148:151], v[202:205], v[42:45]
	v_mfma_i32_16x16x64_i8 v[34:37], v[156:159], v[202:205], v[34:37]
	v_mfma_i32_16x16x64_i8 v[26:29], v[148:151], v[210:213], v[26:29]
	v_mfma_i32_16x16x64_i8 v[18:21], v[156:159], v[210:213], v[18:21]
	v_mfma_i32_16x16x64_i8 v[62:65], v[152:155], v[186:189], v[62:65]
	v_mfma_i32_16x16x64_i8 v[58:61], v[160:163], v[186:189], v[58:61]
	v_mfma_i32_16x16x64_i8 v[54:57], v[152:155], v[194:197], v[54:57]
	v_mfma_i32_16x16x64_i8 v[50:53], v[160:163], v[194:197], v[50:53]
	v_mfma_i32_16x16x64_i8 v[42:45], v[152:155], v[206:209], v[42:45]
	v_mfma_i32_16x16x64_i8 v[34:37], v[160:163], v[206:209], v[34:37]
	v_mfma_i32_16x16x64_i8 v[26:29], v[152:155], v[214:217], v[26:29]
	v_mfma_i32_16x16x64_i8 v[18:21], v[160:163], v[214:217], v[18:21]
	v_mfma_i32_16x16x64_i8 v[46:49], v[164:167], v[182:185], v[46:49]
	v_mfma_i32_16x16x64_i8 v[38:41], v[174:177], v[182:185], v[38:41]
	v_mfma_i32_16x16x64_i8 v[30:33], v[164:167], v[190:193], v[30:33]
	v_mfma_i32_16x16x64_i8 v[22:25], v[174:177], v[190:193], v[22:25]
	v_mfma_i32_16x16x64_i8 v[14:17], v[164:167], v[202:205], v[14:17]
	v_mfma_i32_16x16x64_i8 v[10:13], v[174:177], v[202:205], v[10:13]
	v_mfma_i32_16x16x64_i8 v[6:9], v[164:167], v[210:213], v[6:9]
	v_mfma_i32_16x16x64_i8 v[2:5], v[174:177], v[210:213], v[2:5]
	v_mfma_i32_16x16x64_i8 v[46:49], v[170:173], v[186:189], v[46:49]
	v_mfma_i32_16x16x64_i8 v[38:41], v[178:181], v[186:189], v[38:41]
	v_mfma_i32_16x16x64_i8 v[30:33], v[170:173], v[194:197], v[30:33]
	v_mfma_i32_16x16x64_i8 v[22:25], v[178:181], v[194:197], v[22:25]
	v_mfma_i32_16x16x64_i8 v[14:17], v[170:173], v[206:209], v[14:17]
	v_mfma_i32_16x16x64_i8 v[10:13], v[178:181], v[206:209], v[10:13]
	v_mfma_i32_16x16x64_i8 v[6:9], v[170:173], v[214:217], v[6:9]
	v_mfma_i32_16x16x64_i8 v[2:5], v[178:181], v[214:217], v[2:5]
	s_barrier
	s_setprio 0
	s_add_i32 s45, 0, 0x18000
	v_add_u32_e32 v138, s45, v1
	s_add_i32 s47, 0, 0x1c000
	ds_read_b128 v[148:151], v138
	ds_read_b128 v[152:155], v138 offset:1024
	ds_read_b128 v[156:159], v138 offset:2048
	ds_read_b128 v[160:163], v138 offset:3072
	v_add_u32_e32 v138, s47, v1
	ds_read_b128 v[164:167], v138
	ds_read_b128 v[170:173], v138 offset:1024
	ds_read_b128 v[174:177], v138 offset:2048
	ds_read_b128 v[178:181], v138 offset:3072
	s_add_u32 s4, s4, s16
	s_addc_u32 s5, s5, s17
	s_mov_b32 m0, s91
	v_lshl_add_u64 v[228:229], s[4:5], 0, v[130:131]
	ds_read_b128 v[182:185], v169 offset:32768
	ds_read_b128 v[186:189], v169 offset:33792
	ds_read_b128 v[190:193], v169 offset:34816
	ds_read_b128 v[194:197], v169 offset:35840
	ds_read_b128 v[202:205], v169 offset:36864
	ds_read_b128 v[206:209], v169 offset:37888
	ds_read_b128 v[210:213], v169 offset:38912
	ds_read_b128 v[214:217], v169 offset:39936
	global_load_lds_dwordx4 v[228:229], off
	v_lshl_add_u64 v[228:229], s[4:5], 0, v[134:135]
	s_mov_b32 m0, s92
	s_nop 0
	global_load_lds_dwordx4 v[228:229], off
	s_waitcnt vmcnt(8)
	s_waitcnt lgkmcnt(0)
	s_barrier
	s_setprio 1
	v_mfma_i32_16x16x64_i8 v[126:129], v[148:151], v[182:185], v[126:129]
	v_mfma_i32_16x16x64_i8 v[122:125], v[156:159], v[182:185], v[122:125]
	v_mfma_i32_16x16x64_i8 v[118:121], v[148:151], v[190:193], v[118:121]
	v_mfma_i32_16x16x64_i8 v[114:117], v[156:159], v[190:193], v[114:117]
	v_mfma_i32_16x16x64_i8 v[106:109], v[148:151], v[202:205], v[106:109]
	v_mfma_i32_16x16x64_i8 v[98:101], v[156:159], v[202:205], v[98:101]
	v_mfma_i32_16x16x64_i8 v[90:93], v[148:151], v[210:213], v[90:93]
	v_mfma_i32_16x16x64_i8 v[82:85], v[156:159], v[210:213], v[82:85]
	v_mfma_i32_16x16x64_i8 v[126:129], v[152:155], v[186:189], v[126:129]
	v_mfma_i32_16x16x64_i8 v[122:125], v[160:163], v[186:189], v[122:125]
	v_mfma_i32_16x16x64_i8 v[118:121], v[152:155], v[194:197], v[118:121]
	v_mfma_i32_16x16x64_i8 v[114:117], v[160:163], v[194:197], v[114:117]
	v_mfma_i32_16x16x64_i8 v[106:109], v[152:155], v[206:209], v[106:109]
	v_mfma_i32_16x16x64_i8 v[98:101], v[160:163], v[206:209], v[98:101]
	v_mfma_i32_16x16x64_i8 v[90:93], v[152:155], v[214:217], v[90:93]
	v_mfma_i32_16x16x64_i8 v[82:85], v[160:163], v[214:217], v[82:85]
	v_mfma_i32_16x16x64_i8 v[110:113], v[164:167], v[182:185], v[110:113]
	v_mfma_i32_16x16x64_i8 v[102:105], v[174:177], v[182:185], v[102:105]
	v_mfma_i32_16x16x64_i8 v[94:97], v[164:167], v[190:193], v[94:97]
	v_mfma_i32_16x16x64_i8 v[86:89], v[174:177], v[190:193], v[86:89]
	v_mfma_i32_16x16x64_i8 v[78:81], v[164:167], v[202:205], v[78:81]
	v_mfma_i32_16x16x64_i8 v[74:77], v[174:177], v[202:205], v[74:77]
	v_mfma_i32_16x16x64_i8 v[70:73], v[164:167], v[210:213], v[70:73]
	v_mfma_i32_16x16x64_i8 v[66:69], v[174:177], v[210:213], v[66:69]
	v_mfma_i32_16x16x64_i8 v[110:113], v[170:173], v[186:189], v[110:113]
	v_mfma_i32_16x16x64_i8 v[102:105], v[178:181], v[186:189], v[102:105]
	v_mfma_i32_16x16x64_i8 v[94:97], v[170:173], v[194:197], v[94:97]
	v_mfma_i32_16x16x64_i8 v[86:89], v[178:181], v[194:197], v[86:89]
	v_mfma_i32_16x16x64_i8 v[78:81], v[170:173], v[206:209], v[78:81]
	v_mfma_i32_16x16x64_i8 v[74:77], v[178:181], v[206:209], v[74:77]
	v_mfma_i32_16x16x64_i8 v[70:73], v[170:173], v[214:217], v[70:73]
	v_mfma_i32_16x16x64_i8 v[66:69], v[178:181], v[214:217], v[66:69]
	s_barrier
	s_setprio 0
	s_add_i32 s4, s45, s67
	v_lshl_add_u64 v[198:199], v[198:199], 0, s[26:27]
	s_mov_b32 m0, s4
	ds_read_b128 v[182:185], v169 offset:49152
	ds_read_b128 v[186:189], v169 offset:50176
	ds_read_b128 v[190:193], v169 offset:51200
	ds_read_b128 v[194:197], v169 offset:52224
	ds_read_b128 v[202:205], v169 offset:53248
	ds_read_b128 v[206:209], v169 offset:54272
	ds_read_b128 v[210:213], v169 offset:55296
	ds_read_b128 v[214:217], v169 offset:56320
	global_load_lds_dwordx4 v[198:199], off
	v_lshl_add_u64 v[198:199], v[218:219], 0, s[26:27]
	s_add_i32 m0, s4, 0x2000
	s_add_i32 s4, s47, s67
	global_load_lds_dwordx4 v[198:199], off
	v_lshl_add_u64 v[198:199], v[220:221], 0, s[26:27]
	s_mov_b32 m0, s4
	s_nop 0
	global_load_lds_dwordx4 v[198:199], off
	v_lshl_add_u64 v[198:199], v[222:223], 0, s[26:27]
	s_add_i32 m0, s4, 0x2000
	s_nop 0
	global_load_lds_dwordx4 v[198:199], off
	v_lshl_add_u64 v[198:199], v[224:225], 0, s[26:27]
	s_mov_b32 m0, s97
	s_nop 0
	global_load_lds_dwordx4 v[198:199], off
	v_lshl_add_u64 v[198:199], v[226:227], 0, s[26:27]
	s_mov_b32 m0, s6
	s_nop 0
	global_load_lds_dwordx4 v[198:199], off
	s_waitcnt vmcnt(8)
	s_waitcnt lgkmcnt(0)
	s_barrier
	s_setprio 1
	v_mfma_i32_16x16x64_i8 v[62:65], v[148:151], v[182:185], v[62:65]
	v_mfma_i32_16x16x64_i8 v[58:61], v[156:159], v[182:185], v[58:61]
	v_mfma_i32_16x16x64_i8 v[54:57], v[148:151], v[190:193], v[54:57]
	v_mfma_i32_16x16x64_i8 v[50:53], v[156:159], v[190:193], v[50:53]
	v_mfma_i32_16x16x64_i8 v[42:45], v[148:151], v[202:205], v[42:45]
	v_mfma_i32_16x16x64_i8 v[34:37], v[156:159], v[202:205], v[34:37]
	v_mfma_i32_16x16x64_i8 v[26:29], v[148:151], v[210:213], v[26:29]
	v_mfma_i32_16x16x64_i8 v[18:21], v[156:159], v[210:213], v[18:21]
	v_mfma_i32_16x16x64_i8 v[62:65], v[152:155], v[186:189], v[62:65]
	v_mfma_i32_16x16x64_i8 v[58:61], v[160:163], v[186:189], v[58:61]
	v_mfma_i32_16x16x64_i8 v[54:57], v[152:155], v[194:197], v[54:57]
	v_mfma_i32_16x16x64_i8 v[50:53], v[160:163], v[194:197], v[50:53]
	v_mfma_i32_16x16x64_i8 v[42:45], v[152:155], v[206:209], v[42:45]
	v_mfma_i32_16x16x64_i8 v[34:37], v[160:163], v[206:209], v[34:37]
	v_mfma_i32_16x16x64_i8 v[26:29], v[152:155], v[214:217], v[26:29]
	v_mfma_i32_16x16x64_i8 v[18:21], v[160:163], v[214:217], v[18:21]
	v_mfma_i32_16x16x64_i8 v[46:49], v[164:167], v[182:185], v[46:49]
	v_mfma_i32_16x16x64_i8 v[38:41], v[174:177], v[182:185], v[38:41]
	v_mfma_i32_16x16x64_i8 v[30:33], v[164:167], v[190:193], v[30:33]
	v_mfma_i32_16x16x64_i8 v[22:25], v[174:177], v[190:193], v[22:25]
	v_mfma_i32_16x16x64_i8 v[14:17], v[164:167], v[202:205], v[14:17]
	v_mfma_i32_16x16x64_i8 v[10:13], v[174:177], v[202:205], v[10:13]
	v_mfma_i32_16x16x64_i8 v[6:9], v[164:167], v[210:213], v[6:9]
	v_mfma_i32_16x16x64_i8 v[2:5], v[174:177], v[210:213], v[2:5]
	v_mfma_i32_16x16x64_i8 v[46:49], v[170:173], v[186:189], v[46:49]
	v_mfma_i32_16x16x64_i8 v[38:41], v[178:181], v[186:189], v[38:41]
	v_mfma_i32_16x16x64_i8 v[30:33], v[170:173], v[194:197], v[30:33]
	v_mfma_i32_16x16x64_i8 v[22:25], v[178:181], v[194:197], v[22:25]
	v_mfma_i32_16x16x64_i8 v[14:17], v[170:173], v[206:209], v[14:17]
	v_mfma_i32_16x16x64_i8 v[10:13], v[178:181], v[206:209], v[10:13]
	v_mfma_i32_16x16x64_i8 v[6:9], v[170:173], v[214:217], v[6:9]
	v_mfma_i32_16x16x64_i8 v[2:5], v[178:181], v[214:217], v[2:5]
	s_barrier
	s_setprio 0
	s_add_u32 s2, s2, 0x100
	s_addc_u32 s3, s3, 0
	s_add_u32 s42, s42, 0x100
	s_addc_u32 s43, s43, 0
	s_cmp_ge_i32 s44, s7
	s_mov_b32 s4, s44
	s_cbranch_scc0 .LBB0_338
	v_cvt_f32_i32_e32 v182, v126
	v_cvt_f32_i32_e32 v183, v127
	v_cvt_f32_i32_e32 v180, v128
	v_cvt_f32_i32_e32 v181, v129
	v_cvt_f32_i32_e32 v184, v122
	v_cvt_f32_i32_e32 v185, v123
	v_cvt_f32_i32_e32 v186, v124
	v_cvt_f32_i32_e32 v187, v125
	v_cvt_f32_i32_e32 v170, v110
	v_cvt_f32_i32_e32 v171, v111
	v_cvt_f32_i32_e32 v174, v112
	v_cvt_f32_i32_e32 v175, v113
	v_cvt_f32_i32_e32 v172, v102
	v_cvt_f32_i32_e32 v173, v103
	v_cvt_f32_i32_e32 v166, v104
	v_cvt_f32_i32_e32 v167, v105
	v_cvt_f32_i32_e32 v162, v118
	v_cvt_f32_i32_e32 v163, v119
	v_cvt_f32_i32_e32 v164, v120
	v_cvt_f32_i32_e32 v165, v121
	v_cvt_f32_i32_e32 v158, v114
	v_cvt_f32_i32_e32 v159, v115
	v_cvt_f32_i32_e32 v160, v116
	v_cvt_f32_i32_e32 v161, v117
	v_cvt_f32_i32_e32 v150, v94
	v_cvt_f32_i32_e32 v151, v95
	v_cvt_f32_i32_e32 v154, v96
	v_cvt_f32_i32_e32 v155, v97
	v_cvt_f32_i32_e32 v128, v86
	v_cvt_f32_i32_e32 v129, v87
	v_cvt_f32_i32_e32 v148, v88
	v_cvt_f32_i32_e32 v149, v89
	v_cvt_f32_i32_e32 v124, v106
	v_cvt_f32_i32_e32 v125, v107
	v_cvt_f32_i32_e32 v126, v108
	v_cvt_f32_i32_e32 v127, v109
	v_cvt_f32_i32_e32 v120, v98
	v_cvt_f32_i32_e32 v121, v99
	v_cvt_f32_i32_e32 v122, v100
	v_cvt_f32_i32_e32 v123, v101
	v_cvt_f32_i32_e32 v114, v78
	v_cvt_f32_i32_e32 v115, v79
	v_cvt_f32_i32_e32 v116, v80
	v_cvt_f32_i32_e32 v117, v81
	v_cvt_f32_i32_e32 v110, v74
	v_cvt_f32_i32_e32 v111, v75
	v_cvt_f32_i32_e32 v112, v76
	v_cvt_f32_i32_e32 v113, v77
	v_cvt_f32_i32_e32 v104, v90
	v_cvt_f32_i32_e32 v105, v91
	v_cvt_f32_i32_e32 v106, v92
	v_cvt_f32_i32_e32 v107, v93
	v_cvt_f32_i32_e32 v100, v82
	v_cvt_f32_i32_e32 v101, v83
	v_cvt_f32_i32_e32 v102, v84
	v_cvt_f32_i32_e32 v103, v85
	v_cvt_f32_i32_e32 v96, v70
	v_cvt_f32_i32_e32 v97, v71
	v_cvt_f32_i32_e32 v98, v72
	v_cvt_f32_i32_e32 v99, v73
	v_cvt_f32_i32_e32 v92, v66
	v_cvt_f32_i32_e32 v93, v67
	v_cvt_f32_i32_e32 v94, v68
	v_cvt_f32_i32_e32 v95, v69
	v_cvt_f32_i32_e32 v86, v62
	v_cvt_f32_i32_e32 v87, v63
	v_cvt_f32_i32_e32 v88, v64
	v_cvt_f32_i32_e32 v89, v65
	v_cvt_f32_i32_e32 v82, v58
	v_cvt_f32_i32_e32 v83, v59
	v_cvt_f32_i32_e32 v84, v60
	v_cvt_f32_i32_e32 v85, v61
	v_cvt_f32_i32_e32 v78, v46
	v_cvt_f32_i32_e32 v79, v47
	v_cvt_f32_i32_e32 v80, v48
	v_cvt_f32_i32_e32 v81, v49
	v_cvt_f32_i32_e32 v74, v38
	v_cvt_f32_i32_e32 v75, v39
	v_cvt_f32_i32_e32 v76, v40
	v_cvt_f32_i32_e32 v77, v41
	v_cvt_f32_i32_e32 v68, v54
	v_cvt_f32_i32_e32 v69, v55
	v_cvt_f32_i32_e32 v70, v56
	v_cvt_f32_i32_e32 v71, v57
	v_cvt_f32_i32_e32 v64, v50
	v_cvt_f32_i32_e32 v65, v51
	v_cvt_f32_i32_e32 v66, v52
	v_cvt_f32_i32_e32 v67, v53
	v_cvt_f32_i32_e32 v60, v30
	v_cvt_f32_i32_e32 v61, v31
	v_cvt_f32_i32_e32 v62, v32
	v_cvt_f32_i32_e32 v63, v33
	v_cvt_f32_i32_e32 v56, v22
	v_cvt_f32_i32_e32 v57, v23
	v_cvt_f32_i32_e32 v58, v24
	v_cvt_f32_i32_e32 v59, v25
	v_cvt_f32_i32_e32 v50, v42
	v_cvt_f32_i32_e32 v51, v43
	v_cvt_f32_i32_e32 v52, v44
	v_cvt_f32_i32_e32 v53, v45
	v_cvt_f32_i32_e32 v46, v34
	v_cvt_f32_i32_e32 v47, v35
	v_cvt_f32_i32_e32 v48, v36
	v_cvt_f32_i32_e32 v49, v37
	v_cvt_f32_i32_e32 v34, v14
	v_cvt_f32_i32_e32 v35, v15
	v_cvt_f32_i32_e32 v36, v16
	v_cvt_f32_i32_e32 v37, v17
	v_cvt_f32_i32_e32 v30, v10
	v_cvt_f32_i32_e32 v31, v11
	v_cvt_f32_i32_e32 v32, v12
	v_cvt_f32_i32_e32 v33, v13
	v_cvt_f32_i32_e32 v22, v26
	v_cvt_f32_i32_e32 v23, v27
	v_cvt_f32_i32_e32 v24, v28
	v_cvt_f32_i32_e32 v25, v29
	v_cvt_f32_i32_e32 v18, v18
	v_cvt_f32_i32_e32 v19, v19
	v_cvt_f32_i32_e32 v20, v20
	v_cvt_f32_i32_e32 v21, v21
	v_cvt_f32_i32_e32 v14, v6
	v_cvt_f32_i32_e32 v15, v7
	v_cvt_f32_i32_e32 v16, v8
	v_cvt_f32_i32_e32 v17, v9
	v_cvt_f32_i32_e32 v10, v2
	v_cvt_f32_i32_e32 v11, v3
	v_cvt_f32_i32_e32 v12, v4
	v_cvt_f32_i32_e32 v13, v5

.LBB0_549:
	ds_read_b128 v[148:151], v154
	ds_read_b128 v[158:161], v154 offset:1024
	ds_read_b128 v[162:165], v154 offset:2048
	ds_read_b128 v[170:173], v154 offset:3072
	ds_read_b128 v[174:177], v155
	ds_read_b128 v[178:181], v155 offset:1024
	ds_read_b128 v[182:185], v155 offset:2048
	ds_read_b128 v[186:189], v155 offset:3072
	s_add_u32 s64, s56, 0xfff00080
	s_addc_u32 s65, s57, -1
	s_cmp_eq_u32 s93, 60
	s_cselect_b32 s67, s45, s65
	s_cselect_b32 s66, s51, s64
	s_cselect_b32 s65, s43, s83
	s_cselect_b32 s64, s79, s82
	v_lshl_add_u64 v[152:153], s[56:57], 0, v[140:141]
	s_add_i32 m0, s7, 0xc000
	ds_read_b128 v[190:193], v156
	ds_read_b128 v[194:197], v156 offset:1024
	ds_read_b128 v[198:201], v156 offset:2048
	ds_read_b128 v[202:205], v156 offset:3072
	ds_read_b128 v[206:209], v156 offset:4096
	ds_read_b128 v[210:213], v156 offset:5120
	ds_read_b128 v[214:217], v156 offset:6144
	ds_read_b128 v[218:221], v156 offset:7168
	global_load_lds_dwordx4 v[152:153], off
	v_lshl_add_u64 v[152:153], s[56:57], 0, v[142:143]
	s_add_i32 m0, s7, 0xe000
	s_nop 0
	global_load_lds_dwordx4 v[152:153], off
	s_waitcnt vmcnt(8)
	s_waitcnt lgkmcnt(0)
	s_barrier
	s_setprio 1
	v_mfma_f32_16x16x32_bf16 v[126:129], v[148:151], v[190:193], v[126:129]
	v_mfma_f32_16x16x32_bf16 v[122:125], v[162:165], v[190:193], v[122:125]
	v_mfma_f32_16x16x32_bf16 v[118:121], v[148:151], v[198:201], v[118:121]
	v_mfma_f32_16x16x32_bf16 v[114:117], v[162:165], v[198:201], v[114:117]
	v_mfma_f32_16x16x32_bf16 v[102:105], v[148:151], v[206:209], v[102:105]
	v_mfma_f32_16x16x32_bf16 v[98:101], v[162:165], v[206:209], v[98:101]
	v_mfma_f32_16x16x32_bf16 v[86:89], v[148:151], v[214:217], v[86:89]
	v_mfma_f32_16x16x32_bf16 v[82:85], v[162:165], v[214:217], v[82:85]
	v_mfma_f32_16x16x32_bf16 v[126:129], v[158:161], v[194:197], v[126:129]
	v_mfma_f32_16x16x32_bf16 v[122:125], v[170:173], v[194:197], v[122:125]
	v_mfma_f32_16x16x32_bf16 v[118:121], v[158:161], v[202:205], v[118:121]
	v_mfma_f32_16x16x32_bf16 v[114:117], v[170:173], v[202:205], v[114:117]
	v_mfma_f32_16x16x32_bf16 v[102:105], v[158:161], v[210:213], v[102:105]
	v_mfma_f32_16x16x32_bf16 v[98:101], v[170:173], v[210:213], v[98:101]
	v_mfma_f32_16x16x32_bf16 v[86:89], v[158:161], v[218:221], v[86:89]
	v_mfma_f32_16x16x32_bf16 v[82:85], v[170:173], v[218:221], v[82:85]
	v_mfma_f32_16x16x32_bf16 v[110:113], v[174:177], v[190:193], v[110:113]
	v_mfma_f32_16x16x32_bf16 v[106:109], v[182:185], v[190:193], v[106:109]
	v_mfma_f32_16x16x32_bf16 v[94:97], v[174:177], v[198:201], v[94:97]
	v_mfma_f32_16x16x32_bf16 v[90:93], v[182:185], v[198:201], v[90:93]
	v_mfma_f32_16x16x32_bf16 v[78:81], v[174:177], v[206:209], v[78:81]
	v_mfma_f32_16x16x32_bf16 v[74:77], v[182:185], v[206:209], v[74:77]
	v_mfma_f32_16x16x32_bf16 v[70:73], v[174:177], v[214:217], v[70:73]
	v_mfma_f32_16x16x32_bf16 v[66:69], v[182:185], v[214:217], v[66:69]
	v_mfma_f32_16x16x32_bf16 v[110:113], v[178:181], v[194:197], v[110:113]
	v_mfma_f32_16x16x32_bf16 v[106:109], v[186:189], v[194:197], v[106:109]
	v_mfma_f32_16x16x32_bf16 v[94:97], v[178:181], v[202:205], v[94:97]
	v_mfma_f32_16x16x32_bf16 v[90:93], v[186:189], v[202:205], v[90:93]
	v_mfma_f32_16x16x32_bf16 v[78:81], v[178:181], v[210:213], v[78:81]
	v_mfma_f32_16x16x32_bf16 v[74:77], v[186:189], v[210:213], v[74:77]
	v_mfma_f32_16x16x32_bf16 v[70:73], v[178:181], v[218:221], v[70:73]
	v_mfma_f32_16x16x32_bf16 v[66:69], v[186:189], v[218:221], v[66:69]
	s_barrier
	s_setprio 0
	s_add_i32 s95, s71, s6
	v_lshl_add_u64 v[152:153], s[64:65], 0, v[132:133]
	s_mov_b32 m0, s95
	ds_read_b128 v[190:193], v156 offset:16384
	ds_read_b128 v[194:197], v156 offset:17408
	ds_read_b128 v[198:201], v156 offset:18432
	ds_read_b128 v[202:205], v156 offset:19456
	ds_read_b128 v[206:209], v156 offset:20480
	ds_read_b128 v[210:213], v156 offset:21504
	ds_read_b128 v[214:217], v156 offset:22528
	ds_read_b128 v[218:221], v156 offset:23552
	global_load_lds_dwordx4 v[152:153], off
	s_add_i32 m0, s95, 0x2000
	s_add_u32 vcc_lo, s64, 0x100000
	v_lshl_add_u64 v[166:167], s[64:65], 0, v[136:137]
	s_addc_u32 vcc_hi, s65, 0
	s_add_i32 s95, s72, s6
	global_load_lds_dwordx4 v[166:167], off
	v_lshl_add_u64 v[222:223], vcc, 0, v[132:133]
	s_mov_b32 m0, s95
	v_lshl_add_u64 v[224:225], s[66:67], 0, v[134:135]
	global_load_lds_dwordx4 v[222:223], off
	v_lshl_add_u64 v[222:223], vcc, 0, v[136:137]
	s_add_i32 m0, s95, 0x2000
	s_nop 0
	global_load_lds_dwordx4 v[222:223], off
	v_lshl_add_u64 v[222:223], s[66:67], 0, v[130:131]
	s_mov_b32 m0, s7
	s_nop 0
	global_load_lds_dwordx4 v[222:223], off
	s_mov_b32 m0, s52
	s_nop 0
	global_load_lds_dwordx4 v[224:225], off
	s_waitcnt vmcnt(8)
	s_waitcnt lgkmcnt(0)
	s_barrier
	s_setprio 1
	v_mfma_f32_16x16x32_bf16 v[62:65], v[148:151], v[190:193], v[62:65]
	v_mfma_f32_16x16x32_bf16 v[58:61], v[162:165], v[190:193], v[58:61]
	v_mfma_f32_16x16x32_bf16 v[54:57], v[148:151], v[198:201], v[54:57]
	v_mfma_f32_16x16x32_bf16 v[50:53], v[162:165], v[198:201], v[50:53]
	v_mfma_f32_16x16x32_bf16 v[38:41], v[148:151], v[206:209], v[38:41]
	v_mfma_f32_16x16x32_bf16 v[34:37], v[162:165], v[206:209], v[34:37]
	v_mfma_f32_16x16x32_bf16 v[22:25], v[148:151], v[214:217], v[22:25]
	v_mfma_f32_16x16x32_bf16 v[18:21], v[162:165], v[214:217], v[18:21]
	v_mfma_f32_16x16x32_bf16 v[62:65], v[158:161], v[194:197], v[62:65]
	v_mfma_f32_16x16x32_bf16 v[58:61], v[170:173], v[194:197], v[58:61]
	v_mfma_f32_16x16x32_bf16 v[54:57], v[158:161], v[202:205], v[54:57]
	v_mfma_f32_16x16x32_bf16 v[50:53], v[170:173], v[202:205], v[50:53]
	v_mfma_f32_16x16x32_bf16 v[38:41], v[158:161], v[210:213], v[38:41]
	v_mfma_f32_16x16x32_bf16 v[34:37], v[170:173], v[210:213], v[34:37]
	v_mfma_f32_16x16x32_bf16 v[22:25], v[158:161], v[218:221], v[22:25]
	v_mfma_f32_16x16x32_bf16 v[18:21], v[170:173], v[218:221], v[18:21]
	v_mfma_f32_16x16x32_bf16 v[46:49], v[174:177], v[190:193], v[46:49]
	v_mfma_f32_16x16x32_bf16 v[42:45], v[182:185], v[190:193], v[42:45]
	v_mfma_f32_16x16x32_bf16 v[30:33], v[174:177], v[198:201], v[30:33]
	v_mfma_f32_16x16x32_bf16 v[26:29], v[182:185], v[198:201], v[26:29]
	v_mfma_f32_16x16x32_bf16 v[14:17], v[174:177], v[206:209], v[14:17]
	v_mfma_f32_16x16x32_bf16 v[10:13], v[182:185], v[206:209], v[10:13]
	v_mfma_f32_16x16x32_bf16 v[6:9], v[174:177], v[214:217], v[6:9]
	v_mfma_f32_16x16x32_bf16 v[2:5], v[182:185], v[214:217], v[2:5]
	v_mfma_f32_16x16x32_bf16 v[46:49], v[178:181], v[194:197], v[46:49]
	v_mfma_f32_16x16x32_bf16 v[42:45], v[186:189], v[194:197], v[42:45]
	v_mfma_f32_16x16x32_bf16 v[30:33], v[178:181], v[202:205], v[30:33]
	v_mfma_f32_16x16x32_bf16 v[26:29], v[186:189], v[202:205], v[26:29]
	v_mfma_f32_16x16x32_bf16 v[14:17], v[178:181], v[210:213], v[14:17]
	v_mfma_f32_16x16x32_bf16 v[10:13], v[186:189], v[210:213], v[10:13]
	v_mfma_f32_16x16x32_bf16 v[6:9], v[178:181], v[218:221], v[6:9]
	v_mfma_f32_16x16x32_bf16 v[2:5], v[186:189], v[218:221], v[2:5]
	s_barrier
	s_setprio 0
	s_add_i32 s95, 0, 0x18000
	v_add_u32_e32 v138, s95, v1
	s_add_i32 s97, 0, 0x1c000
	ds_read_b128 v[148:151], v138
	ds_read_b128 v[158:161], v138 offset:1024
	ds_read_b128 v[162:165], v138 offset:2048
	ds_read_b128 v[170:173], v138 offset:3072
	v_add_u32_e32 v138, s97, v1
	ds_read_b128 v[174:177], v138
	ds_read_b128 v[178:181], v138 offset:1024
	ds_read_b128 v[182:185], v138 offset:2048
	ds_read_b128 v[186:189], v138 offset:3072
	s_add_u32 s66, s66, 0x100000
	s_addc_u32 s67, s67, 0
	s_mov_b32 m0, s53
	v_lshl_add_u64 v[226:227], s[66:67], 0, v[130:131]
	ds_read_b128 v[190:193], v156 offset:32768
	ds_read_b128 v[194:197], v156 offset:33792
	ds_read_b128 v[198:201], v156 offset:34816
	ds_read_b128 v[202:205], v156 offset:35840
	ds_read_b128 v[206:209], v156 offset:36864
	ds_read_b128 v[210:213], v156 offset:37888
	ds_read_b128 v[214:217], v156 offset:38912
	ds_read_b128 v[218:221], v156 offset:39936
	global_load_lds_dwordx4 v[226:227], off
	v_lshl_add_u64 v[226:227], s[66:67], 0, v[134:135]
	s_mov_b32 m0, s54
	s_nop 0
	global_load_lds_dwordx4 v[226:227], off
	s_waitcnt vmcnt(8)
	s_waitcnt lgkmcnt(0)
	s_barrier
	s_setprio 1
	v_mfma_f32_16x16x32_bf16 v[126:129], v[148:151], v[190:193], v[126:129]
	v_mfma_f32_16x16x32_bf16 v[122:125], v[162:165], v[190:193], v[122:125]
	v_mfma_f32_16x16x32_bf16 v[118:121], v[148:151], v[198:201], v[118:121]
	v_mfma_f32_16x16x32_bf16 v[114:117], v[162:165], v[198:201], v[114:117]
	v_mfma_f32_16x16x32_bf16 v[102:105], v[148:151], v[206:209], v[102:105]
	v_mfma_f32_16x16x32_bf16 v[98:101], v[162:165], v[206:209], v[98:101]
	v_mfma_f32_16x16x32_bf16 v[86:89], v[148:151], v[214:217], v[86:89]
	v_mfma_f32_16x16x32_bf16 v[82:85], v[162:165], v[214:217], v[82:85]
	v_mfma_f32_16x16x32_bf16 v[126:129], v[158:161], v[194:197], v[126:129]
	v_mfma_f32_16x16x32_bf16 v[122:125], v[170:173], v[194:197], v[122:125]
	v_mfma_f32_16x16x32_bf16 v[118:121], v[158:161], v[202:205], v[118:121]
	v_mfma_f32_16x16x32_bf16 v[114:117], v[170:173], v[202:205], v[114:117]
	v_mfma_f32_16x16x32_bf16 v[102:105], v[158:161], v[210:213], v[102:105]
	v_mfma_f32_16x16x32_bf16 v[98:101], v[170:173], v[210:213], v[98:101]
	v_mfma_f32_16x16x32_bf16 v[86:89], v[158:161], v[218:221], v[86:89]
	v_mfma_f32_16x16x32_bf16 v[82:85], v[170:173], v[218:221], v[82:85]
	v_mfma_f32_16x16x32_bf16 v[110:113], v[174:177], v[190:193], v[110:113]
	v_mfma_f32_16x16x32_bf16 v[106:109], v[182:185], v[190:193], v[106:109]
	v_mfma_f32_16x16x32_bf16 v[94:97], v[174:177], v[198:201], v[94:97]
	v_mfma_f32_16x16x32_bf16 v[90:93], v[182:185], v[198:201], v[90:93]
	v_mfma_f32_16x16x32_bf16 v[78:81], v[174:177], v[206:209], v[78:81]
	v_mfma_f32_16x16x32_bf16 v[74:77], v[182:185], v[206:209], v[74:77]
	v_mfma_f32_16x16x32_bf16 v[70:73], v[174:177], v[214:217], v[70:73]
	v_mfma_f32_16x16x32_bf16 v[66:69], v[182:185], v[214:217], v[66:69]
	v_mfma_f32_16x16x32_bf16 v[110:113], v[178:181], v[194:197], v[110:113]
	v_mfma_f32_16x16x32_bf16 v[106:109], v[186:189], v[194:197], v[106:109]
	v_mfma_f32_16x16x32_bf16 v[94:97], v[178:181], v[202:205], v[94:97]
	v_mfma_f32_16x16x32_bf16 v[90:93], v[186:189], v[202:205], v[90:93]
	v_mfma_f32_16x16x32_bf16 v[78:81], v[178:181], v[210:213], v[78:81]
	v_mfma_f32_16x16x32_bf16 v[74:77], v[186:189], v[210:213], v[74:77]
	v_mfma_f32_16x16x32_bf16 v[70:73], v[178:181], v[218:221], v[70:73]
	v_mfma_f32_16x16x32_bf16 v[66:69], v[186:189], v[218:221], v[66:69]
	s_barrier
	s_setprio 0
	s_add_i32 s66, s95, s6
	v_lshl_add_u64 v[152:153], v[152:153], 0, s[24:25]
	s_mov_b32 m0, s66
	ds_read_b128 v[190:193], v156 offset:49152
	ds_read_b128 v[194:197], v156 offset:50176
	ds_read_b128 v[198:201], v156 offset:51200
	ds_read_b128 v[202:205], v156 offset:52224
	ds_read_b128 v[206:209], v156 offset:53248
	ds_read_b128 v[210:213], v156 offset:54272
	ds_read_b128 v[214:217], v156 offset:55296
	ds_read_b128 v[218:221], v156 offset:56320
	global_load_lds_dwordx4 v[152:153], off
	s_add_i32 m0, s66, 0x2000
	s_add_u32 s64, s64, 0x100080
	v_lshl_add_u64 v[152:153], v[166:167], 0, s[24:25]
	s_addc_u32 s65, s65, 0
	s_add_i32 s66, s97, s6
	global_load_lds_dwordx4 v[152:153], off
	v_lshl_add_u64 v[152:153], s[64:65], 0, v[132:133]
	s_mov_b32 m0, s66
	s_nop 0
	global_load_lds_dwordx4 v[152:153], off
	v_lshl_add_u64 v[152:153], s[64:65], 0, v[136:137]
	s_add_i32 m0, s66, 0x2000
	s_nop 0
	global_load_lds_dwordx4 v[152:153], off
	v_lshl_add_u64 v[152:153], v[222:223], 0, s[24:25]
	s_mov_b32 m0, s63
	s_nop 0
	global_load_lds_dwordx4 v[152:153], off
	v_lshl_add_u64 v[152:153], v[224:225], 0, s[24:25]
	s_mov_b32 m0, s68
	s_nop 0
	global_load_lds_dwordx4 v[152:153], off
	s_waitcnt vmcnt(8)
	s_waitcnt lgkmcnt(0)
	s_barrier
	s_setprio 1
	v_mfma_f32_16x16x32_bf16 v[62:65], v[148:151], v[190:193], v[62:65]
	v_mfma_f32_16x16x32_bf16 v[58:61], v[162:165], v[190:193], v[58:61]
	v_mfma_f32_16x16x32_bf16 v[54:57], v[148:151], v[198:201], v[54:57]
	v_mfma_f32_16x16x32_bf16 v[50:53], v[162:165], v[198:201], v[50:53]
	v_mfma_f32_16x16x32_bf16 v[38:41], v[148:151], v[206:209], v[38:41]
	v_mfma_f32_16x16x32_bf16 v[34:37], v[162:165], v[206:209], v[34:37]
	v_mfma_f32_16x16x32_bf16 v[22:25], v[148:151], v[214:217], v[22:25]
	v_mfma_f32_16x16x32_bf16 v[18:21], v[162:165], v[214:217], v[18:21]
	v_mfma_f32_16x16x32_bf16 v[62:65], v[158:161], v[194:197], v[62:65]
	v_mfma_f32_16x16x32_bf16 v[58:61], v[170:173], v[194:197], v[58:61]
	v_mfma_f32_16x16x32_bf16 v[54:57], v[158:161], v[202:205], v[54:57]
	v_mfma_f32_16x16x32_bf16 v[50:53], v[170:173], v[202:205], v[50:53]
	v_mfma_f32_16x16x32_bf16 v[38:41], v[158:161], v[210:213], v[38:41]
	v_mfma_f32_16x16x32_bf16 v[34:37], v[170:173], v[210:213], v[34:37]
	v_mfma_f32_16x16x32_bf16 v[22:25], v[158:161], v[218:221], v[22:25]
	v_mfma_f32_16x16x32_bf16 v[18:21], v[170:173], v[218:221], v[18:21]
	v_mfma_f32_16x16x32_bf16 v[46:49], v[174:177], v[190:193], v[46:49]
	v_mfma_f32_16x16x32_bf16 v[42:45], v[182:185], v[190:193], v[42:45]
	v_mfma_f32_16x16x32_bf16 v[30:33], v[174:177], v[198:201], v[30:33]
	v_mfma_f32_16x16x32_bf16 v[26:29], v[182:185], v[198:201], v[26:29]
	v_mfma_f32_16x16x32_bf16 v[14:17], v[174:177], v[206:209], v[14:17]
	v_mfma_f32_16x16x32_bf16 v[10:13], v[182:185], v[206:209], v[10:13]
	v_mfma_f32_16x16x32_bf16 v[6:9], v[174:177], v[214:217], v[6:9]
	v_mfma_f32_16x16x32_bf16 v[2:5], v[182:185], v[214:217], v[2:5]
	v_mfma_f32_16x16x32_bf16 v[46:49], v[178:181], v[194:197], v[46:49]
	v_mfma_f32_16x16x32_bf16 v[42:45], v[186:189], v[194:197], v[42:45]
	v_mfma_f32_16x16x32_bf16 v[30:33], v[178:181], v[202:205], v[30:33]
	v_mfma_f32_16x16x32_bf16 v[26:29], v[186:189], v[202:205], v[26:29]
	v_mfma_f32_16x16x32_bf16 v[14:17], v[178:181], v[210:213], v[14:17]
	v_mfma_f32_16x16x32_bf16 v[10:13], v[186:189], v[210:213], v[10:13]
	v_mfma_f32_16x16x32_bf16 v[6:9], v[178:181], v[218:221], v[6:9]
	v_mfma_f32_16x16x32_bf16 v[2:5], v[186:189], v[218:221], v[2:5]
	s_barrier
	s_setprio 0
	s_add_i32 s93, s93, 2
	s_add_u32 s56, s56, 0x100
	s_addc_u32 s57, s57, 0
	s_add_u32 s82, s82, 0x100
	s_addc_u32 s83, s83, 0
	s_cmp_gt_u32 s93, 61
	s_cbranch_scc0 .LBB0_549
	s_and_b64 vcc, exec, s[26:27]
	s_cbranch_vccz .LBB0_552
	s_barrier

.LBB0_736:
	ds_read_b128 v[118:121], v164
	ds_read_b128 v[122:125], v164 offset:1024
	ds_read_b128 v[138:141], v164 offset:2048
	ds_read_b128 v[142:145], v164 offset:3072
	ds_read_b128 v[160:163], v165
	ds_read_b128 v[170:173], v165 offset:1024
	ds_read_b128 v[174:177], v165 offset:2048
	ds_read_b128 v[178:181], v165 offset:3072
	s_add_i32 s58, s22, 2
	s_add_u32 s59, s20, 0x80
	s_addc_u32 s23, s21, 0
	s_cmp_eq_u32 s47, s22
	s_cselect_b32 s22, s16, s59
	s_cselect_b32 s23, s17, s23
	s_cselect_b32 s61, s19, s57
	s_cselect_b32 s60, s18, s56
	v_lshl_add_u64 v[214:215], s[20:21], 0, v[156:157]
	s_add_i32 m0, s29, 0xc000
	ds_read_b128 v[182:185], v166
	ds_read_b128 v[186:189], v166 offset:1024
	ds_read_b128 v[190:193], v166 offset:2048
	ds_read_b128 v[194:197], v166 offset:3072
	ds_read_b128 v[198:201], v166 offset:4096
	ds_read_b128 v[202:205], v166 offset:5120
	ds_read_b128 v[206:209], v166 offset:6144
	ds_read_b128 v[210:213], v166 offset:7168
	global_load_lds_dwordx4 v[214:215], off
	v_lshl_add_u64 v[214:215], s[20:21], 0, v[158:159]
	s_add_i32 m0, s29, 0xe000
	s_nop 0
	global_load_lds_dwordx4 v[214:215], off
	s_waitcnt vmcnt(8)
	s_waitcnt lgkmcnt(0)
	s_barrier
	s_setprio 1
	v_mfma_f32_16x16x32_bf16 v[134:137], v[118:121], v[182:185], v[134:137]
	v_mfma_f32_16x16x32_bf16 v[130:133], v[138:141], v[182:185], v[130:133]
	v_mfma_f32_16x16x32_bf16 v[110:113], v[118:121], v[190:193], v[110:113]
	v_mfma_f32_16x16x32_bf16 v[106:109], v[138:141], v[190:193], v[106:109]
	v_mfma_f32_16x16x32_bf16 v[94:97], v[118:121], v[198:201], v[94:97]
	v_mfma_f32_16x16x32_bf16 v[90:93], v[138:141], v[198:201], v[90:93]
	v_mfma_f32_16x16x32_bf16 v[78:81], v[118:121], v[206:209], v[78:81]
	v_mfma_f32_16x16x32_bf16 v[74:77], v[138:141], v[206:209], v[74:77]
	v_mfma_f32_16x16x32_bf16 v[134:137], v[122:125], v[186:189], v[134:137]
	v_mfma_f32_16x16x32_bf16 v[130:133], v[142:145], v[186:189], v[130:133]
	v_mfma_f32_16x16x32_bf16 v[110:113], v[122:125], v[194:197], v[110:113]
	v_mfma_f32_16x16x32_bf16 v[106:109], v[142:145], v[194:197], v[106:109]
	v_mfma_f32_16x16x32_bf16 v[94:97], v[122:125], v[202:205], v[94:97]
	v_mfma_f32_16x16x32_bf16 v[90:93], v[142:145], v[202:205], v[90:93]
	v_mfma_f32_16x16x32_bf16 v[78:81], v[122:125], v[210:213], v[78:81]
	v_mfma_f32_16x16x32_bf16 v[74:77], v[142:145], v[210:213], v[74:77]
	v_mfma_f32_16x16x32_bf16 v[126:129], v[160:163], v[182:185], v[126:129]
	v_mfma_f32_16x16x32_bf16 v[114:117], v[174:177], v[182:185], v[114:117]
	v_mfma_f32_16x16x32_bf16 v[102:105], v[160:163], v[190:193], v[102:105]
	v_mfma_f32_16x16x32_bf16 v[98:101], v[174:177], v[190:193], v[98:101]
	v_mfma_f32_16x16x32_bf16 v[86:89], v[160:163], v[198:201], v[86:89]
	v_mfma_f32_16x16x32_bf16 v[82:85], v[174:177], v[198:201], v[82:85]
	v_mfma_f32_16x16x32_bf16 v[70:73], v[160:163], v[206:209], v[70:73]
	v_mfma_f32_16x16x32_bf16 v[66:69], v[174:177], v[206:209], v[66:69]
	v_mfma_f32_16x16x32_bf16 v[126:129], v[170:173], v[186:189], v[126:129]
	v_mfma_f32_16x16x32_bf16 v[114:117], v[178:181], v[186:189], v[114:117]
	v_mfma_f32_16x16x32_bf16 v[102:105], v[170:173], v[194:197], v[102:105]
	v_mfma_f32_16x16x32_bf16 v[98:101], v[178:181], v[194:197], v[98:101]
	v_mfma_f32_16x16x32_bf16 v[86:89], v[170:173], v[202:205], v[86:89]
	v_mfma_f32_16x16x32_bf16 v[82:85], v[178:181], v[202:205], v[82:85]
	v_mfma_f32_16x16x32_bf16 v[70:73], v[170:173], v[210:213], v[70:73]
	v_mfma_f32_16x16x32_bf16 v[66:69], v[178:181], v[210:213], v[66:69]
	s_barrier
	s_setprio 0
	s_add_i32 s59, s48, s28
	v_lshl_add_u64 v[214:215], s[60:61], 0, v[150:151]
	s_mov_b32 m0, s59
	ds_read_b128 v[182:185], v166 offset:16384
	ds_read_b128 v[186:189], v166 offset:17408
	ds_read_b128 v[190:193], v166 offset:18432
	ds_read_b128 v[194:197], v166 offset:19456
	ds_read_b128 v[198:201], v166 offset:20480
	ds_read_b128 v[202:205], v166 offset:21504
	ds_read_b128 v[206:209], v166 offset:22528
	ds_read_b128 v[210:213], v166 offset:23552
	global_load_lds_dwordx4 v[214:215], off
	s_add_i32 m0, s59, 0x2000
	v_lshl_add_u64 v[216:217], s[60:61], 0, v[146:147]
	s_add_u32 s60, s60, s6
	s_addc_u32 s61, s61, s7
	s_add_i32 s59, s49, s28
	global_load_lds_dwordx4 v[216:217], off
	v_lshl_add_u64 v[218:219], s[60:61], 0, v[150:151]
	s_mov_b32 m0, s59
	v_lshl_add_u64 v[220:221], s[60:61], 0, v[146:147]
	global_load_lds_dwordx4 v[218:219], off
	s_add_i32 m0, s59, 0x2000
	v_lshl_add_u64 v[222:223], s[22:23], 0, v[152:153]
	global_load_lds_dwordx4 v[220:221], off
	s_mov_b32 m0, s29
	v_lshl_add_u64 v[224:225], s[22:23], 0, v[148:149]
	global_load_lds_dwordx4 v[222:223], off
	s_mov_b32 m0, s30
	s_nop 0
	global_load_lds_dwordx4 v[224:225], off
	s_waitcnt vmcnt(8)
	s_waitcnt lgkmcnt(0)
	s_barrier
	s_setprio 1
	v_mfma_f32_16x16x32_bf16 v[62:65], v[118:121], v[182:185], v[62:65]
	v_mfma_f32_16x16x32_bf16 v[58:61], v[138:141], v[182:185], v[58:61]
	v_mfma_f32_16x16x32_bf16 v[46:49], v[118:121], v[190:193], v[46:49]
	v_mfma_f32_16x16x32_bf16 v[42:45], v[138:141], v[190:193], v[42:45]
	v_mfma_f32_16x16x32_bf16 v[30:33], v[118:121], v[198:201], v[30:33]
	v_mfma_f32_16x16x32_bf16 v[26:29], v[138:141], v[198:201], v[26:29]
	v_mfma_f32_16x16x32_bf16 v[14:17], v[118:121], v[206:209], v[14:17]
	v_mfma_f32_16x16x32_bf16 v[10:13], v[138:141], v[206:209], v[10:13]
	v_mfma_f32_16x16x32_bf16 v[62:65], v[122:125], v[186:189], v[62:65]
	v_mfma_f32_16x16x32_bf16 v[58:61], v[142:145], v[186:189], v[58:61]
	v_mfma_f32_16x16x32_bf16 v[46:49], v[122:125], v[194:197], v[46:49]
	v_mfma_f32_16x16x32_bf16 v[42:45], v[142:145], v[194:197], v[42:45]
	v_mfma_f32_16x16x32_bf16 v[30:33], v[122:125], v[202:205], v[30:33]
	v_mfma_f32_16x16x32_bf16 v[26:29], v[142:145], v[202:205], v[26:29]
	v_mfma_f32_16x16x32_bf16 v[14:17], v[122:125], v[210:213], v[14:17]
	v_mfma_f32_16x16x32_bf16 v[10:13], v[142:145], v[210:213], v[10:13]
	v_mfma_f32_16x16x32_bf16 v[54:57], v[160:163], v[182:185], v[54:57]
	v_mfma_f32_16x16x32_bf16 v[50:53], v[174:177], v[182:185], v[50:53]
	v_mfma_f32_16x16x32_bf16 v[38:41], v[160:163], v[190:193], v[38:41]
	v_mfma_f32_16x16x32_bf16 v[34:37], v[174:177], v[190:193], v[34:37]
	v_mfma_f32_16x16x32_bf16 v[22:25], v[160:163], v[198:201], v[22:25]
	v_mfma_f32_16x16x32_bf16 v[18:21], v[174:177], v[198:201], v[18:21]
	v_mfma_f32_16x16x32_bf16 v[6:9], v[160:163], v[206:209], v[6:9]
	v_mfma_f32_16x16x32_bf16 v[2:5], v[174:177], v[206:209], v[2:5]
	v_mfma_f32_16x16x32_bf16 v[54:57], v[170:173], v[186:189], v[54:57]
	v_mfma_f32_16x16x32_bf16 v[50:53], v[178:181], v[186:189], v[50:53]
	v_mfma_f32_16x16x32_bf16 v[38:41], v[170:173], v[194:197], v[38:41]
	v_mfma_f32_16x16x32_bf16 v[34:37], v[178:181], v[194:197], v[34:37]
	v_mfma_f32_16x16x32_bf16 v[22:25], v[170:173], v[202:205], v[22:25]
	v_mfma_f32_16x16x32_bf16 v[18:21], v[178:181], v[202:205], v[18:21]
	v_mfma_f32_16x16x32_bf16 v[6:9], v[170:173], v[210:213], v[6:9]
	v_mfma_f32_16x16x32_bf16 v[2:5], v[178:181], v[210:213], v[2:5]
	s_barrier
	s_setprio 0
	s_add_i32 s59, 0, 0x18000
	s_add_i32 s60, 0, 0x1c000
	v_add_u32_e32 v142, s59, v1
	v_add_u32_e32 v154, s60, v1
	ds_read_b128 v[118:121], v142
	ds_read_b128 v[122:125], v142 offset:1024
	ds_read_b128 v[138:141], v142 offset:2048
	ds_read_b128 v[142:145], v142 offset:3072
	ds_read_b128 v[160:163], v154
	ds_read_b128 v[170:173], v154 offset:1024
	ds_read_b128 v[174:177], v154 offset:2048
	ds_read_b128 v[178:181], v154 offset:3072
	s_add_u32 s22, s22, s6
	s_addc_u32 s23, s23, s7
	s_mov_b32 m0, s31
	v_lshl_add_u64 v[226:227], s[22:23], 0, v[152:153]
	ds_read_b128 v[182:185], v166 offset:32768
	ds_read_b128 v[186:189], v166 offset:33792
	ds_read_b128 v[190:193], v166 offset:34816
	ds_read_b128 v[194:197], v166 offset:35840
	ds_read_b128 v[198:201], v166 offset:36864
	ds_read_b128 v[202:205], v166 offset:37888
	ds_read_b128 v[206:209], v166 offset:38912
	ds_read_b128 v[210:213], v166 offset:39936
	global_load_lds_dwordx4 v[226:227], off
	v_lshl_add_u64 v[226:227], s[22:23], 0, v[148:149]
	s_mov_b32 m0, s34
	s_nop 0
	global_load_lds_dwordx4 v[226:227], off
	s_waitcnt vmcnt(8)
	s_waitcnt lgkmcnt(0)
	s_barrier
	s_setprio 1
	v_mfma_f32_16x16x32_bf16 v[134:137], v[118:121], v[182:185], v[134:137]
	v_mfma_f32_16x16x32_bf16 v[130:133], v[138:141], v[182:185], v[130:133]
	v_mfma_f32_16x16x32_bf16 v[110:113], v[118:121], v[190:193], v[110:113]
	v_mfma_f32_16x16x32_bf16 v[106:109], v[138:141], v[190:193], v[106:109]
	v_mfma_f32_16x16x32_bf16 v[94:97], v[118:121], v[198:201], v[94:97]
	v_mfma_f32_16x16x32_bf16 v[90:93], v[138:141], v[198:201], v[90:93]
	v_mfma_f32_16x16x32_bf16 v[78:81], v[118:121], v[206:209], v[78:81]
	v_mfma_f32_16x16x32_bf16 v[74:77], v[138:141], v[206:209], v[74:77]
	v_mfma_f32_16x16x32_bf16 v[134:137], v[122:125], v[186:189], v[134:137]
	v_mfma_f32_16x16x32_bf16 v[130:133], v[142:145], v[186:189], v[130:133]
	v_mfma_f32_16x16x32_bf16 v[110:113], v[122:125], v[194:197], v[110:113]
	v_mfma_f32_16x16x32_bf16 v[106:109], v[142:145], v[194:197], v[106:109]
	v_mfma_f32_16x16x32_bf16 v[94:97], v[122:125], v[202:205], v[94:97]
	v_mfma_f32_16x16x32_bf16 v[90:93], v[142:145], v[202:205], v[90:93]
	v_mfma_f32_16x16x32_bf16 v[78:81], v[122:125], v[210:213], v[78:81]
	v_mfma_f32_16x16x32_bf16 v[74:77], v[142:145], v[210:213], v[74:77]
	v_mfma_f32_16x16x32_bf16 v[126:129], v[160:163], v[182:185], v[126:129]
	v_mfma_f32_16x16x32_bf16 v[114:117], v[174:177], v[182:185], v[114:117]
	v_mfma_f32_16x16x32_bf16 v[102:105], v[160:163], v[190:193], v[102:105]
	v_mfma_f32_16x16x32_bf16 v[98:101], v[174:177], v[190:193], v[98:101]
	v_mfma_f32_16x16x32_bf16 v[86:89], v[160:163], v[198:201], v[86:89]
	v_mfma_f32_16x16x32_bf16 v[82:85], v[174:177], v[198:201], v[82:85]
	v_mfma_f32_16x16x32_bf16 v[70:73], v[160:163], v[206:209], v[70:73]
	v_mfma_f32_16x16x32_bf16 v[66:69], v[174:177], v[206:209], v[66:69]
	v_mfma_f32_16x16x32_bf16 v[126:129], v[170:173], v[186:189], v[126:129]
	v_mfma_f32_16x16x32_bf16 v[114:117], v[178:181], v[186:189], v[114:117]
	v_mfma_f32_16x16x32_bf16 v[102:105], v[170:173], v[194:197], v[102:105]
	v_mfma_f32_16x16x32_bf16 v[98:101], v[178:181], v[194:197], v[98:101]
	v_mfma_f32_16x16x32_bf16 v[86:89], v[170:173], v[202:205], v[86:89]
	v_mfma_f32_16x16x32_bf16 v[82:85], v[178:181], v[202:205], v[82:85]
	v_mfma_f32_16x16x32_bf16 v[70:73], v[170:173], v[210:213], v[70:73]
	v_mfma_f32_16x16x32_bf16 v[66:69], v[178:181], v[210:213], v[66:69]
	s_barrier
	s_setprio 0
	s_add_i32 s22, s59, s28
	v_lshl_add_u64 v[214:215], v[214:215], 0, s[12:13]
	s_mov_b32 m0, s22
	ds_read_b128 v[182:185], v166 offset:49152
	ds_read_b128 v[186:189], v166 offset:50176
	ds_read_b128 v[190:193], v166 offset:51200
	ds_read_b128 v[194:197], v166 offset:52224
	ds_read_b128 v[198:201], v166 offset:53248
	ds_read_b128 v[202:205], v166 offset:54272
	ds_read_b128 v[206:209], v166 offset:55296
	ds_read_b128 v[210:213], v166 offset:56320
	global_load_lds_dwordx4 v[214:215], off
	v_lshl_add_u64 v[214:215], v[216:217], 0, s[12:13]
	s_add_i32 m0, s22, 0x2000
	s_add_i32 s22, s60, s28
	global_load_lds_dwordx4 v[214:215], off
	v_lshl_add_u64 v[214:215], v[218:219], 0, s[12:13]
	s_mov_b32 m0, s22
	s_nop 0
	global_load_lds_dwordx4 v[214:215], off
	v_lshl_add_u64 v[214:215], v[220:221], 0, s[12:13]
	s_add_i32 m0, s22, 0x2000
	s_nop 0
	global_load_lds_dwordx4 v[214:215], off
	v_lshl_add_u64 v[214:215], v[222:223], 0, s[12:13]
	s_mov_b32 m0, s45
	s_nop 0
	global_load_lds_dwordx4 v[214:215], off
	v_lshl_add_u64 v[214:215], v[224:225], 0, s[12:13]
	s_mov_b32 m0, s46
	s_nop 0
	global_load_lds_dwordx4 v[214:215], off
	s_waitcnt vmcnt(8)
	s_waitcnt lgkmcnt(0)
	s_barrier
	s_setprio 1
	v_mfma_f32_16x16x32_bf16 v[62:65], v[118:121], v[182:185], v[62:65]
	v_mfma_f32_16x16x32_bf16 v[58:61], v[138:141], v[182:185], v[58:61]
	v_mfma_f32_16x16x32_bf16 v[46:49], v[118:121], v[190:193], v[46:49]
	v_mfma_f32_16x16x32_bf16 v[42:45], v[138:141], v[190:193], v[42:45]
	v_mfma_f32_16x16x32_bf16 v[30:33], v[118:121], v[198:201], v[30:33]
	v_mfma_f32_16x16x32_bf16 v[26:29], v[138:141], v[198:201], v[26:29]
	v_mfma_f32_16x16x32_bf16 v[14:17], v[118:121], v[206:209], v[14:17]
	v_mfma_f32_16x16x32_bf16 v[10:13], v[138:141], v[206:209], v[10:13]
	v_mfma_f32_16x16x32_bf16 v[62:65], v[122:125], v[186:189], v[62:65]
	v_mfma_f32_16x16x32_bf16 v[58:61], v[142:145], v[186:189], v[58:61]
	v_mfma_f32_16x16x32_bf16 v[46:49], v[122:125], v[194:197], v[46:49]
	v_mfma_f32_16x16x32_bf16 v[42:45], v[142:145], v[194:197], v[42:45]
	v_mfma_f32_16x16x32_bf16 v[30:33], v[122:125], v[202:205], v[30:33]
	v_mfma_f32_16x16x32_bf16 v[26:29], v[142:145], v[202:205], v[26:29]
	v_mfma_f32_16x16x32_bf16 v[14:17], v[122:125], v[210:213], v[14:17]
	v_mfma_f32_16x16x32_bf16 v[10:13], v[142:145], v[210:213], v[10:13]
	v_mfma_f32_16x16x32_bf16 v[54:57], v[160:163], v[182:185], v[54:57]
	v_mfma_f32_16x16x32_bf16 v[50:53], v[174:177], v[182:185], v[50:53]
	v_mfma_f32_16x16x32_bf16 v[38:41], v[160:163], v[190:193], v[38:41]
	v_mfma_f32_16x16x32_bf16 v[34:37], v[174:177], v[190:193], v[34:37]
	v_mfma_f32_16x16x32_bf16 v[22:25], v[160:163], v[198:201], v[22:25]
	v_mfma_f32_16x16x32_bf16 v[18:21], v[174:177], v[198:201], v[18:21]
	v_mfma_f32_16x16x32_bf16 v[6:9], v[160:163], v[206:209], v[6:9]
	v_mfma_f32_16x16x32_bf16 v[2:5], v[174:177], v[206:209], v[2:5]
	v_mfma_f32_16x16x32_bf16 v[54:57], v[170:173], v[186:189], v[54:57]
	v_mfma_f32_16x16x32_bf16 v[50:53], v[178:181], v[186:189], v[50:53]
	v_mfma_f32_16x16x32_bf16 v[38:41], v[170:173], v[194:197], v[38:41]
	v_mfma_f32_16x16x32_bf16 v[34:37], v[178:181], v[194:197], v[34:37]
	v_mfma_f32_16x16x32_bf16 v[22:25], v[170:173], v[202:205], v[22:25]
	v_mfma_f32_16x16x32_bf16 v[18:21], v[178:181], v[202:205], v[18:21]
	v_mfma_f32_16x16x32_bf16 v[6:9], v[170:173], v[210:213], v[6:9]
	v_mfma_f32_16x16x32_bf16 v[2:5], v[178:181], v[210:213], v[2:5]
	s_barrier
	s_setprio 0
	s_add_u32 s20, s20, 0x100
	s_addc_u32 s21, s21, 0
	s_add_u32 s56, s56, 0x100
	s_addc_u32 s57, s57, 0
	s_cmp_ge_i32 s58, s42
	s_mov_b32 s22, s58
	s_cbranch_scc0 .LBB0_736

.LBB0_757:
	ds_read_b128 v[152:155], v148
	ds_read_b128 v[156:159], v148 offset:1024
	ds_read_b128 v[160:163], v148 offset:2048
	ds_read_b128 v[164:167], v148 offset:3072
	ds_read_b128 v[170:173], v149
	ds_read_b128 v[174:177], v149 offset:1024
	ds_read_b128 v[178:181], v149 offset:2048
	ds_read_b128 v[182:185], v149 offset:3072
	s_add_i32 s60, s26, 2
	s_add_u32 s61, s24, 0x80
	s_addc_u32 s27, s25, 0
	s_cmp_eq_u32 s51, s26
	s_cselect_b32 s26, s2, s61
	s_cselect_b32 s27, s3, s27
	s_cselect_b32 s63, s23, s59
	s_cselect_b32 s62, s22, s58
	v_lshl_add_u64 v[218:219], s[24:25], 0, v[140:141]
	s_add_i32 m0, s38, 0xc000
	ds_read_b128 v[186:189], v150
	ds_read_b128 v[190:193], v150 offset:1024
	ds_read_b128 v[194:197], v150 offset:2048
	ds_read_b128 v[198:201], v150 offset:3072
	ds_read_b128 v[202:205], v150 offset:4096
	ds_read_b128 v[206:209], v150 offset:5120
	ds_read_b128 v[210:213], v150 offset:6144
	ds_read_b128 v[214:217], v150 offset:7168
	global_load_lds_dwordx4 v[218:219], off
	v_lshl_add_u64 v[218:219], s[24:25], 0, v[142:143]
	s_add_i32 m0, s38, 0xe000
	s_nop 0
	global_load_lds_dwordx4 v[218:219], off
	s_waitcnt vmcnt(8)
	s_waitcnt lgkmcnt(0)
	s_barrier
	s_setprio 1
	v_mfma_f32_16x16x32_bf16 v[122:125], v[152:155], v[186:189], v[122:125]
	v_mfma_f32_16x16x32_bf16 v[126:129], v[160:163], v[186:189], v[126:129]
	v_mfma_f32_16x16x32_bf16 v[110:113], v[152:155], v[194:197], v[110:113]
	v_mfma_f32_16x16x32_bf16 v[106:109], v[160:163], v[194:197], v[106:109]
	v_mfma_f32_16x16x32_bf16 v[94:97], v[152:155], v[202:205], v[94:97]
	v_mfma_f32_16x16x32_bf16 v[90:93], v[160:163], v[202:205], v[90:93]
	v_mfma_f32_16x16x32_bf16 v[78:81], v[152:155], v[210:213], v[78:81]
	v_mfma_f32_16x16x32_bf16 v[74:77], v[160:163], v[210:213], v[74:77]
	v_mfma_f32_16x16x32_bf16 v[122:125], v[156:159], v[190:193], v[122:125]
	v_mfma_f32_16x16x32_bf16 v[126:129], v[164:167], v[190:193], v[126:129]
	v_mfma_f32_16x16x32_bf16 v[110:113], v[156:159], v[198:201], v[110:113]
	v_mfma_f32_16x16x32_bf16 v[106:109], v[164:167], v[198:201], v[106:109]
	v_mfma_f32_16x16x32_bf16 v[94:97], v[156:159], v[206:209], v[94:97]
	v_mfma_f32_16x16x32_bf16 v[90:93], v[164:167], v[206:209], v[90:93]
	v_mfma_f32_16x16x32_bf16 v[78:81], v[156:159], v[214:217], v[78:81]
	v_mfma_f32_16x16x32_bf16 v[74:77], v[164:167], v[214:217], v[74:77]
	v_mfma_f32_16x16x32_bf16 v[118:121], v[170:173], v[186:189], v[118:121]
	v_mfma_f32_16x16x32_bf16 v[114:117], v[178:181], v[186:189], v[114:117]
	v_mfma_f32_16x16x32_bf16 v[102:105], v[170:173], v[194:197], v[102:105]
	v_mfma_f32_16x16x32_bf16 v[98:101], v[178:181], v[194:197], v[98:101]
	v_mfma_f32_16x16x32_bf16 v[86:89], v[170:173], v[202:205], v[86:89]
	v_mfma_f32_16x16x32_bf16 v[82:85], v[178:181], v[202:205], v[82:85]
	v_mfma_f32_16x16x32_bf16 v[70:73], v[170:173], v[210:213], v[70:73]
	v_mfma_f32_16x16x32_bf16 v[66:69], v[178:181], v[210:213], v[66:69]
	v_mfma_f32_16x16x32_bf16 v[118:121], v[174:177], v[190:193], v[118:121]
	v_mfma_f32_16x16x32_bf16 v[114:117], v[182:185], v[190:193], v[114:117]
	v_mfma_f32_16x16x32_bf16 v[102:105], v[174:177], v[198:201], v[102:105]
	v_mfma_f32_16x16x32_bf16 v[98:101], v[182:185], v[198:201], v[98:101]
	v_mfma_f32_16x16x32_bf16 v[86:89], v[174:177], v[206:209], v[86:89]
	v_mfma_f32_16x16x32_bf16 v[82:85], v[182:185], v[206:209], v[82:85]
	v_mfma_f32_16x16x32_bf16 v[70:73], v[174:177], v[214:217], v[70:73]
	v_mfma_f32_16x16x32_bf16 v[66:69], v[182:185], v[214:217], v[66:69]
	s_barrier
	s_setprio 0
	s_add_i32 s61, s53, s36
	v_lshl_add_u64 v[218:219], s[62:63], 0, v[134:135]
	s_mov_b32 m0, s61
	ds_read_b128 v[186:189], v150 offset:16384
	ds_read_b128 v[190:193], v150 offset:17408
	ds_read_b128 v[194:197], v150 offset:18432
	ds_read_b128 v[198:201], v150 offset:19456
	ds_read_b128 v[202:205], v150 offset:20480
	ds_read_b128 v[206:209], v150 offset:21504
	ds_read_b128 v[210:213], v150 offset:22528
	ds_read_b128 v[214:217], v150 offset:23552
	global_load_lds_dwordx4 v[218:219], off
	s_add_i32 m0, s61, 0x2000
	v_lshl_add_u64 v[220:221], s[62:63], 0, v[130:131]
	s_add_u32 s62, s62, s6
	s_addc_u32 s63, s63, s7
	s_add_i32 s61, s54, s36
	global_load_lds_dwordx4 v[220:221], off
	v_lshl_add_u64 v[222:223], s[62:63], 0, v[134:135]
	s_mov_b32 m0, s61
	v_lshl_add_u64 v[224:225], s[62:63], 0, v[130:131]
	global_load_lds_dwordx4 v[222:223], off
	s_add_i32 m0, s61, 0x2000
	v_lshl_add_u64 v[226:227], s[26:27], 0, v[136:137]
	global_load_lds_dwordx4 v[224:225], off
	s_mov_b32 m0, s38
	v_lshl_add_u64 v[228:229], s[26:27], 0, v[132:133]
	global_load_lds_dwordx4 v[226:227], off
	s_mov_b32 m0, s39
	s_nop 0
	global_load_lds_dwordx4 v[228:229], off
	s_waitcnt vmcnt(8)
	s_waitcnt lgkmcnt(0)
	s_barrier
	s_setprio 1
	v_mfma_f32_16x16x32_bf16 v[62:65], v[152:155], v[186:189], v[62:65]
	v_mfma_f32_16x16x32_bf16 v[58:61], v[160:163], v[186:189], v[58:61]
	v_mfma_f32_16x16x32_bf16 v[46:49], v[152:155], v[194:197], v[46:49]
	v_mfma_f32_16x16x32_bf16 v[42:45], v[160:163], v[194:197], v[42:45]
	v_mfma_f32_16x16x32_bf16 v[30:33], v[152:155], v[202:205], v[30:33]
	v_mfma_f32_16x16x32_bf16 v[26:29], v[160:163], v[202:205], v[26:29]
	v_mfma_f32_16x16x32_bf16 v[14:17], v[152:155], v[210:213], v[14:17]
	v_mfma_f32_16x16x32_bf16 v[10:13], v[160:163], v[210:213], v[10:13]
	v_mfma_f32_16x16x32_bf16 v[62:65], v[156:159], v[190:193], v[62:65]
	v_mfma_f32_16x16x32_bf16 v[58:61], v[164:167], v[190:193], v[58:61]
	v_mfma_f32_16x16x32_bf16 v[46:49], v[156:159], v[198:201], v[46:49]
	v_mfma_f32_16x16x32_bf16 v[42:45], v[164:167], v[198:201], v[42:45]
	v_mfma_f32_16x16x32_bf16 v[30:33], v[156:159], v[206:209], v[30:33]
	v_mfma_f32_16x16x32_bf16 v[26:29], v[164:167], v[206:209], v[26:29]
	v_mfma_f32_16x16x32_bf16 v[14:17], v[156:159], v[214:217], v[14:17]
	v_mfma_f32_16x16x32_bf16 v[10:13], v[164:167], v[214:217], v[10:13]
	v_mfma_f32_16x16x32_bf16 v[54:57], v[170:173], v[186:189], v[54:57]
	v_mfma_f32_16x16x32_bf16 v[50:53], v[178:181], v[186:189], v[50:53]
	v_mfma_f32_16x16x32_bf16 v[38:41], v[170:173], v[194:197], v[38:41]
	v_mfma_f32_16x16x32_bf16 v[34:37], v[178:181], v[194:197], v[34:37]
	v_mfma_f32_16x16x32_bf16 v[22:25], v[170:173], v[202:205], v[22:25]
	v_mfma_f32_16x16x32_bf16 v[18:21], v[178:181], v[202:205], v[18:21]
	v_mfma_f32_16x16x32_bf16 v[6:9], v[170:173], v[210:213], v[6:9]
	v_mfma_f32_16x16x32_bf16 v[2:5], v[178:181], v[210:213], v[2:5]
	v_mfma_f32_16x16x32_bf16 v[54:57], v[174:177], v[190:193], v[54:57]
	v_mfma_f32_16x16x32_bf16 v[50:53], v[182:185], v[190:193], v[50:53]
	v_mfma_f32_16x16x32_bf16 v[38:41], v[174:177], v[198:201], v[38:41]
	v_mfma_f32_16x16x32_bf16 v[34:37], v[182:185], v[198:201], v[34:37]
	v_mfma_f32_16x16x32_bf16 v[22:25], v[174:177], v[206:209], v[22:25]
	v_mfma_f32_16x16x32_bf16 v[18:21], v[182:185], v[206:209], v[18:21]
	v_mfma_f32_16x16x32_bf16 v[6:9], v[174:177], v[214:217], v[6:9]
	v_mfma_f32_16x16x32_bf16 v[2:5], v[182:185], v[214:217], v[2:5]
	s_barrier
	s_setprio 0
	s_add_i32 s61, 0, 0x18000
	v_add_u32_e32 v138, s61, v1
	s_add_i32 s62, 0, 0x1c000
	ds_read_b128 v[152:155], v138
	ds_read_b128 v[156:159], v138 offset:1024
	ds_read_b128 v[160:163], v138 offset:2048
	ds_read_b128 v[164:167], v138 offset:3072
	v_add_u32_e32 v138, s62, v1
	ds_read_b128 v[170:173], v138
	ds_read_b128 v[174:177], v138 offset:1024
	ds_read_b128 v[178:181], v138 offset:2048
	ds_read_b128 v[182:185], v138 offset:3072
	s_add_u32 s26, s26, s6
	s_addc_u32 s27, s27, s7
	s_mov_b32 m0, s42
	v_lshl_add_u64 v[230:231], s[26:27], 0, v[136:137]
	ds_read_b128 v[186:189], v150 offset:32768
	ds_read_b128 v[190:193], v150 offset:33792
	ds_read_b128 v[194:197], v150 offset:34816
	ds_read_b128 v[198:201], v150 offset:35840
	ds_read_b128 v[202:205], v150 offset:36864
	ds_read_b128 v[206:209], v150 offset:37888
	ds_read_b128 v[210:213], v150 offset:38912
	ds_read_b128 v[214:217], v150 offset:39936
	global_load_lds_dwordx4 v[230:231], off
	v_lshl_add_u64 v[230:231], s[26:27], 0, v[132:133]
	s_mov_b32 m0, s43
	s_nop 0
	global_load_lds_dwordx4 v[230:231], off
	s_waitcnt vmcnt(8)
	s_waitcnt lgkmcnt(0)
	s_barrier
	s_setprio 1
	v_mfma_f32_16x16x32_bf16 v[122:125], v[152:155], v[186:189], v[122:125]
	v_mfma_f32_16x16x32_bf16 v[126:129], v[160:163], v[186:189], v[126:129]
	v_mfma_f32_16x16x32_bf16 v[110:113], v[152:155], v[194:197], v[110:113]
	v_mfma_f32_16x16x32_bf16 v[106:109], v[160:163], v[194:197], v[106:109]
	v_mfma_f32_16x16x32_bf16 v[94:97], v[152:155], v[202:205], v[94:97]
	v_mfma_f32_16x16x32_bf16 v[90:93], v[160:163], v[202:205], v[90:93]
	v_mfma_f32_16x16x32_bf16 v[78:81], v[152:155], v[210:213], v[78:81]
	v_mfma_f32_16x16x32_bf16 v[74:77], v[160:163], v[210:213], v[74:77]
	v_mfma_f32_16x16x32_bf16 v[122:125], v[156:159], v[190:193], v[122:125]
	v_mfma_f32_16x16x32_bf16 v[126:129], v[164:167], v[190:193], v[126:129]
	v_mfma_f32_16x16x32_bf16 v[110:113], v[156:159], v[198:201], v[110:113]
	v_mfma_f32_16x16x32_bf16 v[106:109], v[164:167], v[198:201], v[106:109]
	v_mfma_f32_16x16x32_bf16 v[94:97], v[156:159], v[206:209], v[94:97]
	v_mfma_f32_16x16x32_bf16 v[90:93], v[164:167], v[206:209], v[90:93]
	v_mfma_f32_16x16x32_bf16 v[78:81], v[156:159], v[214:217], v[78:81]
	v_mfma_f32_16x16x32_bf16 v[74:77], v[164:167], v[214:217], v[74:77]
	v_mfma_f32_16x16x32_bf16 v[118:121], v[170:173], v[186:189], v[118:121]
	v_mfma_f32_16x16x32_bf16 v[114:117], v[178:181], v[186:189], v[114:117]
	v_mfma_f32_16x16x32_bf16 v[102:105], v[170:173], v[194:197], v[102:105]
	v_mfma_f32_16x16x32_bf16 v[98:101], v[178:181], v[194:197], v[98:101]
	v_mfma_f32_16x16x32_bf16 v[86:89], v[170:173], v[202:205], v[86:89]
	v_mfma_f32_16x16x32_bf16 v[82:85], v[178:181], v[202:205], v[82:85]
	v_mfma_f32_16x16x32_bf16 v[70:73], v[170:173], v[210:213], v[70:73]
	v_mfma_f32_16x16x32_bf16 v[66:69], v[178:181], v[210:213], v[66:69]
	v_mfma_f32_16x16x32_bf16 v[118:121], v[174:177], v[190:193], v[118:121]
	v_mfma_f32_16x16x32_bf16 v[114:117], v[182:185], v[190:193], v[114:117]
	v_mfma_f32_16x16x32_bf16 v[102:105], v[174:177], v[198:201], v[102:105]
	v_mfma_f32_16x16x32_bf16 v[98:101], v[182:185], v[198:201], v[98:101]
	v_mfma_f32_16x16x32_bf16 v[86:89], v[174:177], v[206:209], v[86:89]
	v_mfma_f32_16x16x32_bf16 v[82:85], v[182:185], v[206:209], v[82:85]
	v_mfma_f32_16x16x32_bf16 v[70:73], v[174:177], v[214:217], v[70:73]
	v_mfma_f32_16x16x32_bf16 v[66:69], v[182:185], v[214:217], v[66:69]
	s_barrier
	s_setprio 0
	s_add_i32 s26, s61, s36
	v_lshl_add_u64 v[218:219], v[218:219], 0, s[14:15]
	s_mov_b32 m0, s26
	ds_read_b128 v[186:189], v150 offset:49152
	ds_read_b128 v[190:193], v150 offset:50176
	ds_read_b128 v[194:197], v150 offset:51200
	ds_read_b128 v[198:201], v150 offset:52224
	ds_read_b128 v[202:205], v150 offset:53248
	ds_read_b128 v[206:209], v150 offset:54272
	ds_read_b128 v[210:213], v150 offset:55296
	ds_read_b128 v[214:217], v150 offset:56320
	global_load_lds_dwordx4 v[218:219], off
	v_lshl_add_u64 v[218:219], v[220:221], 0, s[14:15]
	s_add_i32 m0, s26, 0x2000
	s_add_i32 s26, s62, s36
	global_load_lds_dwordx4 v[218:219], off
	v_lshl_add_u64 v[218:219], v[222:223], 0, s[14:15]
	s_mov_b32 m0, s26
	s_nop 0
	global_load_lds_dwordx4 v[218:219], off
	v_lshl_add_u64 v[218:219], v[224:225], 0, s[14:15]
	s_add_i32 m0, s26, 0x2000
	s_nop 0
	global_load_lds_dwordx4 v[218:219], off
	v_lshl_add_u64 v[218:219], v[226:227], 0, s[14:15]
	s_mov_b32 m0, s48
	s_nop 0
	global_load_lds_dwordx4 v[218:219], off
	v_lshl_add_u64 v[218:219], v[228:229], 0, s[14:15]
	s_mov_b32 m0, s49
	s_nop 0
	global_load_lds_dwordx4 v[218:219], off
	s_waitcnt vmcnt(8)
	s_waitcnt lgkmcnt(0)
	s_barrier
	s_setprio 1
	v_mfma_f32_16x16x32_bf16 v[62:65], v[152:155], v[186:189], v[62:65]
	v_mfma_f32_16x16x32_bf16 v[58:61], v[160:163], v[186:189], v[58:61]
	v_mfma_f32_16x16x32_bf16 v[46:49], v[152:155], v[194:197], v[46:49]
	v_mfma_f32_16x16x32_bf16 v[42:45], v[160:163], v[194:197], v[42:45]
	v_mfma_f32_16x16x32_bf16 v[30:33], v[152:155], v[202:205], v[30:33]
	v_mfma_f32_16x16x32_bf16 v[26:29], v[160:163], v[202:205], v[26:29]
	v_mfma_f32_16x16x32_bf16 v[14:17], v[152:155], v[210:213], v[14:17]
	v_mfma_f32_16x16x32_bf16 v[10:13], v[160:163], v[210:213], v[10:13]
	v_mfma_f32_16x16x32_bf16 v[62:65], v[156:159], v[190:193], v[62:65]
	v_mfma_f32_16x16x32_bf16 v[58:61], v[164:167], v[190:193], v[58:61]
	v_mfma_f32_16x16x32_bf16 v[46:49], v[156:159], v[198:201], v[46:49]
	v_mfma_f32_16x16x32_bf16 v[42:45], v[164:167], v[198:201], v[42:45]
	v_mfma_f32_16x16x32_bf16 v[30:33], v[156:159], v[206:209], v[30:33]
	v_mfma_f32_16x16x32_bf16 v[26:29], v[164:167], v[206:209], v[26:29]
	v_mfma_f32_16x16x32_bf16 v[14:17], v[156:159], v[214:217], v[14:17]
	v_mfma_f32_16x16x32_bf16 v[10:13], v[164:167], v[214:217], v[10:13]
	v_mfma_f32_16x16x32_bf16 v[54:57], v[170:173], v[186:189], v[54:57]
	v_mfma_f32_16x16x32_bf16 v[50:53], v[178:181], v[186:189], v[50:53]
	v_mfma_f32_16x16x32_bf16 v[38:41], v[170:173], v[194:197], v[38:41]
	v_mfma_f32_16x16x32_bf16 v[34:37], v[178:181], v[194:197], v[34:37]
	v_mfma_f32_16x16x32_bf16 v[22:25], v[170:173], v[202:205], v[22:25]
	v_mfma_f32_16x16x32_bf16 v[18:21], v[178:181], v[202:205], v[18:21]
	v_mfma_f32_16x16x32_bf16 v[6:9], v[170:173], v[210:213], v[6:9]
	v_mfma_f32_16x16x32_bf16 v[2:5], v[178:181], v[210:213], v[2:5]
	v_mfma_f32_16x16x32_bf16 v[54:57], v[174:177], v[190:193], v[54:57]
	v_mfma_f32_16x16x32_bf16 v[50:53], v[182:185], v[190:193], v[50:53]
	v_mfma_f32_16x16x32_bf16 v[38:41], v[174:177], v[198:201], v[38:41]
	v_mfma_f32_16x16x32_bf16 v[34:37], v[182:185], v[198:201], v[34:37]
	v_mfma_f32_16x16x32_bf16 v[22:25], v[174:177], v[206:209], v[22:25]
	v_mfma_f32_16x16x32_bf16 v[18:21], v[182:185], v[206:209], v[18:21]
	v_mfma_f32_16x16x32_bf16 v[6:9], v[174:177], v[214:217], v[6:9]
	v_mfma_f32_16x16x32_bf16 v[2:5], v[182:185], v[214:217], v[2:5]
	s_barrier
	s_setprio 0
	s_add_u32 s24, s24, 0x100
	s_addc_u32 s25, s25, 0
	s_add_u32 s58, s58, 0x100
	s_addc_u32 s59, s59, 0
	s_cmp_ge_i32 s60, s44
	s_mov_b32 s26, s60
	s_cbranch_scc0 .LBB0_757

.LBB0_778:
	v_add_u32_e32 v138, s57, v1
	ds_read_b128 v[148:151], v138
	ds_read_b128 v[152:155], v138 offset:1024
	ds_read_b128 v[158:161], v138 offset:2048
	ds_read_b128 v[162:165], v138 offset:3072
	v_add_u32_e32 v138, s58, v1
	ds_read_b128 v[170:173], v138
	ds_read_b128 v[174:177], v138 offset:1024
	ds_read_b128 v[178:181], v138 offset:2048
	ds_read_b128 v[182:185], v138 offset:3072
	s_add_i32 s66, s28, 2
	s_add_u32 s67, s26, 0x80
	s_addc_u32 s29, s27, 0
	s_cmp_eq_u32 s55, s28
	s_cselect_b32 s28, s2, s67
	s_cselect_b32 s29, s3, s29
	s_cselect_b32 s69, s25, s65
	s_cselect_b32 s68, s24, s64
	v_lshl_add_u64 v[166:167], s[26:27], 0, v[140:141]
	s_add_i32 m0, s43, 0xc000
	ds_read_b128 v[186:189], v157
	ds_read_b128 v[190:193], v157 offset:1024
	ds_read_b128 v[194:197], v157 offset:2048
	ds_read_b128 v[198:201], v157 offset:3072
	ds_read_b128 v[202:205], v157 offset:4096
	ds_read_b128 v[206:209], v157 offset:5120
	ds_read_b128 v[210:213], v157 offset:6144
	ds_read_b128 v[214:217], v157 offset:7168
	global_load_lds_dwordx4 v[166:167], off
	v_lshl_add_u64 v[166:167], s[26:27], 0, v[142:143]
	s_add_i32 m0, s43, 0xe000
	s_nop 0
	global_load_lds_dwordx4 v[166:167], off
	s_waitcnt vmcnt(8)
	s_waitcnt lgkmcnt(0)
	s_barrier
	s_setprio 1
	v_mfma_i32_16x16x64_i8 v[126:129], v[148:151], v[186:189], v[126:129]
	v_mfma_i32_16x16x64_i8 v[122:125], v[158:161], v[186:189], v[122:125]
	v_mfma_i32_16x16x64_i8 v[118:121], v[148:151], v[194:197], v[118:121]
	v_mfma_i32_16x16x64_i8 v[114:117], v[158:161], v[194:197], v[114:117]
	v_mfma_i32_16x16x64_i8 v[106:109], v[148:151], v[202:205], v[106:109]
	v_mfma_i32_16x16x64_i8 v[98:101], v[158:161], v[202:205], v[98:101]
	v_mfma_i32_16x16x64_i8 v[90:93], v[148:151], v[210:213], v[90:93]
	v_mfma_i32_16x16x64_i8 v[82:85], v[158:161], v[210:213], v[82:85]
	v_mfma_i32_16x16x64_i8 v[126:129], v[152:155], v[190:193], v[126:129]
	v_mfma_i32_16x16x64_i8 v[122:125], v[162:165], v[190:193], v[122:125]
	v_mfma_i32_16x16x64_i8 v[118:121], v[152:155], v[198:201], v[118:121]
	v_mfma_i32_16x16x64_i8 v[114:117], v[162:165], v[198:201], v[114:117]
	v_mfma_i32_16x16x64_i8 v[106:109], v[152:155], v[206:209], v[106:109]
	v_mfma_i32_16x16x64_i8 v[98:101], v[162:165], v[206:209], v[98:101]
	v_mfma_i32_16x16x64_i8 v[90:93], v[152:155], v[214:217], v[90:93]
	v_mfma_i32_16x16x64_i8 v[82:85], v[162:165], v[214:217], v[82:85]
	v_mfma_i32_16x16x64_i8 v[110:113], v[170:173], v[186:189], v[110:113]
	v_mfma_i32_16x16x64_i8 v[102:105], v[178:181], v[186:189], v[102:105]
	v_mfma_i32_16x16x64_i8 v[94:97], v[170:173], v[194:197], v[94:97]
	v_mfma_i32_16x16x64_i8 v[86:89], v[178:181], v[194:197], v[86:89]
	v_mfma_i32_16x16x64_i8 v[78:81], v[170:173], v[202:205], v[78:81]
	v_mfma_i32_16x16x64_i8 v[74:77], v[178:181], v[202:205], v[74:77]
	v_mfma_i32_16x16x64_i8 v[70:73], v[170:173], v[210:213], v[70:73]
	v_mfma_i32_16x16x64_i8 v[66:69], v[178:181], v[210:213], v[66:69]
	v_mfma_i32_16x16x64_i8 v[110:113], v[174:177], v[190:193], v[110:113]
	v_mfma_i32_16x16x64_i8 v[102:105], v[182:185], v[190:193], v[102:105]
	v_mfma_i32_16x16x64_i8 v[94:97], v[174:177], v[198:201], v[94:97]
	v_mfma_i32_16x16x64_i8 v[86:89], v[182:185], v[198:201], v[86:89]
	v_mfma_i32_16x16x64_i8 v[78:81], v[174:177], v[206:209], v[78:81]
	v_mfma_i32_16x16x64_i8 v[74:77], v[182:185], v[206:209], v[74:77]
	v_mfma_i32_16x16x64_i8 v[70:73], v[174:177], v[214:217], v[70:73]
	v_mfma_i32_16x16x64_i8 v[66:69], v[182:185], v[214:217], v[66:69]
	s_barrier
	s_setprio 0
	s_add_i32 s67, s57, s38
	v_lshl_add_u64 v[166:167], s[68:69], 0, v[134:135]
	s_mov_b32 m0, s67
	ds_read_b128 v[186:189], v157 offset:16384
	ds_read_b128 v[190:193], v157 offset:17408
	ds_read_b128 v[194:197], v157 offset:18432
	ds_read_b128 v[198:201], v157 offset:19456
	ds_read_b128 v[202:205], v157 offset:20480
	ds_read_b128 v[206:209], v157 offset:21504
	ds_read_b128 v[210:213], v157 offset:22528
	ds_read_b128 v[214:217], v157 offset:23552
	global_load_lds_dwordx4 v[166:167], off
	s_add_i32 m0, s67, 0x2000
	v_lshl_add_u64 v[218:219], s[68:69], 0, v[130:131]
	s_add_u32 s68, s68, s6
	s_addc_u32 s69, s69, s7
	s_add_i32 s67, s58, s38
	global_load_lds_dwordx4 v[218:219], off
	v_lshl_add_u64 v[220:221], s[68:69], 0, v[134:135]
	s_mov_b32 m0, s67
	v_lshl_add_u64 v[222:223], s[68:69], 0, v[130:131]
	global_load_lds_dwordx4 v[220:221], off
	s_add_i32 m0, s67, 0x2000
	v_lshl_add_u64 v[224:225], s[28:29], 0, v[136:137]
	global_load_lds_dwordx4 v[222:223], off
	s_mov_b32 m0, s43
	v_lshl_add_u64 v[226:227], s[28:29], 0, v[132:133]
	global_load_lds_dwordx4 v[224:225], off
	s_mov_b32 m0, s44
	s_nop 0
	global_load_lds_dwordx4 v[226:227], off
	s_waitcnt vmcnt(8)
	s_waitcnt lgkmcnt(0)
	s_barrier
	s_setprio 1
	v_mfma_i32_16x16x64_i8 v[62:65], v[148:151], v[186:189], v[62:65]
	v_mfma_i32_16x16x64_i8 v[58:61], v[158:161], v[186:189], v[58:61]
	v_mfma_i32_16x16x64_i8 v[54:57], v[148:151], v[194:197], v[54:57]
	v_mfma_i32_16x16x64_i8 v[50:53], v[158:161], v[194:197], v[50:53]
	v_mfma_i32_16x16x64_i8 v[42:45], v[148:151], v[202:205], v[42:45]
	v_mfma_i32_16x16x64_i8 v[34:37], v[158:161], v[202:205], v[34:37]
	v_mfma_i32_16x16x64_i8 v[26:29], v[148:151], v[210:213], v[26:29]
	v_mfma_i32_16x16x64_i8 v[18:21], v[158:161], v[210:213], v[18:21]
	v_mfma_i32_16x16x64_i8 v[62:65], v[152:155], v[190:193], v[62:65]
	v_mfma_i32_16x16x64_i8 v[58:61], v[162:165], v[190:193], v[58:61]
	v_mfma_i32_16x16x64_i8 v[54:57], v[152:155], v[198:201], v[54:57]
	v_mfma_i32_16x16x64_i8 v[50:53], v[162:165], v[198:201], v[50:53]
	v_mfma_i32_16x16x64_i8 v[42:45], v[152:155], v[206:209], v[42:45]
	v_mfma_i32_16x16x64_i8 v[34:37], v[162:165], v[206:209], v[34:37]
	v_mfma_i32_16x16x64_i8 v[26:29], v[152:155], v[214:217], v[26:29]
	v_mfma_i32_16x16x64_i8 v[18:21], v[162:165], v[214:217], v[18:21]
	v_mfma_i32_16x16x64_i8 v[46:49], v[170:173], v[186:189], v[46:49]
	v_mfma_i32_16x16x64_i8 v[38:41], v[178:181], v[186:189], v[38:41]
	v_mfma_i32_16x16x64_i8 v[30:33], v[170:173], v[194:197], v[30:33]
	v_mfma_i32_16x16x64_i8 v[22:25], v[178:181], v[194:197], v[22:25]
	v_mfma_i32_16x16x64_i8 v[14:17], v[170:173], v[202:205], v[14:17]
	v_mfma_i32_16x16x64_i8 v[10:13], v[178:181], v[202:205], v[10:13]
	v_mfma_i32_16x16x64_i8 v[6:9], v[170:173], v[210:213], v[6:9]
	v_mfma_i32_16x16x64_i8 v[2:5], v[178:181], v[210:213], v[2:5]
	v_mfma_i32_16x16x64_i8 v[46:49], v[174:177], v[190:193], v[46:49]
	v_mfma_i32_16x16x64_i8 v[38:41], v[182:185], v[190:193], v[38:41]
	v_mfma_i32_16x16x64_i8 v[30:33], v[174:177], v[198:201], v[30:33]
	v_mfma_i32_16x16x64_i8 v[22:25], v[182:185], v[198:201], v[22:25]
	v_mfma_i32_16x16x64_i8 v[14:17], v[174:177], v[206:209], v[14:17]
	v_mfma_i32_16x16x64_i8 v[10:13], v[182:185], v[206:209], v[10:13]
	v_mfma_i32_16x16x64_i8 v[6:9], v[174:177], v[214:217], v[6:9]
	v_mfma_i32_16x16x64_i8 v[2:5], v[182:185], v[214:217], v[2:5]
	s_barrier
	s_setprio 0
	s_add_i32 s67, 0, 0x18000
	v_add_u32_e32 v138, s67, v1
	s_add_i32 s68, 0, 0x1c000
	ds_read_b128 v[148:151], v138
	ds_read_b128 v[152:155], v138 offset:1024
	ds_read_b128 v[158:161], v138 offset:2048
	ds_read_b128 v[162:165], v138 offset:3072
	v_add_u32_e32 v138, s68, v1
	ds_read_b128 v[170:173], v138
	ds_read_b128 v[174:177], v138 offset:1024
	ds_read_b128 v[178:181], v138 offset:2048
	ds_read_b128 v[182:185], v138 offset:3072
	s_add_u32 s28, s28, s6
	s_addc_u32 s29, s29, s7
	s_mov_b32 m0, s45
	v_lshl_add_u64 v[228:229], s[28:29], 0, v[136:137]
	ds_read_b128 v[186:189], v157 offset:32768
	ds_read_b128 v[190:193], v157 offset:33792
	ds_read_b128 v[194:197], v157 offset:34816
	ds_read_b128 v[198:201], v157 offset:35840
	ds_read_b128 v[202:205], v157 offset:36864
	ds_read_b128 v[206:209], v157 offset:37888
	ds_read_b128 v[210:213], v157 offset:38912
	ds_read_b128 v[214:217], v157 offset:39936
	global_load_lds_dwordx4 v[228:229], off
	v_lshl_add_u64 v[228:229], s[28:29], 0, v[132:133]
	s_mov_b32 m0, s46
	s_nop 0
	global_load_lds_dwordx4 v[228:229], off
	s_waitcnt vmcnt(8)
	s_waitcnt lgkmcnt(0)
	s_barrier
	s_setprio 1
	v_mfma_i32_16x16x64_i8 v[126:129], v[148:151], v[186:189], v[126:129]
	v_mfma_i32_16x16x64_i8 v[122:125], v[158:161], v[186:189], v[122:125]
	v_mfma_i32_16x16x64_i8 v[118:121], v[148:151], v[194:197], v[118:121]
	v_mfma_i32_16x16x64_i8 v[114:117], v[158:161], v[194:197], v[114:117]
	v_mfma_i32_16x16x64_i8 v[106:109], v[148:151], v[202:205], v[106:109]
	v_mfma_i32_16x16x64_i8 v[98:101], v[158:161], v[202:205], v[98:101]
	v_mfma_i32_16x16x64_i8 v[90:93], v[148:151], v[210:213], v[90:93]
	v_mfma_i32_16x16x64_i8 v[82:85], v[158:161], v[210:213], v[82:85]
	v_mfma_i32_16x16x64_i8 v[126:129], v[152:155], v[190:193], v[126:129]
	v_mfma_i32_16x16x64_i8 v[122:125], v[162:165], v[190:193], v[122:125]
	v_mfma_i32_16x16x64_i8 v[118:121], v[152:155], v[198:201], v[118:121]
	v_mfma_i32_16x16x64_i8 v[114:117], v[162:165], v[198:201], v[114:117]
	v_mfma_i32_16x16x64_i8 v[106:109], v[152:155], v[206:209], v[106:109]
	v_mfma_i32_16x16x64_i8 v[98:101], v[162:165], v[206:209], v[98:101]
	v_mfma_i32_16x16x64_i8 v[90:93], v[152:155], v[214:217], v[90:93]
	v_mfma_i32_16x16x64_i8 v[82:85], v[162:165], v[214:217], v[82:85]
	v_mfma_i32_16x16x64_i8 v[110:113], v[170:173], v[186:189], v[110:113]
	v_mfma_i32_16x16x64_i8 v[102:105], v[178:181], v[186:189], v[102:105]
	v_mfma_i32_16x16x64_i8 v[94:97], v[170:173], v[194:197], v[94:97]
	v_mfma_i32_16x16x64_i8 v[86:89], v[178:181], v[194:197], v[86:89]
	v_mfma_i32_16x16x64_i8 v[78:81], v[170:173], v[202:205], v[78:81]
	v_mfma_i32_16x16x64_i8 v[74:77], v[178:181], v[202:205], v[74:77]
	v_mfma_i32_16x16x64_i8 v[70:73], v[170:173], v[210:213], v[70:73]
	v_mfma_i32_16x16x64_i8 v[66:69], v[178:181], v[210:213], v[66:69]
	v_mfma_i32_16x16x64_i8 v[110:113], v[174:177], v[190:193], v[110:113]
	v_mfma_i32_16x16x64_i8 v[102:105], v[182:185], v[190:193], v[102:105]
	v_mfma_i32_16x16x64_i8 v[94:97], v[174:177], v[198:201], v[94:97]
	v_mfma_i32_16x16x64_i8 v[86:89], v[182:185], v[198:201], v[86:89]
	v_mfma_i32_16x16x64_i8 v[78:81], v[174:177], v[206:209], v[78:81]
	v_mfma_i32_16x16x64_i8 v[74:77], v[182:185], v[206:209], v[74:77]
	v_mfma_i32_16x16x64_i8 v[70:73], v[174:177], v[214:217], v[70:73]
	v_mfma_i32_16x16x64_i8 v[66:69], v[182:185], v[214:217], v[66:69]
	s_barrier
	s_setprio 0
	s_add_i32 s28, s67, s38
	v_lshl_add_u64 v[166:167], v[166:167], 0, s[16:17]
	s_mov_b32 m0, s28
	ds_read_b128 v[186:189], v157 offset:49152
	ds_read_b128 v[190:193], v157 offset:50176
	ds_read_b128 v[194:197], v157 offset:51200
	ds_read_b128 v[198:201], v157 offset:52224
	ds_read_b128 v[202:205], v157 offset:53248
	ds_read_b128 v[206:209], v157 offset:54272
	ds_read_b128 v[210:213], v157 offset:55296
	ds_read_b128 v[214:217], v157 offset:56320
	global_load_lds_dwordx4 v[166:167], off
	v_lshl_add_u64 v[166:167], v[218:219], 0, s[16:17]
	s_add_i32 m0, s28, 0x2000
	s_add_i32 s28, s68, s38
	global_load_lds_dwordx4 v[166:167], off
	v_lshl_add_u64 v[166:167], v[220:221], 0, s[16:17]
	s_mov_b32 m0, s28
	s_nop 0
	global_load_lds_dwordx4 v[166:167], off
	v_lshl_add_u64 v[166:167], v[222:223], 0, s[16:17]
	s_add_i32 m0, s28, 0x2000
	s_nop 0
	global_load_lds_dwordx4 v[166:167], off
	v_lshl_add_u64 v[166:167], v[224:225], 0, s[16:17]
	s_mov_b32 m0, s53
	s_nop 0
	global_load_lds_dwordx4 v[166:167], off
	v_lshl_add_u64 v[166:167], v[226:227], 0, s[16:17]
	s_mov_b32 m0, s54
	s_nop 0
	global_load_lds_dwordx4 v[166:167], off
	s_waitcnt vmcnt(8)
	s_waitcnt lgkmcnt(0)
	s_barrier
	s_setprio 1
	v_mfma_i32_16x16x64_i8 v[62:65], v[148:151], v[186:189], v[62:65]
	v_mfma_i32_16x16x64_i8 v[58:61], v[158:161], v[186:189], v[58:61]
	v_mfma_i32_16x16x64_i8 v[54:57], v[148:151], v[194:197], v[54:57]
	v_mfma_i32_16x16x64_i8 v[50:53], v[158:161], v[194:197], v[50:53]
	v_mfma_i32_16x16x64_i8 v[42:45], v[148:151], v[202:205], v[42:45]
	v_mfma_i32_16x16x64_i8 v[34:37], v[158:161], v[202:205], v[34:37]
	v_mfma_i32_16x16x64_i8 v[26:29], v[148:151], v[210:213], v[26:29]
	v_mfma_i32_16x16x64_i8 v[18:21], v[158:161], v[210:213], v[18:21]
	v_mfma_i32_16x16x64_i8 v[62:65], v[152:155], v[190:193], v[62:65]
	v_mfma_i32_16x16x64_i8 v[58:61], v[162:165], v[190:193], v[58:61]
	v_mfma_i32_16x16x64_i8 v[54:57], v[152:155], v[198:201], v[54:57]
	v_mfma_i32_16x16x64_i8 v[50:53], v[162:165], v[198:201], v[50:53]
	v_mfma_i32_16x16x64_i8 v[42:45], v[152:155], v[206:209], v[42:45]
	v_mfma_i32_16x16x64_i8 v[34:37], v[162:165], v[206:209], v[34:37]
	v_mfma_i32_16x16x64_i8 v[26:29], v[152:155], v[214:217], v[26:29]
	v_mfma_i32_16x16x64_i8 v[18:21], v[162:165], v[214:217], v[18:21]
	v_mfma_i32_16x16x64_i8 v[46:49], v[170:173], v[186:189], v[46:49]
	v_mfma_i32_16x16x64_i8 v[38:41], v[178:181], v[186:189], v[38:41]
	v_mfma_i32_16x16x64_i8 v[30:33], v[170:173], v[194:197], v[30:33]
	v_mfma_i32_16x16x64_i8 v[22:25], v[178:181], v[194:197], v[22:25]
	v_mfma_i32_16x16x64_i8 v[14:17], v[170:173], v[202:205], v[14:17]
	v_mfma_i32_16x16x64_i8 v[10:13], v[178:181], v[202:205], v[10:13]
	v_mfma_i32_16x16x64_i8 v[6:9], v[170:173], v[210:213], v[6:9]
	v_mfma_i32_16x16x64_i8 v[2:5], v[178:181], v[210:213], v[2:5]
	v_mfma_i32_16x16x64_i8 v[46:49], v[174:177], v[190:193], v[46:49]
	v_mfma_i32_16x16x64_i8 v[38:41], v[182:185], v[190:193], v[38:41]
	v_mfma_i32_16x16x64_i8 v[30:33], v[174:177], v[198:201], v[30:33]
	v_mfma_i32_16x16x64_i8 v[22:25], v[182:185], v[198:201], v[22:25]
	v_mfma_i32_16x16x64_i8 v[14:17], v[174:177], v[206:209], v[14:17]
	v_mfma_i32_16x16x64_i8 v[10:13], v[182:185], v[206:209], v[10:13]
	v_mfma_i32_16x16x64_i8 v[6:9], v[174:177], v[214:217], v[6:9]
	v_mfma_i32_16x16x64_i8 v[2:5], v[182:185], v[214:217], v[2:5]
	s_barrier
	s_setprio 0
	s_add_u32 s26, s26, 0x100
	s_addc_u32 s27, s27, 0
	s_add_u32 s64, s64, 0x100
	s_addc_u32 s65, s65, 0
	s_cmp_ge_i32 s66, s50
	s_mov_b32 s28, s66
	s_cbranch_scc0 .LBB0_778
	v_cvt_f32_i32_e32 v162, v126
	v_cvt_f32_i32_e32 v163, v127
	v_cvt_f32_i32_e32 v160, v128
	v_cvt_f32_i32_e32 v161, v129
	v_cvt_f32_i32_e32 v164, v122
	v_cvt_f32_i32_e32 v165, v123
	v_cvt_f32_i32_e32 v166, v124
	v_cvt_f32_i32_e32 v167, v125
	v_cvt_f32_i32_e32 v148, v110
	v_cvt_f32_i32_e32 v149, v111
	v_cvt_f32_i32_e32 v150, v112
	v_cvt_f32_i32_e32 v151, v113
	v_cvt_f32_i32_e32 v126, v102
	v_cvt_f32_i32_e32 v127, v103
	v_cvt_f32_i32_e32 v128, v104
	v_cvt_f32_i32_e32 v129, v105
	v_cvt_f32_i32_e32 v122, v118
	v_cvt_f32_i32_e32 v123, v119
	v_cvt_f32_i32_e32 v124, v120
	v_cvt_f32_i32_e32 v125, v121
	v_cvt_f32_i32_e32 v118, v114
	v_cvt_f32_i32_e32 v119, v115
	v_cvt_f32_i32_e32 v120, v116
	v_cvt_f32_i32_e32 v121, v117
	v_cvt_f32_i32_e32 v112, v94
	v_cvt_f32_i32_e32 v113, v95
	v_cvt_f32_i32_e32 v116, v96
	v_cvt_f32_i32_e32 v117, v97
	v_cvt_f32_i32_e32 v110, v86
	v_cvt_f32_i32_e32 v111, v87
	v_cvt_f32_i32_e32 v114, v88
	v_cvt_f32_i32_e32 v115, v89
	v_cvt_f32_i32_e32 v96, v106
	v_cvt_f32_i32_e32 v97, v107
	v_cvt_f32_i32_e32 v102, v108
	v_cvt_f32_i32_e32 v103, v109
	v_cvt_f32_i32_e32 v94, v98
	v_cvt_f32_i32_e32 v95, v99
	v_cvt_f32_i32_e32 v98, v100
	v_cvt_f32_i32_e32 v99, v101
	v_cvt_f32_i32_e32 v104, v78
	v_cvt_f32_i32_e32 v105, v79
	v_cvt_f32_i32_e32 v108, v80
	v_cvt_f32_i32_e32 v109, v81
	v_cvt_f32_i32_e32 v100, v74
	v_cvt_f32_i32_e32 v101, v75
	v_cvt_f32_i32_e32 v106, v76
	v_cvt_f32_i32_e32 v107, v77
	v_cvt_f32_i32_e32 v76, v90
	v_cvt_f32_i32_e32 v77, v91
	v_cvt_f32_i32_e32 v80, v92
	v_cvt_f32_i32_e32 v81, v93
	v_cvt_f32_i32_e32 v74, v82
	v_cvt_f32_i32_e32 v75, v83
	v_cvt_f32_i32_e32 v78, v84
	v_cvt_f32_i32_e32 v79, v85
	v_cvt_f32_i32_e32 v82, v70
	v_cvt_f32_i32_e32 v83, v71
	v_cvt_f32_i32_e32 v88, v72
	v_cvt_f32_i32_e32 v89, v73
	v_cvt_f32_i32_e32 v70, v66
	v_cvt_f32_i32_e32 v71, v67
	v_cvt_f32_i32_e32 v86, v68
	v_cvt_f32_i32_e32 v87, v69
	v_cvt_f32_i32_e32 v66, v62
	v_cvt_f32_i32_e32 v67, v63
	v_cvt_f32_i32_e32 v68, v64
	v_cvt_f32_i32_e32 v69, v65
	v_cvt_f32_i32_e32 v62, v58
	v_cvt_f32_i32_e32 v63, v59
	v_cvt_f32_i32_e32 v64, v60
	v_cvt_f32_i32_e32 v65, v61
	v_cvt_f32_i32_e32 v84, v46
	v_cvt_f32_i32_e32 v85, v47
	v_cvt_f32_i32_e32 v92, v48
	v_cvt_f32_i32_e32 v93, v49
	v_cvt_f32_i32_e32 v72, v38
	v_cvt_f32_i32_e32 v73, v39
	v_cvt_f32_i32_e32 v90, v40
	v_cvt_f32_i32_e32 v91, v41
	v_cvt_f32_i32_e32 v48, v54
	v_cvt_f32_i32_e32 v49, v55
	v_cvt_f32_i32_e32 v54, v56
	v_cvt_f32_i32_e32 v55, v57
	v_cvt_f32_i32_e32 v46, v50
	v_cvt_f32_i32_e32 v47, v51
	v_cvt_f32_i32_e32 v50, v52
	v_cvt_f32_i32_e32 v51, v53
	v_cvt_f32_i32_e32 v56, v30
	v_cvt_f32_i32_e32 v57, v31
	v_cvt_f32_i32_e32 v60, v32
	v_cvt_f32_i32_e32 v61, v33
	v_cvt_f32_i32_e32 v52, v22
	v_cvt_f32_i32_e32 v53, v23
	v_cvt_f32_i32_e32 v58, v24
	v_cvt_f32_i32_e32 v59, v25
	v_cvt_f32_i32_e32 v24, v42
	v_cvt_f32_i32_e32 v25, v43
	v_cvt_f32_i32_e32 v32, v44
	v_cvt_f32_i32_e32 v33, v45
	v_cvt_f32_i32_e32 v22, v34
	v_cvt_f32_i32_e32 v23, v35
	v_cvt_f32_i32_e32 v30, v36
	v_cvt_f32_i32_e32 v31, v37
	v_cvt_f32_i32_e32 v36, v14
	v_cvt_f32_i32_e32 v37, v15
	v_cvt_f32_i32_e32 v40, v16
	v_cvt_f32_i32_e32 v41, v17
	v_cvt_f32_i32_e32 v34, v10
	v_cvt_f32_i32_e32 v35, v11
	v_cvt_f32_i32_e32 v38, v12
	v_cvt_f32_i32_e32 v39, v13
	v_cvt_f32_i32_e32 v12, v26
	v_cvt_f32_i32_e32 v13, v27
	v_cvt_f32_i32_e32 v16, v28
	v_cvt_f32_i32_e32 v17, v29
	v_cvt_f32_i32_e32 v10, v18
	v_cvt_f32_i32_e32 v11, v19
	v_cvt_f32_i32_e32 v14, v20
	v_cvt_f32_i32_e32 v15, v21
	v_cvt_f32_i32_e32 v6, v6
	v_cvt_f32_i32_e32 v7, v7
	v_cvt_f32_i32_e32 v8, v8
	v_cvt_f32_i32_e32 v9, v9
	v_cvt_f32_i32_e32 v2, v2
	v_cvt_f32_i32_e32 v3, v3
	v_cvt_f32_i32_e32 v4, v4
	v_cvt_f32_i32_e32 v5, v5

.LBB0_800:
	v_add_u32_e32 v138, s55, v1
	ds_read_b128 v[148:151], v138
	ds_read_b128 v[152:155], v138 offset:1024
	ds_read_b128 v[158:161], v138 offset:2048
	ds_read_b128 v[162:165], v138 offset:3072
	v_add_u32_e32 v138, s56, v1
	ds_read_b128 v[170:173], v138
	ds_read_b128 v[174:177], v138 offset:1024
	ds_read_b128 v[178:181], v138 offset:2048
	ds_read_b128 v[182:185], v138 offset:3072
	s_add_i32 s63, s28, 2
	s_add_u32 s64, s26, 0x80
	s_addc_u32 s29, s27, 0
	s_cmp_eq_u32 s53, s28
	s_cselect_b32 s28, s2, s64
	s_cselect_b32 s29, s3, s29
	s_cselect_b32 s65, s25, s62
	s_cselect_b32 s64, s24, s61
	v_lshl_add_u64 v[166:167], s[26:27], 0, v[140:141]
	s_add_i32 m0, s39, 0xc000
	ds_read_b128 v[186:189], v157
	ds_read_b128 v[190:193], v157 offset:1024
	ds_read_b128 v[194:197], v157 offset:2048
	ds_read_b128 v[198:201], v157 offset:3072
	ds_read_b128 v[202:205], v157 offset:4096
	ds_read_b128 v[206:209], v157 offset:5120
	ds_read_b128 v[210:213], v157 offset:6144
	ds_read_b128 v[214:217], v157 offset:7168
	global_load_lds_dwordx4 v[166:167], off
	v_lshl_add_u64 v[166:167], s[26:27], 0, v[142:143]
	s_add_i32 m0, s39, 0xe000
	s_nop 0
	global_load_lds_dwordx4 v[166:167], off
	s_waitcnt vmcnt(8)
	s_waitcnt lgkmcnt(0)
	s_barrier
	s_setprio 1
	v_mfma_i32_16x16x64_i8 v[126:129], v[148:151], v[186:189], v[126:129]
	v_mfma_i32_16x16x64_i8 v[122:125], v[158:161], v[186:189], v[122:125]
	v_mfma_i32_16x16x64_i8 v[118:121], v[148:151], v[194:197], v[118:121]
	v_mfma_i32_16x16x64_i8 v[114:117], v[158:161], v[194:197], v[114:117]
	v_mfma_i32_16x16x64_i8 v[106:109], v[148:151], v[202:205], v[106:109]
	v_mfma_i32_16x16x64_i8 v[98:101], v[158:161], v[202:205], v[98:101]
	v_mfma_i32_16x16x64_i8 v[90:93], v[148:151], v[210:213], v[90:93]
	v_mfma_i32_16x16x64_i8 v[82:85], v[158:161], v[210:213], v[82:85]
	v_mfma_i32_16x16x64_i8 v[126:129], v[152:155], v[190:193], v[126:129]
	v_mfma_i32_16x16x64_i8 v[122:125], v[162:165], v[190:193], v[122:125]
	v_mfma_i32_16x16x64_i8 v[118:121], v[152:155], v[198:201], v[118:121]
	v_mfma_i32_16x16x64_i8 v[114:117], v[162:165], v[198:201], v[114:117]
	v_mfma_i32_16x16x64_i8 v[106:109], v[152:155], v[206:209], v[106:109]
	v_mfma_i32_16x16x64_i8 v[98:101], v[162:165], v[206:209], v[98:101]
	v_mfma_i32_16x16x64_i8 v[90:93], v[152:155], v[214:217], v[90:93]
	v_mfma_i32_16x16x64_i8 v[82:85], v[162:165], v[214:217], v[82:85]
	v_mfma_i32_16x16x64_i8 v[110:113], v[170:173], v[186:189], v[110:113]
	v_mfma_i32_16x16x64_i8 v[102:105], v[178:181], v[186:189], v[102:105]
	v_mfma_i32_16x16x64_i8 v[94:97], v[170:173], v[194:197], v[94:97]
	v_mfma_i32_16x16x64_i8 v[86:89], v[178:181], v[194:197], v[86:89]
	v_mfma_i32_16x16x64_i8 v[78:81], v[170:173], v[202:205], v[78:81]
	v_mfma_i32_16x16x64_i8 v[74:77], v[178:181], v[202:205], v[74:77]
	v_mfma_i32_16x16x64_i8 v[70:73], v[170:173], v[210:213], v[70:73]
	v_mfma_i32_16x16x64_i8 v[66:69], v[178:181], v[210:213], v[66:69]
	v_mfma_i32_16x16x64_i8 v[110:113], v[174:177], v[190:193], v[110:113]
	v_mfma_i32_16x16x64_i8 v[102:105], v[182:185], v[190:193], v[102:105]
	v_mfma_i32_16x16x64_i8 v[94:97], v[174:177], v[198:201], v[94:97]
	v_mfma_i32_16x16x64_i8 v[86:89], v[182:185], v[198:201], v[86:89]
	v_mfma_i32_16x16x64_i8 v[78:81], v[174:177], v[206:209], v[78:81]
	v_mfma_i32_16x16x64_i8 v[74:77], v[182:185], v[206:209], v[74:77]
	v_mfma_i32_16x16x64_i8 v[70:73], v[174:177], v[214:217], v[70:73]
	v_mfma_i32_16x16x64_i8 v[66:69], v[182:185], v[214:217], v[66:69]
	s_barrier
	s_setprio 0
	s_add_i32 s66, s55, s36
	v_lshl_add_u64 v[166:167], s[64:65], 0, v[134:135]
	s_mov_b32 m0, s66
	ds_read_b128 v[186:189], v157 offset:16384
	ds_read_b128 v[190:193], v157 offset:17408
	ds_read_b128 v[194:197], v157 offset:18432
	ds_read_b128 v[198:201], v157 offset:19456
	ds_read_b128 v[202:205], v157 offset:20480
	ds_read_b128 v[206:209], v157 offset:21504
	ds_read_b128 v[210:213], v157 offset:22528
	ds_read_b128 v[214:217], v157 offset:23552
	global_load_lds_dwordx4 v[166:167], off
	s_add_i32 m0, s66, 0x2000
	v_lshl_add_u64 v[218:219], s[64:65], 0, v[130:131]
	s_add_u32 s64, s64, s6
	s_addc_u32 s65, s65, s7
	s_add_i32 s66, s56, s36
	global_load_lds_dwordx4 v[218:219], off
	v_lshl_add_u64 v[220:221], s[64:65], 0, v[134:135]
	s_mov_b32 m0, s66
	v_lshl_add_u64 v[222:223], s[64:65], 0, v[130:131]
	global_load_lds_dwordx4 v[220:221], off
	s_add_i32 m0, s66, 0x2000
	v_lshl_add_u64 v[224:225], s[28:29], 0, v[136:137]
	global_load_lds_dwordx4 v[222:223], off
	s_mov_b32 m0, s39
	v_lshl_add_u64 v[226:227], s[28:29], 0, v[132:133]
	global_load_lds_dwordx4 v[224:225], off
	s_mov_b32 m0, s42
	s_nop 0
	global_load_lds_dwordx4 v[226:227], off
	s_waitcnt vmcnt(8)
	s_waitcnt lgkmcnt(0)
	s_barrier
	s_setprio 1
	v_mfma_i32_16x16x64_i8 v[62:65], v[148:151], v[186:189], v[62:65]
	v_mfma_i32_16x16x64_i8 v[58:61], v[158:161], v[186:189], v[58:61]
	v_mfma_i32_16x16x64_i8 v[54:57], v[148:151], v[194:197], v[54:57]
	v_mfma_i32_16x16x64_i8 v[50:53], v[158:161], v[194:197], v[50:53]
	v_mfma_i32_16x16x64_i8 v[42:45], v[148:151], v[202:205], v[42:45]
	v_mfma_i32_16x16x64_i8 v[34:37], v[158:161], v[202:205], v[34:37]
	v_mfma_i32_16x16x64_i8 v[26:29], v[148:151], v[210:213], v[26:29]
	v_mfma_i32_16x16x64_i8 v[18:21], v[158:161], v[210:213], v[18:21]
	v_mfma_i32_16x16x64_i8 v[62:65], v[152:155], v[190:193], v[62:65]
	v_mfma_i32_16x16x64_i8 v[58:61], v[162:165], v[190:193], v[58:61]
	v_mfma_i32_16x16x64_i8 v[54:57], v[152:155], v[198:201], v[54:57]
	v_mfma_i32_16x16x64_i8 v[50:53], v[162:165], v[198:201], v[50:53]
	v_mfma_i32_16x16x64_i8 v[42:45], v[152:155], v[206:209], v[42:45]
	v_mfma_i32_16x16x64_i8 v[34:37], v[162:165], v[206:209], v[34:37]
	v_mfma_i32_16x16x64_i8 v[26:29], v[152:155], v[214:217], v[26:29]
	v_mfma_i32_16x16x64_i8 v[18:21], v[162:165], v[214:217], v[18:21]
	v_mfma_i32_16x16x64_i8 v[46:49], v[170:173], v[186:189], v[46:49]
	v_mfma_i32_16x16x64_i8 v[38:41], v[178:181], v[186:189], v[38:41]
	v_mfma_i32_16x16x64_i8 v[30:33], v[170:173], v[194:197], v[30:33]
	v_mfma_i32_16x16x64_i8 v[22:25], v[178:181], v[194:197], v[22:25]
	v_mfma_i32_16x16x64_i8 v[14:17], v[170:173], v[202:205], v[14:17]
	v_mfma_i32_16x16x64_i8 v[10:13], v[178:181], v[202:205], v[10:13]
	v_mfma_i32_16x16x64_i8 v[6:9], v[170:173], v[210:213], v[6:9]
	v_mfma_i32_16x16x64_i8 v[2:5], v[178:181], v[210:213], v[2:5]
	v_mfma_i32_16x16x64_i8 v[46:49], v[174:177], v[190:193], v[46:49]
	v_mfma_i32_16x16x64_i8 v[38:41], v[182:185], v[190:193], v[38:41]
	v_mfma_i32_16x16x64_i8 v[30:33], v[174:177], v[198:201], v[30:33]
	v_mfma_i32_16x16x64_i8 v[22:25], v[182:185], v[198:201], v[22:25]
	v_mfma_i32_16x16x64_i8 v[14:17], v[174:177], v[206:209], v[14:17]
	v_mfma_i32_16x16x64_i8 v[10:13], v[182:185], v[206:209], v[10:13]
	v_mfma_i32_16x16x64_i8 v[6:9], v[174:177], v[214:217], v[6:9]
	v_mfma_i32_16x16x64_i8 v[2:5], v[182:185], v[214:217], v[2:5]
	s_barrier
	s_setprio 0
	s_add_i32 s64, 0, 0x18000
	v_add_u32_e32 v138, s64, v1
	s_add_i32 s65, 0, 0x1c000
	ds_read_b128 v[148:151], v138
	ds_read_b128 v[152:155], v138 offset:1024
	ds_read_b128 v[158:161], v138 offset:2048
	ds_read_b128 v[162:165], v138 offset:3072
	v_add_u32_e32 v138, s65, v1
	ds_read_b128 v[170:173], v138
	ds_read_b128 v[174:177], v138 offset:1024
	ds_read_b128 v[178:181], v138 offset:2048
	ds_read_b128 v[182:185], v138 offset:3072
	s_add_u32 s28, s28, s6
	s_addc_u32 s29, s29, s7
	s_mov_b32 m0, s43
	v_lshl_add_u64 v[228:229], s[28:29], 0, v[136:137]
	ds_read_b128 v[186:189], v157 offset:32768
	ds_read_b128 v[190:193], v157 offset:33792
	ds_read_b128 v[194:197], v157 offset:34816
	ds_read_b128 v[198:201], v157 offset:35840
	ds_read_b128 v[202:205], v157 offset:36864
	ds_read_b128 v[206:209], v157 offset:37888
	ds_read_b128 v[210:213], v157 offset:38912
	ds_read_b128 v[214:217], v157 offset:39936
	global_load_lds_dwordx4 v[228:229], off
	v_lshl_add_u64 v[228:229], s[28:29], 0, v[132:133]
	s_mov_b32 m0, s44
	s_nop 0
	global_load_lds_dwordx4 v[228:229], off
	s_waitcnt vmcnt(8)
	s_waitcnt lgkmcnt(0)
	s_barrier
	s_setprio 1
	v_mfma_i32_16x16x64_i8 v[126:129], v[148:151], v[186:189], v[126:129]
	v_mfma_i32_16x16x64_i8 v[122:125], v[158:161], v[186:189], v[122:125]
	v_mfma_i32_16x16x64_i8 v[118:121], v[148:151], v[194:197], v[118:121]
	v_mfma_i32_16x16x64_i8 v[114:117], v[158:161], v[194:197], v[114:117]
	v_mfma_i32_16x16x64_i8 v[106:109], v[148:151], v[202:205], v[106:109]
	v_mfma_i32_16x16x64_i8 v[98:101], v[158:161], v[202:205], v[98:101]
	v_mfma_i32_16x16x64_i8 v[90:93], v[148:151], v[210:213], v[90:93]
	v_mfma_i32_16x16x64_i8 v[82:85], v[158:161], v[210:213], v[82:85]
	v_mfma_i32_16x16x64_i8 v[126:129], v[152:155], v[190:193], v[126:129]
	v_mfma_i32_16x16x64_i8 v[122:125], v[162:165], v[190:193], v[122:125]
	v_mfma_i32_16x16x64_i8 v[118:121], v[152:155], v[198:201], v[118:121]
	v_mfma_i32_16x16x64_i8 v[114:117], v[162:165], v[198:201], v[114:117]
	v_mfma_i32_16x16x64_i8 v[106:109], v[152:155], v[206:209], v[106:109]
	v_mfma_i32_16x16x64_i8 v[98:101], v[162:165], v[206:209], v[98:101]
	v_mfma_i32_16x16x64_i8 v[90:93], v[152:155], v[214:217], v[90:93]
	v_mfma_i32_16x16x64_i8 v[82:85], v[162:165], v[214:217], v[82:85]
	v_mfma_i32_16x16x64_i8 v[110:113], v[170:173], v[186:189], v[110:113]
	v_mfma_i32_16x16x64_i8 v[102:105], v[178:181], v[186:189], v[102:105]
	v_mfma_i32_16x16x64_i8 v[94:97], v[170:173], v[194:197], v[94:97]
	v_mfma_i32_16x16x64_i8 v[86:89], v[178:181], v[194:197], v[86:89]
	v_mfma_i32_16x16x64_i8 v[78:81], v[170:173], v[202:205], v[78:81]
	v_mfma_i32_16x16x64_i8 v[74:77], v[178:181], v[202:205], v[74:77]
	v_mfma_i32_16x16x64_i8 v[70:73], v[170:173], v[210:213], v[70:73]
	v_mfma_i32_16x16x64_i8 v[66:69], v[178:181], v[210:213], v[66:69]
	v_mfma_i32_16x16x64_i8 v[110:113], v[174:177], v[190:193], v[110:113]
	v_mfma_i32_16x16x64_i8 v[102:105], v[182:185], v[190:193], v[102:105]
	v_mfma_i32_16x16x64_i8 v[94:97], v[174:177], v[198:201], v[94:97]
	v_mfma_i32_16x16x64_i8 v[86:89], v[182:185], v[198:201], v[86:89]
	v_mfma_i32_16x16x64_i8 v[78:81], v[174:177], v[206:209], v[78:81]
	v_mfma_i32_16x16x64_i8 v[74:77], v[182:185], v[206:209], v[74:77]
	v_mfma_i32_16x16x64_i8 v[70:73], v[174:177], v[214:217], v[70:73]
	v_mfma_i32_16x16x64_i8 v[66:69], v[182:185], v[214:217], v[66:69]
	s_barrier
	s_setprio 0
	s_add_i32 s28, s64, s36
	v_lshl_add_u64 v[166:167], v[166:167], 0, s[16:17]
	s_mov_b32 m0, s28
	ds_read_b128 v[186:189], v157 offset:49152
	ds_read_b128 v[190:193], v157 offset:50176
	ds_read_b128 v[194:197], v157 offset:51200
	ds_read_b128 v[198:201], v157 offset:52224
	ds_read_b128 v[202:205], v157 offset:53248
	ds_read_b128 v[206:209], v157 offset:54272
	ds_read_b128 v[210:213], v157 offset:55296
	ds_read_b128 v[214:217], v157 offset:56320
	global_load_lds_dwordx4 v[166:167], off
	v_lshl_add_u64 v[166:167], v[218:219], 0, s[16:17]
	s_add_i32 m0, s28, 0x2000
	s_add_i32 s28, s65, s36
	global_load_lds_dwordx4 v[166:167], off
	v_lshl_add_u64 v[166:167], v[220:221], 0, s[16:17]
	s_mov_b32 m0, s28
	s_nop 0
	global_load_lds_dwordx4 v[166:167], off
	v_lshl_add_u64 v[166:167], v[222:223], 0, s[16:17]
	s_add_i32 m0, s28, 0x2000
	s_nop 0
	global_load_lds_dwordx4 v[166:167], off
	v_lshl_add_u64 v[166:167], v[224:225], 0, s[16:17]
	s_mov_b32 m0, s51
	s_nop 0
	global_load_lds_dwordx4 v[166:167], off
	v_lshl_add_u64 v[166:167], v[226:227], 0, s[16:17]
	s_mov_b32 m0, s52
	s_nop 0
	global_load_lds_dwordx4 v[166:167], off
	s_waitcnt vmcnt(8)
	s_waitcnt lgkmcnt(0)
	s_barrier
	s_setprio 1
	v_mfma_i32_16x16x64_i8 v[62:65], v[148:151], v[186:189], v[62:65]
	v_mfma_i32_16x16x64_i8 v[58:61], v[158:161], v[186:189], v[58:61]
	v_mfma_i32_16x16x64_i8 v[54:57], v[148:151], v[194:197], v[54:57]
	v_mfma_i32_16x16x64_i8 v[50:53], v[158:161], v[194:197], v[50:53]
	v_mfma_i32_16x16x64_i8 v[42:45], v[148:151], v[202:205], v[42:45]
	v_mfma_i32_16x16x64_i8 v[34:37], v[158:161], v[202:205], v[34:37]
	v_mfma_i32_16x16x64_i8 v[26:29], v[148:151], v[210:213], v[26:29]
	v_mfma_i32_16x16x64_i8 v[18:21], v[158:161], v[210:213], v[18:21]
	v_mfma_i32_16x16x64_i8 v[62:65], v[152:155], v[190:193], v[62:65]
	v_mfma_i32_16x16x64_i8 v[58:61], v[162:165], v[190:193], v[58:61]
	v_mfma_i32_16x16x64_i8 v[54:57], v[152:155], v[198:201], v[54:57]
	v_mfma_i32_16x16x64_i8 v[50:53], v[162:165], v[198:201], v[50:53]
	v_mfma_i32_16x16x64_i8 v[42:45], v[152:155], v[206:209], v[42:45]
	v_mfma_i32_16x16x64_i8 v[34:37], v[162:165], v[206:209], v[34:37]
	v_mfma_i32_16x16x64_i8 v[26:29], v[152:155], v[214:217], v[26:29]
	v_mfma_i32_16x16x64_i8 v[18:21], v[162:165], v[214:217], v[18:21]
	v_mfma_i32_16x16x64_i8 v[46:49], v[170:173], v[186:189], v[46:49]
	v_mfma_i32_16x16x64_i8 v[38:41], v[178:181], v[186:189], v[38:41]
	v_mfma_i32_16x16x64_i8 v[30:33], v[170:173], v[194:197], v[30:33]
	v_mfma_i32_16x16x64_i8 v[22:25], v[178:181], v[194:197], v[22:25]
	v_mfma_i32_16x16x64_i8 v[14:17], v[170:173], v[202:205], v[14:17]
	v_mfma_i32_16x16x64_i8 v[10:13], v[178:181], v[202:205], v[10:13]
	v_mfma_i32_16x16x64_i8 v[6:9], v[170:173], v[210:213], v[6:9]
	v_mfma_i32_16x16x64_i8 v[2:5], v[178:181], v[210:213], v[2:5]
	v_mfma_i32_16x16x64_i8 v[46:49], v[174:177], v[190:193], v[46:49]
	v_mfma_i32_16x16x64_i8 v[38:41], v[182:185], v[190:193], v[38:41]
	v_mfma_i32_16x16x64_i8 v[30:33], v[174:177], v[198:201], v[30:33]
	v_mfma_i32_16x16x64_i8 v[22:25], v[182:185], v[198:201], v[22:25]
	v_mfma_i32_16x16x64_i8 v[14:17], v[174:177], v[206:209], v[14:17]
	v_mfma_i32_16x16x64_i8 v[10:13], v[182:185], v[206:209], v[10:13]
	v_mfma_i32_16x16x64_i8 v[6:9], v[174:177], v[214:217], v[6:9]
	v_mfma_i32_16x16x64_i8 v[2:5], v[182:185], v[214:217], v[2:5]
	s_barrier
	s_setprio 0
	s_add_u32 s26, s26, 0x100
	s_addc_u32 s27, s27, 0
	s_add_u32 s61, s61, 0x100
	s_addc_u32 s62, s62, 0
	s_cmp_ge_i32 s63, s48
	s_mov_b32 s28, s63
	s_cbranch_scc0 .LBB0_800
	v_cvt_f32_i32_e32 v172, v126
	v_cvt_f32_i32_e32 v173, v127
	v_cvt_f32_i32_e32 v166, v128
	v_cvt_f32_i32_e32 v167, v129
	v_cvt_f32_i32_e32 v174, v122
	v_cvt_f32_i32_e32 v175, v123
	v_cvt_f32_i32_e32 v176, v124
	v_cvt_f32_i32_e32 v177, v125
	v_cvt_f32_i32_e32 v158, v110
	v_cvt_f32_i32_e32 v159, v111
	v_cvt_f32_i32_e32 v160, v112
	v_cvt_f32_i32_e32 v161, v113
	v_cvt_f32_i32_e32 v162, v102
	v_cvt_f32_i32_e32 v163, v103
	v_cvt_f32_i32_e32 v164, v104
	v_cvt_f32_i32_e32 v165, v105
	v_cvt_f32_i32_e32 v148, v118
	v_cvt_f32_i32_e32 v149, v119
	v_cvt_f32_i32_e32 v150, v120
	v_cvt_f32_i32_e32 v151, v121
	v_cvt_f32_i32_e32 v152, v114
	v_cvt_f32_i32_e32 v153, v115
	v_cvt_f32_i32_e32 v154, v116
	v_cvt_f32_i32_e32 v155, v117
	v_cvt_f32_i32_e32 v112, v94
	v_cvt_f32_i32_e32 v113, v95
	v_cvt_f32_i32_e32 v116, v96
	v_cvt_f32_i32_e32 v117, v97
	v_cvt_f32_i32_e32 v110, v86
	v_cvt_f32_i32_e32 v111, v87
	v_cvt_f32_i32_e32 v114, v88
	v_cvt_f32_i32_e32 v115, v89
	v_cvt_f32_i32_e32 v96, v106
	v_cvt_f32_i32_e32 v97, v107
	v_cvt_f32_i32_e32 v102, v108
	v_cvt_f32_i32_e32 v103, v109
	v_cvt_f32_i32_e32 v94, v98
	v_cvt_f32_i32_e32 v95, v99
	v_cvt_f32_i32_e32 v98, v100
	v_cvt_f32_i32_e32 v99, v101
	v_cvt_f32_i32_e32 v104, v78
	v_cvt_f32_i32_e32 v105, v79
	v_cvt_f32_i32_e32 v108, v80
	v_cvt_f32_i32_e32 v109, v81
	v_cvt_f32_i32_e32 v100, v74
	v_cvt_f32_i32_e32 v101, v75
	v_cvt_f32_i32_e32 v106, v76
	v_cvt_f32_i32_e32 v107, v77
	v_cvt_f32_i32_e32 v76, v90
	v_cvt_f32_i32_e32 v77, v91
	v_cvt_f32_i32_e32 v80, v92
	v_cvt_f32_i32_e32 v81, v93
	v_cvt_f32_i32_e32 v74, v82
	v_cvt_f32_i32_e32 v75, v83
	v_cvt_f32_i32_e32 v78, v84
	v_cvt_f32_i32_e32 v79, v85
	v_cvt_f32_i32_e32 v84, v70
	v_cvt_f32_i32_e32 v85, v71
	v_cvt_f32_i32_e32 v92, v72
	v_cvt_f32_i32_e32 v93, v73
	v_cvt_f32_i32_e32 v82, v66
	v_cvt_f32_i32_e32 v83, v67
	v_cvt_f32_i32_e32 v90, v68
	v_cvt_f32_i32_e32 v91, v69
	v_cvt_f32_i32_e32 v66, v62
	v_cvt_f32_i32_e32 v67, v63
	v_cvt_f32_i32_e32 v68, v64
	v_cvt_f32_i32_e32 v69, v65
	v_cvt_f32_i32_e32 v62, v58
	v_cvt_f32_i32_e32 v63, v59
	v_cvt_f32_i32_e32 v64, v60
	v_cvt_f32_i32_e32 v65, v61
	v_cvt_f32_i32_e32 v72, v46
	v_cvt_f32_i32_e32 v73, v47
	v_cvt_f32_i32_e32 v88, v48
	v_cvt_f32_i32_e32 v89, v49
	v_cvt_f32_i32_e32 v70, v38
	v_cvt_f32_i32_e32 v71, v39
	v_cvt_f32_i32_e32 v86, v40
	v_cvt_f32_i32_e32 v87, v41
	v_cvt_f32_i32_e32 v48, v54
	v_cvt_f32_i32_e32 v49, v55
	v_cvt_f32_i32_e32 v54, v56
	v_cvt_f32_i32_e32 v55, v57
	v_cvt_f32_i32_e32 v46, v50
	v_cvt_f32_i32_e32 v47, v51
	v_cvt_f32_i32_e32 v50, v52
	v_cvt_f32_i32_e32 v51, v53
	v_cvt_f32_i32_e32 v56, v30
	v_cvt_f32_i32_e32 v57, v31
	v_cvt_f32_i32_e32 v60, v32
	v_cvt_f32_i32_e32 v61, v33
	v_cvt_f32_i32_e32 v52, v22
	v_cvt_f32_i32_e32 v53, v23
	v_cvt_f32_i32_e32 v58, v24
	v_cvt_f32_i32_e32 v59, v25
	v_cvt_f32_i32_e32 v24, v42
	v_cvt_f32_i32_e32 v25, v43
	v_cvt_f32_i32_e32 v32, v44
	v_cvt_f32_i32_e32 v33, v45
	v_cvt_f32_i32_e32 v22, v34
	v_cvt_f32_i32_e32 v23, v35
	v_cvt_f32_i32_e32 v30, v36
	v_cvt_f32_i32_e32 v31, v37
	v_cvt_f32_i32_e32 v36, v14
	v_cvt_f32_i32_e32 v37, v15
	v_cvt_f32_i32_e32 v40, v16
	v_cvt_f32_i32_e32 v41, v17
	v_cvt_f32_i32_e32 v34, v10
	v_cvt_f32_i32_e32 v35, v11
	v_cvt_f32_i32_e32 v38, v12
	v_cvt_f32_i32_e32 v39, v13
	v_cvt_f32_i32_e32 v12, v26
	v_cvt_f32_i32_e32 v13, v27
	v_cvt_f32_i32_e32 v16, v28
	v_cvt_f32_i32_e32 v17, v29
	v_cvt_f32_i32_e32 v10, v18
	v_cvt_f32_i32_e32 v11, v19
	v_cvt_f32_i32_e32 v14, v20
	v_cvt_f32_i32_e32 v15, v21
	v_cvt_f32_i32_e32 v18, v6
	v_cvt_f32_i32_e32 v19, v7
	v_cvt_f32_i32_e32 v20, v8
	v_cvt_f32_i32_e32 v21, v9
	v_cvt_f32_i32_e32 v6, v2
	v_cvt_f32_i32_e32 v7, v3
	v_cvt_f32_i32_e32 v8, v4
	v_cvt_f32_i32_e32 v9, v5

.LBB0_1297:
	v_add_u32_e32 v138, s77, v1
	ds_read_b128 v[148:151], v138
	ds_read_b128 v[152:155], v138 offset:1024
	ds_read_b128 v[156:159], v138 offset:2048
	ds_read_b128 v[160:163], v138 offset:3072
	v_add_u32_e32 v138, s78, v1
	ds_read_b128 v[164:167], v138
	ds_read_b128 v[170:173], v138 offset:1024
	ds_read_b128 v[174:177], v138 offset:2048
	ds_read_b128 v[178:181], v138 offset:3072
	s_add_i32 s46, s6, 2
	s_add_u32 s47, s4, 0x80
	s_addc_u32 s7, s5, 0
	s_cmp_eq_u32 s55, s6
	s_cselect_b32 s6, s40, s47
	s_cselect_b32 s7, s41, s7
	s_cselect_b32 s51, s43, s45
	s_cselect_b32 s50, s42, s44
	v_lshl_add_u64 v[198:199], s[4:5], 0, v[140:141]
	s_add_i32 m0, s70, 0xc000
	ds_read_b128 v[182:185], v169
	ds_read_b128 v[186:189], v169 offset:1024
	ds_read_b128 v[190:193], v169 offset:2048
	ds_read_b128 v[194:197], v169 offset:3072
	ds_read_b128 v[202:205], v169 offset:4096
	ds_read_b128 v[206:209], v169 offset:5120
	ds_read_b128 v[210:213], v169 offset:6144
	ds_read_b128 v[214:217], v169 offset:7168
	global_load_lds_dwordx4 v[198:199], off
	v_lshl_add_u64 v[198:199], s[4:5], 0, v[142:143]
	s_add_i32 m0, s70, 0xe000
	s_nop 0
	global_load_lds_dwordx4 v[198:199], off
	s_waitcnt vmcnt(8)
	s_waitcnt lgkmcnt(0)
	s_barrier
	s_setprio 1
	v_mfma_i32_16x16x64_i8 v[126:129], v[148:151], v[182:185], v[126:129]
	v_mfma_i32_16x16x64_i8 v[122:125], v[156:159], v[182:185], v[122:125]
	v_mfma_i32_16x16x64_i8 v[118:121], v[148:151], v[190:193], v[118:121]
	v_mfma_i32_16x16x64_i8 v[114:117], v[156:159], v[190:193], v[114:117]
	v_mfma_i32_16x16x64_i8 v[106:109], v[148:151], v[202:205], v[106:109]
	v_mfma_i32_16x16x64_i8 v[98:101], v[156:159], v[202:205], v[98:101]
	v_mfma_i32_16x16x64_i8 v[90:93], v[148:151], v[210:213], v[90:93]
	v_mfma_i32_16x16x64_i8 v[82:85], v[156:159], v[210:213], v[82:85]
	v_mfma_i32_16x16x64_i8 v[126:129], v[152:155], v[186:189], v[126:129]
	v_mfma_i32_16x16x64_i8 v[122:125], v[160:163], v[186:189], v[122:125]
	v_mfma_i32_16x16x64_i8 v[118:121], v[152:155], v[194:197], v[118:121]
	v_mfma_i32_16x16x64_i8 v[114:117], v[160:163], v[194:197], v[114:117]
	v_mfma_i32_16x16x64_i8 v[106:109], v[152:155], v[206:209], v[106:109]
	v_mfma_i32_16x16x64_i8 v[98:101], v[160:163], v[206:209], v[98:101]
	v_mfma_i32_16x16x64_i8 v[90:93], v[152:155], v[214:217], v[90:93]
	v_mfma_i32_16x16x64_i8 v[82:85], v[160:163], v[214:217], v[82:85]
	v_mfma_i32_16x16x64_i8 v[110:113], v[164:167], v[182:185], v[110:113]
	v_mfma_i32_16x16x64_i8 v[102:105], v[174:177], v[182:185], v[102:105]
	v_mfma_i32_16x16x64_i8 v[94:97], v[164:167], v[190:193], v[94:97]
	v_mfma_i32_16x16x64_i8 v[86:89], v[174:177], v[190:193], v[86:89]
	v_mfma_i32_16x16x64_i8 v[78:81], v[164:167], v[202:205], v[78:81]
	v_mfma_i32_16x16x64_i8 v[74:77], v[174:177], v[202:205], v[74:77]
	v_mfma_i32_16x16x64_i8 v[70:73], v[164:167], v[210:213], v[70:73]
	v_mfma_i32_16x16x64_i8 v[66:69], v[174:177], v[210:213], v[66:69]
	v_mfma_i32_16x16x64_i8 v[110:113], v[170:173], v[186:189], v[110:113]
	v_mfma_i32_16x16x64_i8 v[102:105], v[178:181], v[186:189], v[102:105]
	v_mfma_i32_16x16x64_i8 v[94:97], v[170:173], v[194:197], v[94:97]
	v_mfma_i32_16x16x64_i8 v[86:89], v[178:181], v[194:197], v[86:89]
	v_mfma_i32_16x16x64_i8 v[78:81], v[170:173], v[206:209], v[78:81]
	v_mfma_i32_16x16x64_i8 v[74:77], v[178:181], v[206:209], v[74:77]
	v_mfma_i32_16x16x64_i8 v[70:73], v[170:173], v[214:217], v[70:73]
	v_mfma_i32_16x16x64_i8 v[66:69], v[178:181], v[214:217], v[66:69]
	s_barrier
	s_setprio 0
	s_add_i32 s47, s77, s69
	v_lshl_add_u64 v[198:199], s[50:51], 0, v[132:133]
	s_mov_b32 m0, s47
	ds_read_b128 v[182:185], v169 offset:16384
	ds_read_b128 v[186:189], v169 offset:17408
	ds_read_b128 v[190:193], v169 offset:18432
	ds_read_b128 v[194:197], v169 offset:19456
	ds_read_b128 v[202:205], v169 offset:20480
	ds_read_b128 v[206:209], v169 offset:21504
	ds_read_b128 v[210:213], v169 offset:22528
	ds_read_b128 v[214:217], v169 offset:23552
	global_load_lds_dwordx4 v[198:199], off
	s_add_i32 m0, s47, 0x2000
	v_lshl_add_u64 v[218:219], s[50:51], 0, v[136:137]
	s_add_u32 s50, s50, s22
	s_addc_u32 s51, s51, s23
	s_add_i32 s47, s78, s69
	global_load_lds_dwordx4 v[218:219], off
	v_lshl_add_u64 v[220:221], s[50:51], 0, v[132:133]
	s_mov_b32 m0, s47
	v_lshl_add_u64 v[222:223], s[50:51], 0, v[136:137]
	global_load_lds_dwordx4 v[220:221], off
	s_add_i32 m0, s47, 0x2000
	v_lshl_add_u64 v[224:225], s[6:7], 0, v[130:131]
	global_load_lds_dwordx4 v[222:223], off
	s_mov_b32 m0, s70
	v_lshl_add_u64 v[226:227], s[6:7], 0, v[134:135]
	global_load_lds_dwordx4 v[224:225], off
	s_mov_b32 m0, s71
	s_nop 0
	global_load_lds_dwordx4 v[226:227], off
	s_waitcnt vmcnt(8)
	s_waitcnt lgkmcnt(0)
	s_barrier
	s_setprio 1
	v_mfma_i32_16x16x64_i8 v[62:65], v[148:151], v[182:185], v[62:65]
	v_mfma_i32_16x16x64_i8 v[58:61], v[156:159], v[182:185], v[58:61]
	v_mfma_i32_16x16x64_i8 v[54:57], v[148:151], v[190:193], v[54:57]
	v_mfma_i32_16x16x64_i8 v[50:53], v[156:159], v[190:193], v[50:53]
	v_mfma_i32_16x16x64_i8 v[42:45], v[148:151], v[202:205], v[42:45]
	v_mfma_i32_16x16x64_i8 v[34:37], v[156:159], v[202:205], v[34:37]
	v_mfma_i32_16x16x64_i8 v[26:29], v[148:151], v[210:213], v[26:29]
	v_mfma_i32_16x16x64_i8 v[18:21], v[156:159], v[210:213], v[18:21]
	v_mfma_i32_16x16x64_i8 v[62:65], v[152:155], v[186:189], v[62:65]
	v_mfma_i32_16x16x64_i8 v[58:61], v[160:163], v[186:189], v[58:61]
	v_mfma_i32_16x16x64_i8 v[54:57], v[152:155], v[194:197], v[54:57]
	v_mfma_i32_16x16x64_i8 v[50:53], v[160:163], v[194:197], v[50:53]
	v_mfma_i32_16x16x64_i8 v[42:45], v[152:155], v[206:209], v[42:45]
	v_mfma_i32_16x16x64_i8 v[34:37], v[160:163], v[206:209], v[34:37]
	v_mfma_i32_16x16x64_i8 v[26:29], v[152:155], v[214:217], v[26:29]
	v_mfma_i32_16x16x64_i8 v[18:21], v[160:163], v[214:217], v[18:21]
	v_mfma_i32_16x16x64_i8 v[46:49], v[164:167], v[182:185], v[46:49]
	v_mfma_i32_16x16x64_i8 v[38:41], v[174:177], v[182:185], v[38:41]
	v_mfma_i32_16x16x64_i8 v[30:33], v[164:167], v[190:193], v[30:33]
	v_mfma_i32_16x16x64_i8 v[22:25], v[174:177], v[190:193], v[22:25]
	v_mfma_i32_16x16x64_i8 v[14:17], v[164:167], v[202:205], v[14:17]
	v_mfma_i32_16x16x64_i8 v[10:13], v[174:177], v[202:205], v[10:13]
	v_mfma_i32_16x16x64_i8 v[6:9], v[164:167], v[210:213], v[6:9]
	v_mfma_i32_16x16x64_i8 v[2:5], v[174:177], v[210:213], v[2:5]
	v_mfma_i32_16x16x64_i8 v[46:49], v[170:173], v[186:189], v[46:49]
	v_mfma_i32_16x16x64_i8 v[38:41], v[178:181], v[186:189], v[38:41]
	v_mfma_i32_16x16x64_i8 v[30:33], v[170:173], v[194:197], v[30:33]
	v_mfma_i32_16x16x64_i8 v[22:25], v[178:181], v[194:197], v[22:25]
	v_mfma_i32_16x16x64_i8 v[14:17], v[170:173], v[206:209], v[14:17]
	v_mfma_i32_16x16x64_i8 v[10:13], v[178:181], v[206:209], v[10:13]
	v_mfma_i32_16x16x64_i8 v[6:9], v[170:173], v[214:217], v[6:9]
	v_mfma_i32_16x16x64_i8 v[2:5], v[178:181], v[214:217], v[2:5]
	s_barrier
	s_setprio 0
	s_add_i32 s47, 0, 0x18000
	v_add_u32_e32 v138, s47, v1
	s_add_i32 s49, 0, 0x1c000
	ds_read_b128 v[148:151], v138
	ds_read_b128 v[152:155], v138 offset:1024
	ds_read_b128 v[156:159], v138 offset:2048
	ds_read_b128 v[160:163], v138 offset:3072
	v_add_u32_e32 v138, s49, v1
	ds_read_b128 v[164:167], v138
	ds_read_b128 v[170:173], v138 offset:1024
	ds_read_b128 v[174:177], v138 offset:2048
	ds_read_b128 v[178:181], v138 offset:3072
	s_add_u32 s6, s6, s22
	s_addc_u32 s7, s7, s23
	s_mov_b32 m0, s72
	v_lshl_add_u64 v[228:229], s[6:7], 0, v[130:131]
	ds_read_b128 v[182:185], v169 offset:32768
	ds_read_b128 v[186:189], v169 offset:33792
	ds_read_b128 v[190:193], v169 offset:34816
	ds_read_b128 v[194:197], v169 offset:35840
	ds_read_b128 v[202:205], v169 offset:36864
	ds_read_b128 v[206:209], v169 offset:37888
	ds_read_b128 v[210:213], v169 offset:38912
	ds_read_b128 v[214:217], v169 offset:39936
	global_load_lds_dwordx4 v[228:229], off
	v_lshl_add_u64 v[228:229], s[6:7], 0, v[134:135]
	s_mov_b32 m0, s73
	s_nop 0
	global_load_lds_dwordx4 v[228:229], off
	s_waitcnt vmcnt(8)
	s_waitcnt lgkmcnt(0)
	s_barrier
	s_setprio 1
	v_mfma_i32_16x16x64_i8 v[126:129], v[148:151], v[182:185], v[126:129]
	v_mfma_i32_16x16x64_i8 v[122:125], v[156:159], v[182:185], v[122:125]
	v_mfma_i32_16x16x64_i8 v[118:121], v[148:151], v[190:193], v[118:121]
	v_mfma_i32_16x16x64_i8 v[114:117], v[156:159], v[190:193], v[114:117]
	v_mfma_i32_16x16x64_i8 v[106:109], v[148:151], v[202:205], v[106:109]
	v_mfma_i32_16x16x64_i8 v[98:101], v[156:159], v[202:205], v[98:101]
	v_mfma_i32_16x16x64_i8 v[90:93], v[148:151], v[210:213], v[90:93]
	v_mfma_i32_16x16x64_i8 v[82:85], v[156:159], v[210:213], v[82:85]
	v_mfma_i32_16x16x64_i8 v[126:129], v[152:155], v[186:189], v[126:129]
	v_mfma_i32_16x16x64_i8 v[122:125], v[160:163], v[186:189], v[122:125]
	v_mfma_i32_16x16x64_i8 v[118:121], v[152:155], v[194:197], v[118:121]
	v_mfma_i32_16x16x64_i8 v[114:117], v[160:163], v[194:197], v[114:117]
	v_mfma_i32_16x16x64_i8 v[106:109], v[152:155], v[206:209], v[106:109]
	v_mfma_i32_16x16x64_i8 v[98:101], v[160:163], v[206:209], v[98:101]
	v_mfma_i32_16x16x64_i8 v[90:93], v[152:155], v[214:217], v[90:93]
	v_mfma_i32_16x16x64_i8 v[82:85], v[160:163], v[214:217], v[82:85]
	v_mfma_i32_16x16x64_i8 v[110:113], v[164:167], v[182:185], v[110:113]
	v_mfma_i32_16x16x64_i8 v[102:105], v[174:177], v[182:185], v[102:105]
	v_mfma_i32_16x16x64_i8 v[94:97], v[164:167], v[190:193], v[94:97]
	v_mfma_i32_16x16x64_i8 v[86:89], v[174:177], v[190:193], v[86:89]
	v_mfma_i32_16x16x64_i8 v[78:81], v[164:167], v[202:205], v[78:81]
	v_mfma_i32_16x16x64_i8 v[74:77], v[174:177], v[202:205], v[74:77]
	v_mfma_i32_16x16x64_i8 v[70:73], v[164:167], v[210:213], v[70:73]
	v_mfma_i32_16x16x64_i8 v[66:69], v[174:177], v[210:213], v[66:69]
	v_mfma_i32_16x16x64_i8 v[110:113], v[170:173], v[186:189], v[110:113]
	v_mfma_i32_16x16x64_i8 v[102:105], v[178:181], v[186:189], v[102:105]
	v_mfma_i32_16x16x64_i8 v[94:97], v[170:173], v[194:197], v[94:97]
	v_mfma_i32_16x16x64_i8 v[86:89], v[178:181], v[194:197], v[86:89]
	v_mfma_i32_16x16x64_i8 v[78:81], v[170:173], v[206:209], v[78:81]
	v_mfma_i32_16x16x64_i8 v[74:77], v[178:181], v[206:209], v[74:77]
	v_mfma_i32_16x16x64_i8 v[70:73], v[170:173], v[214:217], v[70:73]
	v_mfma_i32_16x16x64_i8 v[66:69], v[178:181], v[214:217], v[66:69]
	s_barrier
	s_setprio 0
	s_add_i32 s6, s47, s69
	v_lshl_add_u64 v[198:199], v[198:199], 0, s[34:35]
	s_mov_b32 m0, s6
	ds_read_b128 v[182:185], v169 offset:49152
	ds_read_b128 v[186:189], v169 offset:50176
	ds_read_b128 v[190:193], v169 offset:51200
	ds_read_b128 v[194:197], v169 offset:52224
	ds_read_b128 v[202:205], v169 offset:53248
	ds_read_b128 v[206:209], v169 offset:54272
	ds_read_b128 v[210:213], v169 offset:55296
	ds_read_b128 v[214:217], v169 offset:56320
	global_load_lds_dwordx4 v[198:199], off
	v_lshl_add_u64 v[198:199], v[218:219], 0, s[34:35]
	s_add_i32 m0, s6, 0x2000
	s_add_i32 s6, s49, s69
	global_load_lds_dwordx4 v[198:199], off
	v_lshl_add_u64 v[198:199], v[220:221], 0, s[34:35]
	s_mov_b32 m0, s6
	s_nop 0
	global_load_lds_dwordx4 v[198:199], off
	v_lshl_add_u64 v[198:199], v[222:223], 0, s[34:35]
	s_add_i32 m0, s6, 0x2000
	s_nop 0
	global_load_lds_dwordx4 v[198:199], off
	v_lshl_add_u64 v[198:199], v[224:225], 0, s[34:35]
	s_mov_b32 m0, s74
	s_nop 0
	global_load_lds_dwordx4 v[198:199], off
	v_lshl_add_u64 v[198:199], v[226:227], 0, s[34:35]
	s_mov_b32 m0, s75
	s_nop 0
	global_load_lds_dwordx4 v[198:199], off
	s_waitcnt vmcnt(8)
	s_waitcnt lgkmcnt(0)
	s_barrier
	s_setprio 1
	v_mfma_i32_16x16x64_i8 v[62:65], v[148:151], v[182:185], v[62:65]
	v_mfma_i32_16x16x64_i8 v[58:61], v[156:159], v[182:185], v[58:61]
	v_mfma_i32_16x16x64_i8 v[54:57], v[148:151], v[190:193], v[54:57]
	v_mfma_i32_16x16x64_i8 v[50:53], v[156:159], v[190:193], v[50:53]
	v_mfma_i32_16x16x64_i8 v[42:45], v[148:151], v[202:205], v[42:45]
	v_mfma_i32_16x16x64_i8 v[34:37], v[156:159], v[202:205], v[34:37]
	v_mfma_i32_16x16x64_i8 v[26:29], v[148:151], v[210:213], v[26:29]
	v_mfma_i32_16x16x64_i8 v[18:21], v[156:159], v[210:213], v[18:21]
	v_mfma_i32_16x16x64_i8 v[62:65], v[152:155], v[186:189], v[62:65]
	v_mfma_i32_16x16x64_i8 v[58:61], v[160:163], v[186:189], v[58:61]
	v_mfma_i32_16x16x64_i8 v[54:57], v[152:155], v[194:197], v[54:57]
	v_mfma_i32_16x16x64_i8 v[50:53], v[160:163], v[194:197], v[50:53]
	v_mfma_i32_16x16x64_i8 v[42:45], v[152:155], v[206:209], v[42:45]
	v_mfma_i32_16x16x64_i8 v[34:37], v[160:163], v[206:209], v[34:37]
	v_mfma_i32_16x16x64_i8 v[26:29], v[152:155], v[214:217], v[26:29]
	v_mfma_i32_16x16x64_i8 v[18:21], v[160:163], v[214:217], v[18:21]
	v_mfma_i32_16x16x64_i8 v[46:49], v[164:167], v[182:185], v[46:49]
	v_mfma_i32_16x16x64_i8 v[38:41], v[174:177], v[182:185], v[38:41]
	v_mfma_i32_16x16x64_i8 v[30:33], v[164:167], v[190:193], v[30:33]
	v_mfma_i32_16x16x64_i8 v[22:25], v[174:177], v[190:193], v[22:25]
	v_mfma_i32_16x16x64_i8 v[14:17], v[164:167], v[202:205], v[14:17]
	v_mfma_i32_16x16x64_i8 v[10:13], v[174:177], v[202:205], v[10:13]
	v_mfma_i32_16x16x64_i8 v[6:9], v[164:167], v[210:213], v[6:9]
	v_mfma_i32_16x16x64_i8 v[2:5], v[174:177], v[210:213], v[2:5]
	v_mfma_i32_16x16x64_i8 v[46:49], v[170:173], v[186:189], v[46:49]
	v_mfma_i32_16x16x64_i8 v[38:41], v[178:181], v[186:189], v[38:41]
	v_mfma_i32_16x16x64_i8 v[30:33], v[170:173], v[194:197], v[30:33]
	v_mfma_i32_16x16x64_i8 v[22:25], v[178:181], v[194:197], v[22:25]
	v_mfma_i32_16x16x64_i8 v[14:17], v[170:173], v[206:209], v[14:17]
	v_mfma_i32_16x16x64_i8 v[10:13], v[178:181], v[206:209], v[10:13]
	v_mfma_i32_16x16x64_i8 v[6:9], v[170:173], v[214:217], v[6:9]
	v_mfma_i32_16x16x64_i8 v[2:5], v[178:181], v[214:217], v[2:5]
	s_barrier
	s_setprio 0
	s_add_u32 s4, s4, 0x100
	s_addc_u32 s5, s5, 0
	s_add_u32 s44, s44, 0x100
	s_addc_u32 s45, s45, 0
	s_cmp_ge_i32 s46, s52
	s_mov_b32 s6, s46
	s_cbranch_scc0 .LBB0_1297
	v_cvt_f32_i32_e32 v182, v126
	v_cvt_f32_i32_e32 v183, v127
	v_cvt_f32_i32_e32 v180, v128
	v_cvt_f32_i32_e32 v181, v129
	v_cvt_f32_i32_e32 v184, v122
	v_cvt_f32_i32_e32 v185, v123
	v_cvt_f32_i32_e32 v186, v124
	v_cvt_f32_i32_e32 v187, v125
	v_cvt_f32_i32_e32 v170, v110
	v_cvt_f32_i32_e32 v171, v111
	v_cvt_f32_i32_e32 v174, v112
	v_cvt_f32_i32_e32 v175, v113
	v_cvt_f32_i32_e32 v172, v102
	v_cvt_f32_i32_e32 v173, v103
	v_cvt_f32_i32_e32 v166, v104
	v_cvt_f32_i32_e32 v167, v105
	v_cvt_f32_i32_e32 v162, v118
	v_cvt_f32_i32_e32 v163, v119
	v_cvt_f32_i32_e32 v164, v120
	v_cvt_f32_i32_e32 v165, v121
	v_cvt_f32_i32_e32 v158, v114
	v_cvt_f32_i32_e32 v159, v115
	v_cvt_f32_i32_e32 v160, v116
	v_cvt_f32_i32_e32 v161, v117
	v_cvt_f32_i32_e32 v152, v94
	v_cvt_f32_i32_e32 v153, v95
	v_cvt_f32_i32_e32 v154, v96
	v_cvt_f32_i32_e32 v155, v97
	v_cvt_f32_i32_e32 v128, v86
	v_cvt_f32_i32_e32 v129, v87
	v_cvt_f32_i32_e32 v148, v88
	v_cvt_f32_i32_e32 v149, v89
	v_cvt_f32_i32_e32 v124, v106
	v_cvt_f32_i32_e32 v125, v107
	v_cvt_f32_i32_e32 v126, v108
	v_cvt_f32_i32_e32 v127, v109
	v_cvt_f32_i32_e32 v120, v98
	v_cvt_f32_i32_e32 v121, v99
	v_cvt_f32_i32_e32 v122, v100
	v_cvt_f32_i32_e32 v123, v101
	v_cvt_f32_i32_e32 v114, v78
	v_cvt_f32_i32_e32 v115, v79
	v_cvt_f32_i32_e32 v116, v80
	v_cvt_f32_i32_e32 v117, v81
	v_cvt_f32_i32_e32 v110, v74
	v_cvt_f32_i32_e32 v111, v75
	v_cvt_f32_i32_e32 v112, v76
	v_cvt_f32_i32_e32 v113, v77
	v_cvt_f32_i32_e32 v104, v90
	v_cvt_f32_i32_e32 v105, v91
	v_cvt_f32_i32_e32 v106, v92
	v_cvt_f32_i32_e32 v107, v93
	v_cvt_f32_i32_e32 v100, v82
	v_cvt_f32_i32_e32 v101, v83
	v_cvt_f32_i32_e32 v102, v84
	v_cvt_f32_i32_e32 v103, v85
	v_cvt_f32_i32_e32 v96, v70
	v_cvt_f32_i32_e32 v97, v71
	v_cvt_f32_i32_e32 v98, v72
	v_cvt_f32_i32_e32 v99, v73
	v_cvt_f32_i32_e32 v92, v66
	v_cvt_f32_i32_e32 v93, v67
	v_cvt_f32_i32_e32 v94, v68
	v_cvt_f32_i32_e32 v95, v69
	v_cvt_f32_i32_e32 v86, v62
	v_cvt_f32_i32_e32 v87, v63
	v_cvt_f32_i32_e32 v88, v64
	v_cvt_f32_i32_e32 v89, v65
	v_cvt_f32_i32_e32 v82, v58
	v_cvt_f32_i32_e32 v83, v59
	v_cvt_f32_i32_e32 v84, v60
	v_cvt_f32_i32_e32 v85, v61
	v_cvt_f32_i32_e32 v78, v46
	v_cvt_f32_i32_e32 v79, v47
	v_cvt_f32_i32_e32 v80, v48
	v_cvt_f32_i32_e32 v81, v49
	v_cvt_f32_i32_e32 v74, v38
	v_cvt_f32_i32_e32 v75, v39
	v_cvt_f32_i32_e32 v76, v40
	v_cvt_f32_i32_e32 v77, v41
	v_cvt_f32_i32_e32 v68, v54
	v_cvt_f32_i32_e32 v69, v55
	v_cvt_f32_i32_e32 v70, v56
	v_cvt_f32_i32_e32 v71, v57
	v_cvt_f32_i32_e32 v64, v50
	v_cvt_f32_i32_e32 v65, v51
	v_cvt_f32_i32_e32 v66, v52
	v_cvt_f32_i32_e32 v67, v53
	v_cvt_f32_i32_e32 v60, v30
	v_cvt_f32_i32_e32 v61, v31
	v_cvt_f32_i32_e32 v62, v32
	v_cvt_f32_i32_e32 v63, v33
	v_cvt_f32_i32_e32 v56, v22
	v_cvt_f32_i32_e32 v57, v23
	v_cvt_f32_i32_e32 v58, v24
	v_cvt_f32_i32_e32 v59, v25
	v_cvt_f32_i32_e32 v50, v42
	v_cvt_f32_i32_e32 v51, v43
	v_cvt_f32_i32_e32 v52, v44
	v_cvt_f32_i32_e32 v53, v45
	v_cvt_f32_i32_e32 v46, v34
	v_cvt_f32_i32_e32 v47, v35
	v_cvt_f32_i32_e32 v48, v36
	v_cvt_f32_i32_e32 v49, v37
	v_cvt_f32_i32_e32 v34, v14
	v_cvt_f32_i32_e32 v35, v15
	v_cvt_f32_i32_e32 v36, v16
	v_cvt_f32_i32_e32 v37, v17
	v_cvt_f32_i32_e32 v30, v10
	v_cvt_f32_i32_e32 v31, v11
	v_cvt_f32_i32_e32 v32, v12
	v_cvt_f32_i32_e32 v33, v13
	v_cvt_f32_i32_e32 v22, v26
	v_cvt_f32_i32_e32 v23, v27
	v_cvt_f32_i32_e32 v24, v28
	v_cvt_f32_i32_e32 v25, v29
	v_cvt_f32_i32_e32 v18, v18
	v_cvt_f32_i32_e32 v19, v19
	v_cvt_f32_i32_e32 v20, v20
	v_cvt_f32_i32_e32 v21, v21
	v_cvt_f32_i32_e32 v14, v6
	v_cvt_f32_i32_e32 v15, v7
	v_cvt_f32_i32_e32 v16, v8
	v_cvt_f32_i32_e32 v17, v9
	v_cvt_f32_i32_e32 v10, v2
	v_cvt_f32_i32_e32 v11, v3
	v_cvt_f32_i32_e32 v12, v4
	v_cvt_f32_i32_e32 v13, v5

.LBB0_1513:
	v_add_u32_e32 v138, s55, v1
	ds_read_b128 v[148:151], v138
	ds_read_b128 v[152:155], v138 offset:1024
	ds_read_b128 v[156:159], v138 offset:2048
	ds_read_b128 v[160:163], v138 offset:3072
	v_add_u32_e32 v138, s76, v1
	ds_read_b128 v[164:167], v138
	ds_read_b128 v[170:173], v138 offset:1024
	ds_read_b128 v[174:177], v138 offset:2048
	ds_read_b128 v[178:181], v138 offset:3072
	s_add_i32 s46, s6, 2
	s_add_u32 s47, s4, 0x80
	s_addc_u32 s7, s5, 0
	s_cmp_eq_u32 s53, s6
	s_cselect_b32 s6, s40, s47
	s_cselect_b32 s7, s41, s7
	s_cselect_b32 s51, s43, s45
	s_cselect_b32 s50, s42, s44
	v_lshl_add_u64 v[198:199], s[4:5], 0, v[140:141]
	s_add_i32 m0, s68, 0xc000
	ds_read_b128 v[182:185], v169
	ds_read_b128 v[186:189], v169 offset:1024
	ds_read_b128 v[190:193], v169 offset:2048
	ds_read_b128 v[194:197], v169 offset:3072
	ds_read_b128 v[202:205], v169 offset:4096
	ds_read_b128 v[206:209], v169 offset:5120
	ds_read_b128 v[210:213], v169 offset:6144
	ds_read_b128 v[214:217], v169 offset:7168
	global_load_lds_dwordx4 v[198:199], off
	v_lshl_add_u64 v[198:199], s[4:5], 0, v[142:143]
	s_add_i32 m0, s68, 0xe000
	s_nop 0
	global_load_lds_dwordx4 v[198:199], off
	s_waitcnt vmcnt(8)
	s_waitcnt lgkmcnt(0)
	s_barrier
	s_setprio 1
	v_mfma_i32_16x16x64_i8 v[126:129], v[148:151], v[182:185], v[126:129]
	v_mfma_i32_16x16x64_i8 v[122:125], v[156:159], v[182:185], v[122:125]
	v_mfma_i32_16x16x64_i8 v[118:121], v[148:151], v[190:193], v[118:121]
	v_mfma_i32_16x16x64_i8 v[114:117], v[156:159], v[190:193], v[114:117]
	v_mfma_i32_16x16x64_i8 v[106:109], v[148:151], v[202:205], v[106:109]
	v_mfma_i32_16x16x64_i8 v[98:101], v[156:159], v[202:205], v[98:101]
	v_mfma_i32_16x16x64_i8 v[90:93], v[148:151], v[210:213], v[90:93]
	v_mfma_i32_16x16x64_i8 v[82:85], v[156:159], v[210:213], v[82:85]
	v_mfma_i32_16x16x64_i8 v[126:129], v[152:155], v[186:189], v[126:129]
	v_mfma_i32_16x16x64_i8 v[122:125], v[160:163], v[186:189], v[122:125]
	v_mfma_i32_16x16x64_i8 v[118:121], v[152:155], v[194:197], v[118:121]
	v_mfma_i32_16x16x64_i8 v[114:117], v[160:163], v[194:197], v[114:117]
	v_mfma_i32_16x16x64_i8 v[106:109], v[152:155], v[206:209], v[106:109]
	v_mfma_i32_16x16x64_i8 v[98:101], v[160:163], v[206:209], v[98:101]
	v_mfma_i32_16x16x64_i8 v[90:93], v[152:155], v[214:217], v[90:93]
	v_mfma_i32_16x16x64_i8 v[82:85], v[160:163], v[214:217], v[82:85]
	v_mfma_i32_16x16x64_i8 v[110:113], v[164:167], v[182:185], v[110:113]
	v_mfma_i32_16x16x64_i8 v[102:105], v[174:177], v[182:185], v[102:105]
	v_mfma_i32_16x16x64_i8 v[94:97], v[164:167], v[190:193], v[94:97]
	v_mfma_i32_16x16x64_i8 v[86:89], v[174:177], v[190:193], v[86:89]
	v_mfma_i32_16x16x64_i8 v[78:81], v[164:167], v[202:205], v[78:81]
	v_mfma_i32_16x16x64_i8 v[74:77], v[174:177], v[202:205], v[74:77]
	v_mfma_i32_16x16x64_i8 v[70:73], v[164:167], v[210:213], v[70:73]
	v_mfma_i32_16x16x64_i8 v[66:69], v[174:177], v[210:213], v[66:69]
	v_mfma_i32_16x16x64_i8 v[110:113], v[170:173], v[186:189], v[110:113]
	v_mfma_i32_16x16x64_i8 v[102:105], v[178:181], v[186:189], v[102:105]
	v_mfma_i32_16x16x64_i8 v[94:97], v[170:173], v[194:197], v[94:97]
	v_mfma_i32_16x16x64_i8 v[86:89], v[178:181], v[194:197], v[86:89]
	v_mfma_i32_16x16x64_i8 v[78:81], v[170:173], v[206:209], v[78:81]
	v_mfma_i32_16x16x64_i8 v[74:77], v[178:181], v[206:209], v[74:77]
	v_mfma_i32_16x16x64_i8 v[70:73], v[170:173], v[214:217], v[70:73]
	v_mfma_i32_16x16x64_i8 v[66:69], v[178:181], v[214:217], v[66:69]
	s_barrier
	s_setprio 0
	s_add_i32 s47, s55, s67
	v_lshl_add_u64 v[198:199], s[50:51], 0, v[132:133]
	s_mov_b32 m0, s47
	ds_read_b128 v[182:185], v169 offset:16384
	ds_read_b128 v[186:189], v169 offset:17408
	ds_read_b128 v[190:193], v169 offset:18432
	ds_read_b128 v[194:197], v169 offset:19456
	ds_read_b128 v[202:205], v169 offset:20480
	ds_read_b128 v[206:209], v169 offset:21504
	ds_read_b128 v[210:213], v169 offset:22528
	ds_read_b128 v[214:217], v169 offset:23552
	global_load_lds_dwordx4 v[198:199], off
	s_add_i32 m0, s47, 0x2000
	v_lshl_add_u64 v[218:219], s[50:51], 0, v[136:137]
	s_add_u32 s50, s50, s22
	s_addc_u32 s51, s51, s23
	s_add_i32 s47, s76, s67
	global_load_lds_dwordx4 v[218:219], off
	v_lshl_add_u64 v[220:221], s[50:51], 0, v[132:133]
	s_mov_b32 m0, s47
	v_lshl_add_u64 v[222:223], s[50:51], 0, v[136:137]
	global_load_lds_dwordx4 v[220:221], off
	s_add_i32 m0, s47, 0x2000
	v_lshl_add_u64 v[224:225], s[6:7], 0, v[130:131]
	global_load_lds_dwordx4 v[222:223], off
	s_mov_b32 m0, s68
	v_lshl_add_u64 v[226:227], s[6:7], 0, v[134:135]
	global_load_lds_dwordx4 v[224:225], off
	s_mov_b32 m0, s69
	s_nop 0
	global_load_lds_dwordx4 v[226:227], off
	s_waitcnt vmcnt(8)
	s_waitcnt lgkmcnt(0)
	s_barrier
	s_setprio 1
	v_mfma_i32_16x16x64_i8 v[62:65], v[148:151], v[182:185], v[62:65]
	v_mfma_i32_16x16x64_i8 v[58:61], v[156:159], v[182:185], v[58:61]
	v_mfma_i32_16x16x64_i8 v[54:57], v[148:151], v[190:193], v[54:57]
	v_mfma_i32_16x16x64_i8 v[50:53], v[156:159], v[190:193], v[50:53]
	v_mfma_i32_16x16x64_i8 v[42:45], v[148:151], v[202:205], v[42:45]
	v_mfma_i32_16x16x64_i8 v[34:37], v[156:159], v[202:205], v[34:37]
	v_mfma_i32_16x16x64_i8 v[26:29], v[148:151], v[210:213], v[26:29]
	v_mfma_i32_16x16x64_i8 v[18:21], v[156:159], v[210:213], v[18:21]
	v_mfma_i32_16x16x64_i8 v[62:65], v[152:155], v[186:189], v[62:65]
	v_mfma_i32_16x16x64_i8 v[58:61], v[160:163], v[186:189], v[58:61]
	v_mfma_i32_16x16x64_i8 v[54:57], v[152:155], v[194:197], v[54:57]
	v_mfma_i32_16x16x64_i8 v[50:53], v[160:163], v[194:197], v[50:53]
	v_mfma_i32_16x16x64_i8 v[42:45], v[152:155], v[206:209], v[42:45]
	v_mfma_i32_16x16x64_i8 v[34:37], v[160:163], v[206:209], v[34:37]
	v_mfma_i32_16x16x64_i8 v[26:29], v[152:155], v[214:217], v[26:29]
	v_mfma_i32_16x16x64_i8 v[18:21], v[160:163], v[214:217], v[18:21]
	v_mfma_i32_16x16x64_i8 v[46:49], v[164:167], v[182:185], v[46:49]
	v_mfma_i32_16x16x64_i8 v[38:41], v[174:177], v[182:185], v[38:41]
	v_mfma_i32_16x16x64_i8 v[30:33], v[164:167], v[190:193], v[30:33]
	v_mfma_i32_16x16x64_i8 v[22:25], v[174:177], v[190:193], v[22:25]
	v_mfma_i32_16x16x64_i8 v[14:17], v[164:167], v[202:205], v[14:17]
	v_mfma_i32_16x16x64_i8 v[10:13], v[174:177], v[202:205], v[10:13]
	v_mfma_i32_16x16x64_i8 v[6:9], v[164:167], v[210:213], v[6:9]
	v_mfma_i32_16x16x64_i8 v[2:5], v[174:177], v[210:213], v[2:5]
	v_mfma_i32_16x16x64_i8 v[46:49], v[170:173], v[186:189], v[46:49]
	v_mfma_i32_16x16x64_i8 v[38:41], v[178:181], v[186:189], v[38:41]
	v_mfma_i32_16x16x64_i8 v[30:33], v[170:173], v[194:197], v[30:33]
	v_mfma_i32_16x16x64_i8 v[22:25], v[178:181], v[194:197], v[22:25]
	v_mfma_i32_16x16x64_i8 v[14:17], v[170:173], v[206:209], v[14:17]
	v_mfma_i32_16x16x64_i8 v[10:13], v[178:181], v[206:209], v[10:13]
	v_mfma_i32_16x16x64_i8 v[6:9], v[170:173], v[214:217], v[6:9]
	v_mfma_i32_16x16x64_i8 v[2:5], v[178:181], v[214:217], v[2:5]
	s_barrier
	s_setprio 0
	s_add_i32 s47, 0, 0x18000
	v_add_u32_e32 v138, s47, v1
	s_add_i32 s49, 0, 0x1c000
	ds_read_b128 v[148:151], v138
	ds_read_b128 v[152:155], v138 offset:1024
	ds_read_b128 v[156:159], v138 offset:2048
	ds_read_b128 v[160:163], v138 offset:3072
	v_add_u32_e32 v138, s49, v1
	ds_read_b128 v[164:167], v138
	ds_read_b128 v[170:173], v138 offset:1024
	ds_read_b128 v[174:177], v138 offset:2048
	ds_read_b128 v[178:181], v138 offset:3072
	s_add_u32 s6, s6, s22
	s_addc_u32 s7, s7, s23
	s_mov_b32 m0, s70
	v_lshl_add_u64 v[228:229], s[6:7], 0, v[130:131]
	ds_read_b128 v[182:185], v169 offset:32768
	ds_read_b128 v[186:189], v169 offset:33792
	ds_read_b128 v[190:193], v169 offset:34816
	ds_read_b128 v[194:197], v169 offset:35840
	ds_read_b128 v[202:205], v169 offset:36864
	ds_read_b128 v[206:209], v169 offset:37888
	ds_read_b128 v[210:213], v169 offset:38912
	ds_read_b128 v[214:217], v169 offset:39936
	global_load_lds_dwordx4 v[228:229], off
	v_lshl_add_u64 v[228:229], s[6:7], 0, v[134:135]
	s_mov_b32 m0, s71
	s_nop 0
	global_load_lds_dwordx4 v[228:229], off
	s_waitcnt vmcnt(8)
	s_waitcnt lgkmcnt(0)
	s_barrier
	s_setprio 1
	v_mfma_i32_16x16x64_i8 v[126:129], v[148:151], v[182:185], v[126:129]
	v_mfma_i32_16x16x64_i8 v[122:125], v[156:159], v[182:185], v[122:125]
	v_mfma_i32_16x16x64_i8 v[118:121], v[148:151], v[190:193], v[118:121]
	v_mfma_i32_16x16x64_i8 v[114:117], v[156:159], v[190:193], v[114:117]
	v_mfma_i32_16x16x64_i8 v[106:109], v[148:151], v[202:205], v[106:109]
	v_mfma_i32_16x16x64_i8 v[98:101], v[156:159], v[202:205], v[98:101]
	v_mfma_i32_16x16x64_i8 v[90:93], v[148:151], v[210:213], v[90:93]
	v_mfma_i32_16x16x64_i8 v[82:85], v[156:159], v[210:213], v[82:85]
	v_mfma_i32_16x16x64_i8 v[126:129], v[152:155], v[186:189], v[126:129]
	v_mfma_i32_16x16x64_i8 v[122:125], v[160:163], v[186:189], v[122:125]
	v_mfma_i32_16x16x64_i8 v[118:121], v[152:155], v[194:197], v[118:121]
	v_mfma_i32_16x16x64_i8 v[114:117], v[160:163], v[194:197], v[114:117]
	v_mfma_i32_16x16x64_i8 v[106:109], v[152:155], v[206:209], v[106:109]
	v_mfma_i32_16x16x64_i8 v[98:101], v[160:163], v[206:209], v[98:101]
	v_mfma_i32_16x16x64_i8 v[90:93], v[152:155], v[214:217], v[90:93]
	v_mfma_i32_16x16x64_i8 v[82:85], v[160:163], v[214:217], v[82:85]
	v_mfma_i32_16x16x64_i8 v[110:113], v[164:167], v[182:185], v[110:113]
	v_mfma_i32_16x16x64_i8 v[102:105], v[174:177], v[182:185], v[102:105]
	v_mfma_i32_16x16x64_i8 v[94:97], v[164:167], v[190:193], v[94:97]
	v_mfma_i32_16x16x64_i8 v[86:89], v[174:177], v[190:193], v[86:89]
	v_mfma_i32_16x16x64_i8 v[78:81], v[164:167], v[202:205], v[78:81]
	v_mfma_i32_16x16x64_i8 v[74:77], v[174:177], v[202:205], v[74:77]
	v_mfma_i32_16x16x64_i8 v[70:73], v[164:167], v[210:213], v[70:73]
	v_mfma_i32_16x16x64_i8 v[66:69], v[174:177], v[210:213], v[66:69]
	v_mfma_i32_16x16x64_i8 v[110:113], v[170:173], v[186:189], v[110:113]
	v_mfma_i32_16x16x64_i8 v[102:105], v[178:181], v[186:189], v[102:105]
	v_mfma_i32_16x16x64_i8 v[94:97], v[170:173], v[194:197], v[94:97]
	v_mfma_i32_16x16x64_i8 v[86:89], v[178:181], v[194:197], v[86:89]
	v_mfma_i32_16x16x64_i8 v[78:81], v[170:173], v[206:209], v[78:81]
	v_mfma_i32_16x16x64_i8 v[74:77], v[178:181], v[206:209], v[74:77]
	v_mfma_i32_16x16x64_i8 v[70:73], v[170:173], v[214:217], v[70:73]
	v_mfma_i32_16x16x64_i8 v[66:69], v[178:181], v[214:217], v[66:69]
	s_barrier
	s_setprio 0
	s_add_i32 s6, s47, s67
	v_lshl_add_u64 v[198:199], v[198:199], 0, s[34:35]
	s_mov_b32 m0, s6
	ds_read_b128 v[182:185], v169 offset:49152
	ds_read_b128 v[186:189], v169 offset:50176
	ds_read_b128 v[190:193], v169 offset:51200
	ds_read_b128 v[194:197], v169 offset:52224
	ds_read_b128 v[202:205], v169 offset:53248
	ds_read_b128 v[206:209], v169 offset:54272
	ds_read_b128 v[210:213], v169 offset:55296
	ds_read_b128 v[214:217], v169 offset:56320
	global_load_lds_dwordx4 v[198:199], off
	v_lshl_add_u64 v[198:199], v[218:219], 0, s[34:35]
	s_add_i32 m0, s6, 0x2000
	s_add_i32 s6, s49, s67
	global_load_lds_dwordx4 v[198:199], off
	v_lshl_add_u64 v[198:199], v[220:221], 0, s[34:35]
	s_mov_b32 m0, s6
	s_nop 0
	global_load_lds_dwordx4 v[198:199], off
	v_lshl_add_u64 v[198:199], v[222:223], 0, s[34:35]
	s_add_i32 m0, s6, 0x2000
	s_nop 0
	global_load_lds_dwordx4 v[198:199], off
	v_lshl_add_u64 v[198:199], v[224:225], 0, s[34:35]
	s_mov_b32 m0, s72
	s_nop 0
	global_load_lds_dwordx4 v[198:199], off
	v_lshl_add_u64 v[198:199], v[226:227], 0, s[34:35]
	s_mov_b32 m0, s73
	s_nop 0
	global_load_lds_dwordx4 v[198:199], off
	s_waitcnt vmcnt(8)
	s_waitcnt lgkmcnt(0)
	s_barrier
	s_setprio 1
	v_mfma_i32_16x16x64_i8 v[62:65], v[148:151], v[182:185], v[62:65]
	v_mfma_i32_16x16x64_i8 v[58:61], v[156:159], v[182:185], v[58:61]
	v_mfma_i32_16x16x64_i8 v[54:57], v[148:151], v[190:193], v[54:57]
	v_mfma_i32_16x16x64_i8 v[50:53], v[156:159], v[190:193], v[50:53]
	v_mfma_i32_16x16x64_i8 v[42:45], v[148:151], v[202:205], v[42:45]
	v_mfma_i32_16x16x64_i8 v[34:37], v[156:159], v[202:205], v[34:37]
	v_mfma_i32_16x16x64_i8 v[26:29], v[148:151], v[210:213], v[26:29]
	v_mfma_i32_16x16x64_i8 v[18:21], v[156:159], v[210:213], v[18:21]
	v_mfma_i32_16x16x64_i8 v[62:65], v[152:155], v[186:189], v[62:65]
	v_mfma_i32_16x16x64_i8 v[58:61], v[160:163], v[186:189], v[58:61]
	v_mfma_i32_16x16x64_i8 v[54:57], v[152:155], v[194:197], v[54:57]
	v_mfma_i32_16x16x64_i8 v[50:53], v[160:163], v[194:197], v[50:53]
	v_mfma_i32_16x16x64_i8 v[42:45], v[152:155], v[206:209], v[42:45]
	v_mfma_i32_16x16x64_i8 v[34:37], v[160:163], v[206:209], v[34:37]
	v_mfma_i32_16x16x64_i8 v[26:29], v[152:155], v[214:217], v[26:29]
	v_mfma_i32_16x16x64_i8 v[18:21], v[160:163], v[214:217], v[18:21]
	v_mfma_i32_16x16x64_i8 v[46:49], v[164:167], v[182:185], v[46:49]
	v_mfma_i32_16x16x64_i8 v[38:41], v[174:177], v[182:185], v[38:41]
	v_mfma_i32_16x16x64_i8 v[30:33], v[164:167], v[190:193], v[30:33]
	v_mfma_i32_16x16x64_i8 v[22:25], v[174:177], v[190:193], v[22:25]
	v_mfma_i32_16x16x64_i8 v[14:17], v[164:167], v[202:205], v[14:17]
	v_mfma_i32_16x16x64_i8 v[10:13], v[174:177], v[202:205], v[10:13]
	v_mfma_i32_16x16x64_i8 v[6:9], v[164:167], v[210:213], v[6:9]
	v_mfma_i32_16x16x64_i8 v[2:5], v[174:177], v[210:213], v[2:5]
	v_mfma_i32_16x16x64_i8 v[46:49], v[170:173], v[186:189], v[46:49]
	v_mfma_i32_16x16x64_i8 v[38:41], v[178:181], v[186:189], v[38:41]
	v_mfma_i32_16x16x64_i8 v[30:33], v[170:173], v[194:197], v[30:33]
	v_mfma_i32_16x16x64_i8 v[22:25], v[178:181], v[194:197], v[22:25]
	v_mfma_i32_16x16x64_i8 v[14:17], v[170:173], v[206:209], v[14:17]
	v_mfma_i32_16x16x64_i8 v[10:13], v[178:181], v[206:209], v[10:13]
	v_mfma_i32_16x16x64_i8 v[6:9], v[170:173], v[214:217], v[6:9]
	v_mfma_i32_16x16x64_i8 v[2:5], v[178:181], v[214:217], v[2:5]
	s_barrier
	s_setprio 0
	s_add_u32 s4, s4, 0x100
	s_addc_u32 s5, s5, 0
	s_add_u32 s44, s44, 0x100
	s_addc_u32 s45, s45, 0
	s_cmp_lt_i32 s46, s74
	s_mov_b32 s6, s46
	s_cbranch_scc1 .LBB0_1513
	v_cvt_f32_i32_e32 v182, v126
	v_cvt_f32_i32_e32 v183, v127
	v_cvt_f32_i32_e32 v180, v128
	v_cvt_f32_i32_e32 v181, v129
	v_cvt_f32_i32_e32 v184, v122
	v_cvt_f32_i32_e32 v185, v123
	v_cvt_f32_i32_e32 v186, v124
	v_cvt_f32_i32_e32 v187, v125
	v_cvt_f32_i32_e32 v170, v110
	v_cvt_f32_i32_e32 v171, v111
	v_cvt_f32_i32_e32 v174, v112
	v_cvt_f32_i32_e32 v175, v113
	v_cvt_f32_i32_e32 v172, v102
	v_cvt_f32_i32_e32 v173, v103
	v_cvt_f32_i32_e32 v166, v104
	v_cvt_f32_i32_e32 v167, v105
	v_cvt_f32_i32_e32 v162, v118
	v_cvt_f32_i32_e32 v163, v119
	v_cvt_f32_i32_e32 v164, v120
	v_cvt_f32_i32_e32 v165, v121
	v_cvt_f32_i32_e32 v158, v114
	v_cvt_f32_i32_e32 v159, v115
	v_cvt_f32_i32_e32 v160, v116
	v_cvt_f32_i32_e32 v161, v117
	v_cvt_f32_i32_e32 v150, v94
	v_cvt_f32_i32_e32 v151, v95
	v_cvt_f32_i32_e32 v154, v96
	v_cvt_f32_i32_e32 v155, v97
	v_cvt_f32_i32_e32 v128, v86
	v_cvt_f32_i32_e32 v129, v87
	v_cvt_f32_i32_e32 v148, v88
	v_cvt_f32_i32_e32 v149, v89
	v_cvt_f32_i32_e32 v124, v106
	v_cvt_f32_i32_e32 v125, v107
	v_cvt_f32_i32_e32 v126, v108
	v_cvt_f32_i32_e32 v127, v109
	v_cvt_f32_i32_e32 v120, v98
	v_cvt_f32_i32_e32 v121, v99
	v_cvt_f32_i32_e32 v122, v100
	v_cvt_f32_i32_e32 v123, v101
	v_cvt_f32_i32_e32 v114, v78
	v_cvt_f32_i32_e32 v115, v79
	v_cvt_f32_i32_e32 v116, v80
	v_cvt_f32_i32_e32 v117, v81
	v_cvt_f32_i32_e32 v110, v74
	v_cvt_f32_i32_e32 v111, v75
	v_cvt_f32_i32_e32 v112, v76
	v_cvt_f32_i32_e32 v113, v77
	v_cvt_f32_i32_e32 v104, v90
	v_cvt_f32_i32_e32 v105, v91
	v_cvt_f32_i32_e32 v106, v92
	v_cvt_f32_i32_e32 v107, v93
	v_cvt_f32_i32_e32 v100, v82
	v_cvt_f32_i32_e32 v101, v83
	v_cvt_f32_i32_e32 v102, v84
	v_cvt_f32_i32_e32 v103, v85
	v_cvt_f32_i32_e32 v96, v70
	v_cvt_f32_i32_e32 v97, v71
	v_cvt_f32_i32_e32 v98, v72
	v_cvt_f32_i32_e32 v99, v73
	v_cvt_f32_i32_e32 v92, v66
	v_cvt_f32_i32_e32 v93, v67
	v_cvt_f32_i32_e32 v94, v68
	v_cvt_f32_i32_e32 v95, v69
	v_cvt_f32_i32_e32 v86, v62
	v_cvt_f32_i32_e32 v87, v63
	v_cvt_f32_i32_e32 v88, v64
	v_cvt_f32_i32_e32 v89, v65
	v_cvt_f32_i32_e32 v82, v58
	v_cvt_f32_i32_e32 v83, v59
	v_cvt_f32_i32_e32 v84, v60
	v_cvt_f32_i32_e32 v85, v61
	v_cvt_f32_i32_e32 v78, v46
	v_cvt_f32_i32_e32 v79, v47
	v_cvt_f32_i32_e32 v80, v48
	v_cvt_f32_i32_e32 v81, v49
	v_cvt_f32_i32_e32 v74, v38
	v_cvt_f32_i32_e32 v75, v39
	v_cvt_f32_i32_e32 v76, v40
	v_cvt_f32_i32_e32 v77, v41
	v_cvt_f32_i32_e32 v68, v54
	v_cvt_f32_i32_e32 v69, v55
	v_cvt_f32_i32_e32 v70, v56
	v_cvt_f32_i32_e32 v71, v57
	v_cvt_f32_i32_e32 v64, v50
	v_cvt_f32_i32_e32 v65, v51
	v_cvt_f32_i32_e32 v66, v52
	v_cvt_f32_i32_e32 v67, v53
	v_cvt_f32_i32_e32 v60, v30
	v_cvt_f32_i32_e32 v61, v31
	v_cvt_f32_i32_e32 v62, v32
	v_cvt_f32_i32_e32 v63, v33
	v_cvt_f32_i32_e32 v56, v22
	v_cvt_f32_i32_e32 v57, v23
	v_cvt_f32_i32_e32 v58, v24
	v_cvt_f32_i32_e32 v59, v25
	v_cvt_f32_i32_e32 v50, v42
	v_cvt_f32_i32_e32 v51, v43
	v_cvt_f32_i32_e32 v52, v44
	v_cvt_f32_i32_e32 v53, v45
	v_cvt_f32_i32_e32 v46, v34
	v_cvt_f32_i32_e32 v47, v35
	v_cvt_f32_i32_e32 v48, v36
	v_cvt_f32_i32_e32 v49, v37
	v_cvt_f32_i32_e32 v34, v14
	v_cvt_f32_i32_e32 v35, v15
	v_cvt_f32_i32_e32 v36, v16
	v_cvt_f32_i32_e32 v37, v17
	v_cvt_f32_i32_e32 v30, v10
	v_cvt_f32_i32_e32 v31, v11
	v_cvt_f32_i32_e32 v32, v12
	v_cvt_f32_i32_e32 v33, v13
	v_cvt_f32_i32_e32 v22, v26
	v_cvt_f32_i32_e32 v23, v27
	v_cvt_f32_i32_e32 v24, v28
	v_cvt_f32_i32_e32 v25, v29
	v_cvt_f32_i32_e32 v18, v18
	v_cvt_f32_i32_e32 v19, v19
	v_cvt_f32_i32_e32 v20, v20
	v_cvt_f32_i32_e32 v21, v21
	v_cvt_f32_i32_e32 v14, v6
	v_cvt_f32_i32_e32 v15, v7
	v_cvt_f32_i32_e32 v16, v8
	v_cvt_f32_i32_e32 v17, v9
	v_cvt_f32_i32_e32 v10, v2
	v_cvt_f32_i32_e32 v11, v3
	v_cvt_f32_i32_e32 v12, v4
	v_cvt_f32_i32_e32 v13, v5

.LBB0_1727:
	v_add_u32_e32 v150, s52, v1
	ds_read_b128 v[146:149], v150
	ds_read_b128 v[154:157], v150 offset:1024
	ds_read_b128 v[158:161], v150 offset:2048
	ds_read_b128 v[162:165], v150 offset:3072
	v_add_u32_e32 v150, s53, v1
	ds_read_b128 v[170:173], v150
	ds_read_b128 v[174:177], v150 offset:1024
	ds_read_b128 v[178:181], v150 offset:2048
	ds_read_b128 v[182:185], v150 offset:3072
	s_add_i32 s77, s48, 2
	s_add_u32 s78, s46, 0x80
	s_addc_u32 s49, s47, 0
	s_cmp_eq_u32 s72, s48
	s_cselect_b32 s48, s4, s78
	s_cselect_b32 s49, s5, s49
	s_cselect_b32 s79, s45, s76
	s_cselect_b32 s78, s44, s75
	v_lshl_add_u64 v[150:151], s[46:47], 0, v[138:139]
	s_add_i32 m0, s58, 0xc000
	ds_read_b128 v[186:189], v153
	ds_read_b128 v[190:193], v153 offset:1024
	ds_read_b128 v[194:197], v153 offset:2048
	ds_read_b128 v[198:201], v153 offset:3072
	ds_read_b128 v[202:205], v153 offset:4096
	ds_read_b128 v[206:209], v153 offset:5120
	ds_read_b128 v[210:213], v153 offset:6144
	ds_read_b128 v[214:217], v153 offset:7168
	global_load_lds_dwordx4 v[150:151], off
	v_lshl_add_u64 v[150:151], s[46:47], 0, v[140:141]
	s_add_i32 m0, s58, 0xe000
	s_nop 0
	global_load_lds_dwordx4 v[150:151], off
	s_waitcnt vmcnt(8)
	s_waitcnt lgkmcnt(0)
	s_barrier
	s_setprio 1
	v_mfma_i32_16x16x64_i8 v[126:129], v[146:149], v[186:189], v[126:129]
	v_mfma_i32_16x16x64_i8 v[122:125], v[158:161], v[186:189], v[122:125]
	v_mfma_i32_16x16x64_i8 v[118:121], v[146:149], v[194:197], v[118:121]
	v_mfma_i32_16x16x64_i8 v[114:117], v[158:161], v[194:197], v[114:117]
	v_mfma_i32_16x16x64_i8 v[106:109], v[146:149], v[202:205], v[106:109]
	v_mfma_i32_16x16x64_i8 v[98:101], v[158:161], v[202:205], v[98:101]
	v_mfma_i32_16x16x64_i8 v[90:93], v[146:149], v[210:213], v[90:93]
	v_mfma_i32_16x16x64_i8 v[82:85], v[158:161], v[210:213], v[82:85]
	v_mfma_i32_16x16x64_i8 v[126:129], v[154:157], v[190:193], v[126:129]
	v_mfma_i32_16x16x64_i8 v[122:125], v[162:165], v[190:193], v[122:125]
	v_mfma_i32_16x16x64_i8 v[118:121], v[154:157], v[198:201], v[118:121]
	v_mfma_i32_16x16x64_i8 v[114:117], v[162:165], v[198:201], v[114:117]
	v_mfma_i32_16x16x64_i8 v[106:109], v[154:157], v[206:209], v[106:109]
	v_mfma_i32_16x16x64_i8 v[98:101], v[162:165], v[206:209], v[98:101]
	v_mfma_i32_16x16x64_i8 v[90:93], v[154:157], v[214:217], v[90:93]
	v_mfma_i32_16x16x64_i8 v[82:85], v[162:165], v[214:217], v[82:85]
	v_mfma_i32_16x16x64_i8 v[110:113], v[170:173], v[186:189], v[110:113]
	v_mfma_i32_16x16x64_i8 v[102:105], v[178:181], v[186:189], v[102:105]
	v_mfma_i32_16x16x64_i8 v[94:97], v[170:173], v[194:197], v[94:97]
	v_mfma_i32_16x16x64_i8 v[86:89], v[178:181], v[194:197], v[86:89]
	v_mfma_i32_16x16x64_i8 v[78:81], v[170:173], v[202:205], v[78:81]
	v_mfma_i32_16x16x64_i8 v[74:77], v[178:181], v[202:205], v[74:77]
	v_mfma_i32_16x16x64_i8 v[70:73], v[170:173], v[210:213], v[70:73]
	v_mfma_i32_16x16x64_i8 v[66:69], v[178:181], v[210:213], v[66:69]
	v_mfma_i32_16x16x64_i8 v[110:113], v[174:177], v[190:193], v[110:113]
	v_mfma_i32_16x16x64_i8 v[102:105], v[182:185], v[190:193], v[102:105]
	v_mfma_i32_16x16x64_i8 v[94:97], v[174:177], v[198:201], v[94:97]
	v_mfma_i32_16x16x64_i8 v[86:89], v[182:185], v[198:201], v[86:89]
	v_mfma_i32_16x16x64_i8 v[78:81], v[174:177], v[206:209], v[78:81]
	v_mfma_i32_16x16x64_i8 v[74:77], v[182:185], v[206:209], v[74:77]
	v_mfma_i32_16x16x64_i8 v[70:73], v[174:177], v[214:217], v[70:73]
	v_mfma_i32_16x16x64_i8 v[66:69], v[182:185], v[214:217], v[66:69]
	s_barrier
	s_setprio 0
	s_add_i32 s80, s52, s51
	v_lshl_add_u64 v[150:151], s[78:79], 0, v[134:135]
	s_mov_b32 m0, s80
	ds_read_b128 v[186:189], v153 offset:16384
	ds_read_b128 v[190:193], v153 offset:17408
	ds_read_b128 v[194:197], v153 offset:18432
	ds_read_b128 v[198:201], v153 offset:19456
	ds_read_b128 v[202:205], v153 offset:20480
	ds_read_b128 v[206:209], v153 offset:21504
	ds_read_b128 v[210:213], v153 offset:22528
	ds_read_b128 v[214:217], v153 offset:23552
	global_load_lds_dwordx4 v[150:151], off
	s_add_i32 m0, s80, 0x2000
	v_lshl_add_u64 v[166:167], s[78:79], 0, v[130:131]
	s_add_u32 s78, s78, s14
	s_addc_u32 s79, s79, s15
	s_add_i32 s80, s53, s51
	global_load_lds_dwordx4 v[166:167], off
	v_lshl_add_u64 v[218:219], s[78:79], 0, v[134:135]
	s_mov_b32 m0, s80
	v_lshl_add_u64 v[220:221], s[78:79], 0, v[130:131]
	global_load_lds_dwordx4 v[218:219], off
	s_add_i32 m0, s80, 0x2000
	v_lshl_add_u64 v[222:223], s[48:49], 0, v[136:137]
	global_load_lds_dwordx4 v[220:221], off
	s_mov_b32 m0, s58
	v_lshl_add_u64 v[224:225], s[48:49], 0, v[132:133]
	global_load_lds_dwordx4 v[222:223], off
	s_mov_b32 m0, s59
	s_nop 0
	global_load_lds_dwordx4 v[224:225], off
	s_waitcnt vmcnt(8)
	s_waitcnt lgkmcnt(0)
	s_barrier
	s_setprio 1
	v_mfma_i32_16x16x64_i8 v[62:65], v[146:149], v[186:189], v[62:65]
	v_mfma_i32_16x16x64_i8 v[58:61], v[158:161], v[186:189], v[58:61]
	v_mfma_i32_16x16x64_i8 v[54:57], v[146:149], v[194:197], v[54:57]
	v_mfma_i32_16x16x64_i8 v[50:53], v[158:161], v[194:197], v[50:53]
	v_mfma_i32_16x16x64_i8 v[42:45], v[146:149], v[202:205], v[42:45]
	v_mfma_i32_16x16x64_i8 v[34:37], v[158:161], v[202:205], v[34:37]
	v_mfma_i32_16x16x64_i8 v[26:29], v[146:149], v[210:213], v[26:29]
	v_mfma_i32_16x16x64_i8 v[18:21], v[158:161], v[210:213], v[18:21]
	v_mfma_i32_16x16x64_i8 v[62:65], v[154:157], v[190:193], v[62:65]
	v_mfma_i32_16x16x64_i8 v[58:61], v[162:165], v[190:193], v[58:61]
	v_mfma_i32_16x16x64_i8 v[54:57], v[154:157], v[198:201], v[54:57]
	v_mfma_i32_16x16x64_i8 v[50:53], v[162:165], v[198:201], v[50:53]
	v_mfma_i32_16x16x64_i8 v[42:45], v[154:157], v[206:209], v[42:45]
	v_mfma_i32_16x16x64_i8 v[34:37], v[162:165], v[206:209], v[34:37]
	v_mfma_i32_16x16x64_i8 v[26:29], v[154:157], v[214:217], v[26:29]
	v_mfma_i32_16x16x64_i8 v[18:21], v[162:165], v[214:217], v[18:21]
	v_mfma_i32_16x16x64_i8 v[46:49], v[170:173], v[186:189], v[46:49]
	v_mfma_i32_16x16x64_i8 v[38:41], v[178:181], v[186:189], v[38:41]
	v_mfma_i32_16x16x64_i8 v[30:33], v[170:173], v[194:197], v[30:33]
	v_mfma_i32_16x16x64_i8 v[22:25], v[178:181], v[194:197], v[22:25]
	v_mfma_i32_16x16x64_i8 v[14:17], v[170:173], v[202:205], v[14:17]
	v_mfma_i32_16x16x64_i8 v[10:13], v[178:181], v[202:205], v[10:13]
	v_mfma_i32_16x16x64_i8 v[6:9], v[170:173], v[210:213], v[6:9]
	v_mfma_i32_16x16x64_i8 v[2:5], v[178:181], v[210:213], v[2:5]
	v_mfma_i32_16x16x64_i8 v[46:49], v[174:177], v[190:193], v[46:49]
	v_mfma_i32_16x16x64_i8 v[38:41], v[182:185], v[190:193], v[38:41]
	v_mfma_i32_16x16x64_i8 v[30:33], v[174:177], v[198:201], v[30:33]
	v_mfma_i32_16x16x64_i8 v[22:25], v[182:185], v[198:201], v[22:25]
	v_mfma_i32_16x16x64_i8 v[14:17], v[174:177], v[206:209], v[14:17]
	v_mfma_i32_16x16x64_i8 v[10:13], v[182:185], v[206:209], v[10:13]
	v_mfma_i32_16x16x64_i8 v[6:9], v[174:177], v[214:217], v[6:9]
	v_mfma_i32_16x16x64_i8 v[2:5], v[182:185], v[214:217], v[2:5]
	s_barrier
	s_setprio 0
	s_add_i32 s78, 0, 0x18000
	v_add_u32_e32 v152, s78, v1
	s_add_i32 s79, 0, 0x1c000
	ds_read_b128 v[146:149], v152
	ds_read_b128 v[154:157], v152 offset:1024
	ds_read_b128 v[158:161], v152 offset:2048
	ds_read_b128 v[162:165], v152 offset:3072
	v_add_u32_e32 v152, s79, v1
	ds_read_b128 v[170:173], v152
	ds_read_b128 v[174:177], v152 offset:1024
	ds_read_b128 v[178:181], v152 offset:2048
	ds_read_b128 v[182:185], v152 offset:3072
	s_add_u32 s48, s48, s14
	s_addc_u32 s49, s49, s15
	s_mov_b32 m0, s62
	v_lshl_add_u64 v[226:227], s[48:49], 0, v[136:137]
	ds_read_b128 v[186:189], v153 offset:32768
	ds_read_b128 v[190:193], v153 offset:33792
	ds_read_b128 v[194:197], v153 offset:34816
	ds_read_b128 v[198:201], v153 offset:35840
	ds_read_b128 v[202:205], v153 offset:36864
	ds_read_b128 v[206:209], v153 offset:37888
	ds_read_b128 v[210:213], v153 offset:38912
	ds_read_b128 v[214:217], v153 offset:39936
	global_load_lds_dwordx4 v[226:227], off
	v_lshl_add_u64 v[226:227], s[48:49], 0, v[132:133]
	s_mov_b32 m0, s63
	s_nop 0
	global_load_lds_dwordx4 v[226:227], off
	s_waitcnt vmcnt(8)
	s_waitcnt lgkmcnt(0)
	s_barrier
	s_setprio 1
	v_mfma_i32_16x16x64_i8 v[126:129], v[146:149], v[186:189], v[126:129]
	v_mfma_i32_16x16x64_i8 v[122:125], v[158:161], v[186:189], v[122:125]
	v_mfma_i32_16x16x64_i8 v[118:121], v[146:149], v[194:197], v[118:121]
	v_mfma_i32_16x16x64_i8 v[114:117], v[158:161], v[194:197], v[114:117]
	v_mfma_i32_16x16x64_i8 v[106:109], v[146:149], v[202:205], v[106:109]
	v_mfma_i32_16x16x64_i8 v[98:101], v[158:161], v[202:205], v[98:101]
	v_mfma_i32_16x16x64_i8 v[90:93], v[146:149], v[210:213], v[90:93]
	v_mfma_i32_16x16x64_i8 v[82:85], v[158:161], v[210:213], v[82:85]
	v_mfma_i32_16x16x64_i8 v[126:129], v[154:157], v[190:193], v[126:129]
	v_mfma_i32_16x16x64_i8 v[122:125], v[162:165], v[190:193], v[122:125]
	v_mfma_i32_16x16x64_i8 v[118:121], v[154:157], v[198:201], v[118:121]
	v_mfma_i32_16x16x64_i8 v[114:117], v[162:165], v[198:201], v[114:117]
	v_mfma_i32_16x16x64_i8 v[106:109], v[154:157], v[206:209], v[106:109]
	v_mfma_i32_16x16x64_i8 v[98:101], v[162:165], v[206:209], v[98:101]
	v_mfma_i32_16x16x64_i8 v[90:93], v[154:157], v[214:217], v[90:93]
	v_mfma_i32_16x16x64_i8 v[82:85], v[162:165], v[214:217], v[82:85]
	v_mfma_i32_16x16x64_i8 v[110:113], v[170:173], v[186:189], v[110:113]
	v_mfma_i32_16x16x64_i8 v[102:105], v[178:181], v[186:189], v[102:105]
	v_mfma_i32_16x16x64_i8 v[94:97], v[170:173], v[194:197], v[94:97]
	v_mfma_i32_16x16x64_i8 v[86:89], v[178:181], v[194:197], v[86:89]
	v_mfma_i32_16x16x64_i8 v[78:81], v[170:173], v[202:205], v[78:81]
	v_mfma_i32_16x16x64_i8 v[74:77], v[178:181], v[202:205], v[74:77]
	v_mfma_i32_16x16x64_i8 v[70:73], v[170:173], v[210:213], v[70:73]
	v_mfma_i32_16x16x64_i8 v[66:69], v[178:181], v[210:213], v[66:69]
	v_mfma_i32_16x16x64_i8 v[110:113], v[174:177], v[190:193], v[110:113]
	v_mfma_i32_16x16x64_i8 v[102:105], v[182:185], v[190:193], v[102:105]
	v_mfma_i32_16x16x64_i8 v[94:97], v[174:177], v[198:201], v[94:97]
	v_mfma_i32_16x16x64_i8 v[86:89], v[182:185], v[198:201], v[86:89]
	v_mfma_i32_16x16x64_i8 v[78:81], v[174:177], v[206:209], v[78:81]
	v_mfma_i32_16x16x64_i8 v[74:77], v[182:185], v[206:209], v[74:77]
	v_mfma_i32_16x16x64_i8 v[70:73], v[174:177], v[214:217], v[70:73]
	v_mfma_i32_16x16x64_i8 v[66:69], v[182:185], v[214:217], v[66:69]
	s_barrier
	s_setprio 0
	s_add_i32 s48, s78, s51
	v_lshl_add_u64 v[150:151], v[150:151], 0, s[24:25]
	s_mov_b32 m0, s48
	ds_read_b128 v[186:189], v153 offset:49152
	ds_read_b128 v[190:193], v153 offset:50176
	ds_read_b128 v[194:197], v153 offset:51200
	ds_read_b128 v[198:201], v153 offset:52224
	ds_read_b128 v[202:205], v153 offset:53248
	ds_read_b128 v[206:209], v153 offset:54272
	ds_read_b128 v[210:213], v153 offset:55296
	ds_read_b128 v[214:217], v153 offset:56320
	global_load_lds_dwordx4 v[150:151], off
	v_lshl_add_u64 v[150:151], v[166:167], 0, s[24:25]
	s_add_i32 m0, s48, 0x2000
	s_add_i32 s48, s79, s51
	global_load_lds_dwordx4 v[150:151], off
	v_lshl_add_u64 v[150:151], v[218:219], 0, s[24:25]
	s_mov_b32 m0, s48
	s_nop 0
	global_load_lds_dwordx4 v[150:151], off
	v_lshl_add_u64 v[150:151], v[220:221], 0, s[24:25]
	s_add_i32 m0, s48, 0x2000
	s_nop 0
	global_load_lds_dwordx4 v[150:151], off
	v_lshl_add_u64 v[150:151], v[222:223], 0, s[24:25]
	s_mov_b32 m0, s67
	s_nop 0
	global_load_lds_dwordx4 v[150:151], off
	v_lshl_add_u64 v[150:151], v[224:225], 0, s[24:25]
	s_mov_b32 m0, s68
	s_nop 0
	global_load_lds_dwordx4 v[150:151], off
	s_waitcnt vmcnt(8)
	s_waitcnt lgkmcnt(0)
	s_barrier
	s_setprio 1
	v_mfma_i32_16x16x64_i8 v[62:65], v[146:149], v[186:189], v[62:65]
	v_mfma_i32_16x16x64_i8 v[58:61], v[158:161], v[186:189], v[58:61]
	v_mfma_i32_16x16x64_i8 v[54:57], v[146:149], v[194:197], v[54:57]
	v_mfma_i32_16x16x64_i8 v[50:53], v[158:161], v[194:197], v[50:53]
	v_mfma_i32_16x16x64_i8 v[42:45], v[146:149], v[202:205], v[42:45]
	v_mfma_i32_16x16x64_i8 v[34:37], v[158:161], v[202:205], v[34:37]
	v_mfma_i32_16x16x64_i8 v[26:29], v[146:149], v[210:213], v[26:29]
	v_mfma_i32_16x16x64_i8 v[18:21], v[158:161], v[210:213], v[18:21]
	v_mfma_i32_16x16x64_i8 v[62:65], v[154:157], v[190:193], v[62:65]
	v_mfma_i32_16x16x64_i8 v[58:61], v[162:165], v[190:193], v[58:61]
	v_mfma_i32_16x16x64_i8 v[54:57], v[154:157], v[198:201], v[54:57]
	v_mfma_i32_16x16x64_i8 v[50:53], v[162:165], v[198:201], v[50:53]
	v_mfma_i32_16x16x64_i8 v[42:45], v[154:157], v[206:209], v[42:45]
	v_mfma_i32_16x16x64_i8 v[34:37], v[162:165], v[206:209], v[34:37]
	v_mfma_i32_16x16x64_i8 v[26:29], v[154:157], v[214:217], v[26:29]
	v_mfma_i32_16x16x64_i8 v[18:21], v[162:165], v[214:217], v[18:21]
	v_mfma_i32_16x16x64_i8 v[46:49], v[170:173], v[186:189], v[46:49]
	v_mfma_i32_16x16x64_i8 v[38:41], v[178:181], v[186:189], v[38:41]
	v_mfma_i32_16x16x64_i8 v[30:33], v[170:173], v[194:197], v[30:33]
	v_mfma_i32_16x16x64_i8 v[22:25], v[178:181], v[194:197], v[22:25]
	v_mfma_i32_16x16x64_i8 v[14:17], v[170:173], v[202:205], v[14:17]
	v_mfma_i32_16x16x64_i8 v[10:13], v[178:181], v[202:205], v[10:13]
	v_mfma_i32_16x16x64_i8 v[6:9], v[170:173], v[210:213], v[6:9]
	v_mfma_i32_16x16x64_i8 v[2:5], v[178:181], v[210:213], v[2:5]
	v_mfma_i32_16x16x64_i8 v[46:49], v[174:177], v[190:193], v[46:49]
	v_mfma_i32_16x16x64_i8 v[38:41], v[182:185], v[190:193], v[38:41]
	v_mfma_i32_16x16x64_i8 v[30:33], v[174:177], v[198:201], v[30:33]
	v_mfma_i32_16x16x64_i8 v[22:25], v[182:185], v[198:201], v[22:25]
	v_mfma_i32_16x16x64_i8 v[14:17], v[174:177], v[206:209], v[14:17]
	v_mfma_i32_16x16x64_i8 v[10:13], v[182:185], v[206:209], v[10:13]
	v_mfma_i32_16x16x64_i8 v[6:9], v[174:177], v[214:217], v[6:9]
	v_mfma_i32_16x16x64_i8 v[2:5], v[182:185], v[214:217], v[2:5]
	s_barrier
	s_setprio 0
	s_add_u32 s46, s46, 0x100
	s_addc_u32 s47, s47, 0
	s_add_u32 s75, s75, 0x100
	s_addc_u32 s76, s76, 0
	s_cmp_ge_i32 s77, s69
	s_mov_b32 s48, s77
	s_cbranch_scc0 .LBB0_1727
	v_cvt_f32_i32_e32 v180, v126
	v_cvt_f32_i32_e32 v181, v127
	v_cvt_f32_i32_e32 v178, v128
	v_cvt_f32_i32_e32 v179, v129
	v_cvt_f32_i32_e32 v182, v122
	v_cvt_f32_i32_e32 v183, v123
	v_cvt_f32_i32_e32 v184, v124
	v_cvt_f32_i32_e32 v185, v125
	v_cvt_f32_i32_e32 v164, v110
	v_cvt_f32_i32_e32 v165, v111
	v_cvt_f32_i32_e32 v166, v112
	v_cvt_f32_i32_e32 v167, v113
	v_cvt_f32_i32_e32 v170, v102
	v_cvt_f32_i32_e32 v171, v103
	v_cvt_f32_i32_e32 v172, v104
	v_cvt_f32_i32_e32 v173, v105
	v_cvt_f32_i32_e32 v156, v118
	v_cvt_f32_i32_e32 v157, v119
	v_cvt_f32_i32_e32 v158, v120
	v_cvt_f32_i32_e32 v159, v121
	v_cvt_f32_i32_e32 v160, v114
	v_cvt_f32_i32_e32 v161, v115
	v_cvt_f32_i32_e32 v162, v116
	v_cvt_f32_i32_e32 v163, v117
	v_cvt_f32_i32_e32 v126, v94
	v_cvt_f32_i32_e32 v127, v95
	v_cvt_f32_i32_e32 v128, v96
	v_cvt_f32_i32_e32 v129, v97
	v_cvt_f32_i32_e32 v146, v86
	v_cvt_f32_i32_e32 v147, v87
	v_cvt_f32_i32_e32 v148, v88
	v_cvt_f32_i32_e32 v149, v89
	v_cvt_f32_i32_e32 v118, v106
	v_cvt_f32_i32_e32 v119, v107
	v_cvt_f32_i32_e32 v120, v108
	v_cvt_f32_i32_e32 v121, v109
	v_cvt_f32_i32_e32 v122, v98
	v_cvt_f32_i32_e32 v123, v99
	v_cvt_f32_i32_e32 v124, v100
	v_cvt_f32_i32_e32 v125, v101
	v_cvt_f32_i32_e32 v108, v78
	v_cvt_f32_i32_e32 v109, v79
	v_cvt_f32_i32_e32 v110, v80
	v_cvt_f32_i32_e32 v111, v81
	v_cvt_f32_i32_e32 v112, v74
	v_cvt_f32_i32_e32 v113, v75
	v_cvt_f32_i32_e32 v114, v76
	v_cvt_f32_i32_e32 v115, v77
	v_cvt_f32_i32_e32 v100, v90
	v_cvt_f32_i32_e32 v101, v91
	v_cvt_f32_i32_e32 v102, v92
	v_cvt_f32_i32_e32 v103, v93
	v_cvt_f32_i32_e32 v104, v82
	v_cvt_f32_i32_e32 v105, v83
	v_cvt_f32_i32_e32 v106, v84
	v_cvt_f32_i32_e32 v107, v85
	v_cvt_f32_i32_e32 v90, v70
	v_cvt_f32_i32_e32 v91, v71
	v_cvt_f32_i32_e32 v92, v72
	v_cvt_f32_i32_e32 v93, v73
	v_cvt_f32_i32_e32 v94, v66
	v_cvt_f32_i32_e32 v95, v67
	v_cvt_f32_i32_e32 v96, v68
	v_cvt_f32_i32_e32 v97, v69
	v_cvt_f32_i32_e32 v82, v62
	v_cvt_f32_i32_e32 v83, v63
	v_cvt_f32_i32_e32 v84, v64
	v_cvt_f32_i32_e32 v85, v65
	v_cvt_f32_i32_e32 v86, v58
	v_cvt_f32_i32_e32 v87, v59
	v_cvt_f32_i32_e32 v88, v60
	v_cvt_f32_i32_e32 v89, v61
	v_cvt_f32_i32_e32 v72, v46
	v_cvt_f32_i32_e32 v73, v47
	v_cvt_f32_i32_e32 v74, v48
	v_cvt_f32_i32_e32 v75, v49
	v_cvt_f32_i32_e32 v76, v38
	v_cvt_f32_i32_e32 v77, v39
	v_cvt_f32_i32_e32 v78, v40
	v_cvt_f32_i32_e32 v79, v41
	v_cvt_f32_i32_e32 v64, v54
	v_cvt_f32_i32_e32 v65, v55
	v_cvt_f32_i32_e32 v66, v56
	v_cvt_f32_i32_e32 v67, v57
	v_cvt_f32_i32_e32 v68, v50
	v_cvt_f32_i32_e32 v69, v51
	v_cvt_f32_i32_e32 v70, v52
	v_cvt_f32_i32_e32 v71, v53
	v_cvt_f32_i32_e32 v54, v30
	v_cvt_f32_i32_e32 v55, v31
	v_cvt_f32_i32_e32 v56, v32
	v_cvt_f32_i32_e32 v57, v33
	v_cvt_f32_i32_e32 v58, v22
	v_cvt_f32_i32_e32 v59, v23
	v_cvt_f32_i32_e32 v60, v24
	v_cvt_f32_i32_e32 v61, v25
	v_cvt_f32_i32_e32 v46, v42
	v_cvt_f32_i32_e32 v47, v43
	v_cvt_f32_i32_e32 v48, v44
	v_cvt_f32_i32_e32 v49, v45
	v_cvt_f32_i32_e32 v50, v34
	v_cvt_f32_i32_e32 v51, v35
	v_cvt_f32_i32_e32 v52, v36
	v_cvt_f32_i32_e32 v53, v37
	v_cvt_f32_i32_e32 v34, v14
	v_cvt_f32_i32_e32 v35, v15
	v_cvt_f32_i32_e32 v36, v16
	v_cvt_f32_i32_e32 v37, v17
	v_cvt_f32_i32_e32 v38, v10
	v_cvt_f32_i32_e32 v39, v11
	v_cvt_f32_i32_e32 v40, v12
	v_cvt_f32_i32_e32 v41, v13
	v_cvt_f32_i32_e32 v26, v26
	v_cvt_f32_i32_e32 v27, v27
	v_cvt_f32_i32_e32 v28, v28
	v_cvt_f32_i32_e32 v29, v29
	v_cvt_f32_i32_e32 v30, v18
	v_cvt_f32_i32_e32 v31, v19
	v_cvt_f32_i32_e32 v32, v20
	v_cvt_f32_i32_e32 v33, v21
	v_cvt_f32_i32_e32 v18, v6
	v_cvt_f32_i32_e32 v19, v7
	v_cvt_f32_i32_e32 v20, v8
	v_cvt_f32_i32_e32 v21, v9
	v_cvt_f32_i32_e32 v22, v2
	v_cvt_f32_i32_e32 v23, v3
	v_cvt_f32_i32_e32 v24, v4
	v_cvt_f32_i32_e32 v25, v5
	v_readlane_b32 s77, v237, 59

.LBB0_1751:
	v_add_u32_e32 v158, s58, v1
	ds_read_b128 v[146:149], v158
	ds_read_b128 v[150:153], v158 offset:1024
	ds_read_b128 v[154:157], v158 offset:2048
	ds_read_b128 v[162:165], v158 offset:3072
	v_add_u32_e32 v158, s59, v1
	ds_read_b128 v[170:173], v158
	ds_read_b128 v[174:177], v158 offset:1024
	ds_read_b128 v[178:181], v158 offset:2048
	ds_read_b128 v[182:185], v158 offset:3072
	s_add_i32 s68, s38, 2
	s_add_u32 s69, s36, 0x80
	s_addc_u32 s39, s37, 0
	s_cmp_eq_u32 s55, s38
	s_cselect_b32 s38, s2, s69
	s_cselect_b32 s39, s3, s39
	s_cselect_b32 s71, s35, s67
	s_cselect_b32 s70, s34, s66
	v_lshl_add_u64 v[158:159], s[36:37], 0, v[138:139]
	s_add_i32 m0, s43, 0xc000
	ds_read_b128 v[186:189], v161
	ds_read_b128 v[190:193], v161 offset:1024
	ds_read_b128 v[194:197], v161 offset:2048
	ds_read_b128 v[198:201], v161 offset:3072
	ds_read_b128 v[202:205], v161 offset:4096
	ds_read_b128 v[206:209], v161 offset:5120
	ds_read_b128 v[210:213], v161 offset:6144
	ds_read_b128 v[214:217], v161 offset:7168
	global_load_lds_dwordx4 v[158:159], off
	v_lshl_add_u64 v[158:159], s[36:37], 0, v[140:141]
	s_add_i32 m0, s43, 0xe000
	s_nop 0
	global_load_lds_dwordx4 v[158:159], off
	s_waitcnt vmcnt(8)
	s_waitcnt lgkmcnt(0)
	s_barrier
	s_setprio 1
	v_mfma_i32_16x16x64_i8 v[126:129], v[146:149], v[186:189], v[126:129]
	v_mfma_i32_16x16x64_i8 v[122:125], v[154:157], v[186:189], v[122:125]
	v_mfma_i32_16x16x64_i8 v[118:121], v[146:149], v[194:197], v[118:121]
	v_mfma_i32_16x16x64_i8 v[114:117], v[154:157], v[194:197], v[114:117]
	v_mfma_i32_16x16x64_i8 v[106:109], v[146:149], v[202:205], v[106:109]
	v_mfma_i32_16x16x64_i8 v[98:101], v[154:157], v[202:205], v[98:101]
	v_mfma_i32_16x16x64_i8 v[90:93], v[146:149], v[210:213], v[90:93]
	v_mfma_i32_16x16x64_i8 v[82:85], v[154:157], v[210:213], v[82:85]
	v_mfma_i32_16x16x64_i8 v[126:129], v[150:153], v[190:193], v[126:129]
	v_mfma_i32_16x16x64_i8 v[122:125], v[162:165], v[190:193], v[122:125]
	v_mfma_i32_16x16x64_i8 v[118:121], v[150:153], v[198:201], v[118:121]
	v_mfma_i32_16x16x64_i8 v[114:117], v[162:165], v[198:201], v[114:117]
	v_mfma_i32_16x16x64_i8 v[106:109], v[150:153], v[206:209], v[106:109]
	v_mfma_i32_16x16x64_i8 v[98:101], v[162:165], v[206:209], v[98:101]
	v_mfma_i32_16x16x64_i8 v[90:93], v[150:153], v[214:217], v[90:93]
	v_mfma_i32_16x16x64_i8 v[82:85], v[162:165], v[214:217], v[82:85]
	v_mfma_i32_16x16x64_i8 v[110:113], v[170:173], v[186:189], v[110:113]
	v_mfma_i32_16x16x64_i8 v[102:105], v[178:181], v[186:189], v[102:105]
	v_mfma_i32_16x16x64_i8 v[94:97], v[170:173], v[194:197], v[94:97]
	v_mfma_i32_16x16x64_i8 v[86:89], v[178:181], v[194:197], v[86:89]
	v_mfma_i32_16x16x64_i8 v[78:81], v[170:173], v[202:205], v[78:81]
	v_mfma_i32_16x16x64_i8 v[74:77], v[178:181], v[202:205], v[74:77]
	v_mfma_i32_16x16x64_i8 v[70:73], v[170:173], v[210:213], v[70:73]
	v_mfma_i32_16x16x64_i8 v[66:69], v[178:181], v[210:213], v[66:69]
	v_mfma_i32_16x16x64_i8 v[110:113], v[174:177], v[190:193], v[110:113]
	v_mfma_i32_16x16x64_i8 v[102:105], v[182:185], v[190:193], v[102:105]
	v_mfma_i32_16x16x64_i8 v[94:97], v[174:177], v[198:201], v[94:97]
	v_mfma_i32_16x16x64_i8 v[86:89], v[182:185], v[198:201], v[86:89]
	v_mfma_i32_16x16x64_i8 v[78:81], v[174:177], v[206:209], v[78:81]
	v_mfma_i32_16x16x64_i8 v[74:77], v[182:185], v[206:209], v[74:77]
	v_mfma_i32_16x16x64_i8 v[70:73], v[174:177], v[214:217], v[70:73]
	v_mfma_i32_16x16x64_i8 v[66:69], v[182:185], v[214:217], v[66:69]
	s_barrier
	s_setprio 0
	s_add_i32 s69, s58, s42
	v_lshl_add_u64 v[158:159], s[70:71], 0, v[132:133]
	s_mov_b32 m0, s69
	ds_read_b128 v[186:189], v161 offset:16384
	ds_read_b128 v[190:193], v161 offset:17408
	ds_read_b128 v[194:197], v161 offset:18432
	ds_read_b128 v[198:201], v161 offset:19456
	ds_read_b128 v[202:205], v161 offset:20480
	ds_read_b128 v[206:209], v161 offset:21504
	ds_read_b128 v[210:213], v161 offset:22528
	ds_read_b128 v[214:217], v161 offset:23552
	global_load_lds_dwordx4 v[158:159], off
	s_add_i32 m0, s69, 0x2000
	v_lshl_add_u64 v[166:167], s[70:71], 0, v[136:137]
	s_add_u32 s70, s70, s4
	s_addc_u32 s71, s71, s5
	s_add_i32 s69, s59, s42
	global_load_lds_dwordx4 v[166:167], off
	v_lshl_add_u64 v[218:219], s[70:71], 0, v[132:133]
	s_mov_b32 m0, s69
	v_lshl_add_u64 v[220:221], s[70:71], 0, v[136:137]
	global_load_lds_dwordx4 v[218:219], off
	s_add_i32 m0, s69, 0x2000
	v_lshl_add_u64 v[222:223], s[38:39], 0, v[130:131]
	global_load_lds_dwordx4 v[220:221], off
	s_mov_b32 m0, s43
	v_lshl_add_u64 v[224:225], s[38:39], 0, v[134:135]
	global_load_lds_dwordx4 v[222:223], off
	s_mov_b32 m0, s44
	s_nop 0
	global_load_lds_dwordx4 v[224:225], off
	s_waitcnt vmcnt(8)
	s_waitcnt lgkmcnt(0)
	s_barrier
	s_setprio 1
	v_mfma_i32_16x16x64_i8 v[62:65], v[146:149], v[186:189], v[62:65]
	v_mfma_i32_16x16x64_i8 v[58:61], v[154:157], v[186:189], v[58:61]
	v_mfma_i32_16x16x64_i8 v[54:57], v[146:149], v[194:197], v[54:57]
	v_mfma_i32_16x16x64_i8 v[50:53], v[154:157], v[194:197], v[50:53]
	v_mfma_i32_16x16x64_i8 v[42:45], v[146:149], v[202:205], v[42:45]
	v_mfma_i32_16x16x64_i8 v[34:37], v[154:157], v[202:205], v[34:37]
	v_mfma_i32_16x16x64_i8 v[26:29], v[146:149], v[210:213], v[26:29]
	v_mfma_i32_16x16x64_i8 v[18:21], v[154:157], v[210:213], v[18:21]
	v_mfma_i32_16x16x64_i8 v[62:65], v[150:153], v[190:193], v[62:65]
	v_mfma_i32_16x16x64_i8 v[58:61], v[162:165], v[190:193], v[58:61]
	v_mfma_i32_16x16x64_i8 v[54:57], v[150:153], v[198:201], v[54:57]
	v_mfma_i32_16x16x64_i8 v[50:53], v[162:165], v[198:201], v[50:53]
	v_mfma_i32_16x16x64_i8 v[42:45], v[150:153], v[206:209], v[42:45]
	v_mfma_i32_16x16x64_i8 v[34:37], v[162:165], v[206:209], v[34:37]
	v_mfma_i32_16x16x64_i8 v[26:29], v[150:153], v[214:217], v[26:29]
	v_mfma_i32_16x16x64_i8 v[18:21], v[162:165], v[214:217], v[18:21]
	v_mfma_i32_16x16x64_i8 v[46:49], v[170:173], v[186:189], v[46:49]
	v_mfma_i32_16x16x64_i8 v[38:41], v[178:181], v[186:189], v[38:41]
	v_mfma_i32_16x16x64_i8 v[30:33], v[170:173], v[194:197], v[30:33]
	v_mfma_i32_16x16x64_i8 v[22:25], v[178:181], v[194:197], v[22:25]
	v_mfma_i32_16x16x64_i8 v[14:17], v[170:173], v[202:205], v[14:17]
	v_mfma_i32_16x16x64_i8 v[10:13], v[178:181], v[202:205], v[10:13]
	v_mfma_i32_16x16x64_i8 v[6:9], v[170:173], v[210:213], v[6:9]
	v_mfma_i32_16x16x64_i8 v[2:5], v[178:181], v[210:213], v[2:5]
	v_mfma_i32_16x16x64_i8 v[46:49], v[174:177], v[190:193], v[46:49]
	v_mfma_i32_16x16x64_i8 v[38:41], v[182:185], v[190:193], v[38:41]
	v_mfma_i32_16x16x64_i8 v[30:33], v[174:177], v[198:201], v[30:33]
	v_mfma_i32_16x16x64_i8 v[22:25], v[182:185], v[198:201], v[22:25]
	v_mfma_i32_16x16x64_i8 v[14:17], v[174:177], v[206:209], v[14:17]
	v_mfma_i32_16x16x64_i8 v[10:13], v[182:185], v[206:209], v[10:13]
	v_mfma_i32_16x16x64_i8 v[6:9], v[174:177], v[214:217], v[6:9]
	v_mfma_i32_16x16x64_i8 v[2:5], v[182:185], v[214:217], v[2:5]
	s_barrier
	s_setprio 0
	s_add_i32 s69, 0, 0x18000
	v_add_u32_e32 v160, s69, v1
	s_add_i32 s70, 0, 0x1c000
	ds_read_b128 v[146:149], v160
	ds_read_b128 v[150:153], v160 offset:1024
	ds_read_b128 v[154:157], v160 offset:2048
	ds_read_b128 v[162:165], v160 offset:3072
	v_add_u32_e32 v160, s70, v1
	ds_read_b128 v[170:173], v160
	ds_read_b128 v[174:177], v160 offset:1024
	ds_read_b128 v[178:181], v160 offset:2048
	ds_read_b128 v[182:185], v160 offset:3072
	s_add_u32 s38, s38, s4
	s_addc_u32 s39, s39, s5
	s_mov_b32 m0, s45
	v_lshl_add_u64 v[226:227], s[38:39], 0, v[130:131]
	ds_read_b128 v[186:189], v161 offset:32768
	ds_read_b128 v[190:193], v161 offset:33792
	ds_read_b128 v[194:197], v161 offset:34816
	ds_read_b128 v[198:201], v161 offset:35840
	ds_read_b128 v[202:205], v161 offset:36864
	ds_read_b128 v[206:209], v161 offset:37888
	ds_read_b128 v[210:213], v161 offset:38912
	ds_read_b128 v[214:217], v161 offset:39936
	global_load_lds_dwordx4 v[226:227], off
	v_lshl_add_u64 v[226:227], s[38:39], 0, v[134:135]
	s_mov_b32 m0, s46
	s_nop 0
	global_load_lds_dwordx4 v[226:227], off
	s_waitcnt vmcnt(8)
	s_waitcnt lgkmcnt(0)
	s_barrier
	s_setprio 1
	v_mfma_i32_16x16x64_i8 v[126:129], v[146:149], v[186:189], v[126:129]
	v_mfma_i32_16x16x64_i8 v[122:125], v[154:157], v[186:189], v[122:125]
	v_mfma_i32_16x16x64_i8 v[118:121], v[146:149], v[194:197], v[118:121]
	v_mfma_i32_16x16x64_i8 v[114:117], v[154:157], v[194:197], v[114:117]
	v_mfma_i32_16x16x64_i8 v[106:109], v[146:149], v[202:205], v[106:109]
	v_mfma_i32_16x16x64_i8 v[98:101], v[154:157], v[202:205], v[98:101]
	v_mfma_i32_16x16x64_i8 v[90:93], v[146:149], v[210:213], v[90:93]
	v_mfma_i32_16x16x64_i8 v[82:85], v[154:157], v[210:213], v[82:85]
	v_mfma_i32_16x16x64_i8 v[126:129], v[150:153], v[190:193], v[126:129]
	v_mfma_i32_16x16x64_i8 v[122:125], v[162:165], v[190:193], v[122:125]
	v_mfma_i32_16x16x64_i8 v[118:121], v[150:153], v[198:201], v[118:121]
	v_mfma_i32_16x16x64_i8 v[114:117], v[162:165], v[198:201], v[114:117]
	v_mfma_i32_16x16x64_i8 v[106:109], v[150:153], v[206:209], v[106:109]
	v_mfma_i32_16x16x64_i8 v[98:101], v[162:165], v[206:209], v[98:101]
	v_mfma_i32_16x16x64_i8 v[90:93], v[150:153], v[214:217], v[90:93]
	v_mfma_i32_16x16x64_i8 v[82:85], v[162:165], v[214:217], v[82:85]
	v_mfma_i32_16x16x64_i8 v[110:113], v[170:173], v[186:189], v[110:113]
	v_mfma_i32_16x16x64_i8 v[102:105], v[178:181], v[186:189], v[102:105]
	v_mfma_i32_16x16x64_i8 v[94:97], v[170:173], v[194:197], v[94:97]
	v_mfma_i32_16x16x64_i8 v[86:89], v[178:181], v[194:197], v[86:89]
	v_mfma_i32_16x16x64_i8 v[78:81], v[170:173], v[202:205], v[78:81]
	v_mfma_i32_16x16x64_i8 v[74:77], v[178:181], v[202:205], v[74:77]
	v_mfma_i32_16x16x64_i8 v[70:73], v[170:173], v[210:213], v[70:73]
	v_mfma_i32_16x16x64_i8 v[66:69], v[178:181], v[210:213], v[66:69]
	v_mfma_i32_16x16x64_i8 v[110:113], v[174:177], v[190:193], v[110:113]
	v_mfma_i32_16x16x64_i8 v[102:105], v[182:185], v[190:193], v[102:105]
	v_mfma_i32_16x16x64_i8 v[94:97], v[174:177], v[198:201], v[94:97]
	v_mfma_i32_16x16x64_i8 v[86:89], v[182:185], v[198:201], v[86:89]
	v_mfma_i32_16x16x64_i8 v[78:81], v[174:177], v[206:209], v[78:81]
	v_mfma_i32_16x16x64_i8 v[74:77], v[182:185], v[206:209], v[74:77]
	v_mfma_i32_16x16x64_i8 v[70:73], v[174:177], v[214:217], v[70:73]
	v_mfma_i32_16x16x64_i8 v[66:69], v[182:185], v[214:217], v[66:69]
	s_barrier
	s_setprio 0
	s_add_i32 s38, s69, s42
	v_lshl_add_u64 v[158:159], v[158:159], 0, s[24:25]
	s_mov_b32 m0, s38
	ds_read_b128 v[186:189], v161 offset:49152
	ds_read_b128 v[190:193], v161 offset:50176
	ds_read_b128 v[194:197], v161 offset:51200
	ds_read_b128 v[198:201], v161 offset:52224
	ds_read_b128 v[202:205], v161 offset:53248
	ds_read_b128 v[206:209], v161 offset:54272
	ds_read_b128 v[210:213], v161 offset:55296
	ds_read_b128 v[214:217], v161 offset:56320
	global_load_lds_dwordx4 v[158:159], off
	v_lshl_add_u64 v[158:159], v[166:167], 0, s[24:25]
	s_add_i32 m0, s38, 0x2000
	s_add_i32 s38, s70, s42
	global_load_lds_dwordx4 v[158:159], off
	v_lshl_add_u64 v[158:159], v[218:219], 0, s[24:25]
	s_mov_b32 m0, s38
	s_nop 0
	global_load_lds_dwordx4 v[158:159], off
	v_lshl_add_u64 v[158:159], v[220:221], 0, s[24:25]
	s_add_i32 m0, s38, 0x2000
	s_nop 0
	global_load_lds_dwordx4 v[158:159], off
	v_lshl_add_u64 v[158:159], v[222:223], 0, s[24:25]
	s_mov_b32 m0, s50
	s_nop 0
	global_load_lds_dwordx4 v[158:159], off
	v_lshl_add_u64 v[158:159], v[224:225], 0, s[24:25]
	s_mov_b32 m0, s51
	s_nop 0
	global_load_lds_dwordx4 v[158:159], off
	s_waitcnt vmcnt(8)
	s_waitcnt lgkmcnt(0)
	s_barrier
	s_setprio 1
	v_mfma_i32_16x16x64_i8 v[62:65], v[146:149], v[186:189], v[62:65]
	v_mfma_i32_16x16x64_i8 v[58:61], v[154:157], v[186:189], v[58:61]
	v_mfma_i32_16x16x64_i8 v[54:57], v[146:149], v[194:197], v[54:57]
	v_mfma_i32_16x16x64_i8 v[50:53], v[154:157], v[194:197], v[50:53]
	v_mfma_i32_16x16x64_i8 v[42:45], v[146:149], v[202:205], v[42:45]
	v_mfma_i32_16x16x64_i8 v[34:37], v[154:157], v[202:205], v[34:37]
	v_mfma_i32_16x16x64_i8 v[26:29], v[146:149], v[210:213], v[26:29]
	v_mfma_i32_16x16x64_i8 v[18:21], v[154:157], v[210:213], v[18:21]
	v_mfma_i32_16x16x64_i8 v[62:65], v[150:153], v[190:193], v[62:65]
	v_mfma_i32_16x16x64_i8 v[58:61], v[162:165], v[190:193], v[58:61]
	v_mfma_i32_16x16x64_i8 v[54:57], v[150:153], v[198:201], v[54:57]
	v_mfma_i32_16x16x64_i8 v[50:53], v[162:165], v[198:201], v[50:53]
	v_mfma_i32_16x16x64_i8 v[42:45], v[150:153], v[206:209], v[42:45]
	v_mfma_i32_16x16x64_i8 v[34:37], v[162:165], v[206:209], v[34:37]
	v_mfma_i32_16x16x64_i8 v[26:29], v[150:153], v[214:217], v[26:29]
	v_mfma_i32_16x16x64_i8 v[18:21], v[162:165], v[214:217], v[18:21]
	v_mfma_i32_16x16x64_i8 v[46:49], v[170:173], v[186:189], v[46:49]
	v_mfma_i32_16x16x64_i8 v[38:41], v[178:181], v[186:189], v[38:41]
	v_mfma_i32_16x16x64_i8 v[30:33], v[170:173], v[194:197], v[30:33]
	v_mfma_i32_16x16x64_i8 v[22:25], v[178:181], v[194:197], v[22:25]
	v_mfma_i32_16x16x64_i8 v[14:17], v[170:173], v[202:205], v[14:17]
	v_mfma_i32_16x16x64_i8 v[10:13], v[178:181], v[202:205], v[10:13]
	v_mfma_i32_16x16x64_i8 v[6:9], v[170:173], v[210:213], v[6:9]
	v_mfma_i32_16x16x64_i8 v[2:5], v[178:181], v[210:213], v[2:5]
	v_mfma_i32_16x16x64_i8 v[46:49], v[174:177], v[190:193], v[46:49]
	v_mfma_i32_16x16x64_i8 v[38:41], v[182:185], v[190:193], v[38:41]
	v_mfma_i32_16x16x64_i8 v[30:33], v[174:177], v[198:201], v[30:33]
	v_mfma_i32_16x16x64_i8 v[22:25], v[182:185], v[198:201], v[22:25]
	v_mfma_i32_16x16x64_i8 v[14:17], v[174:177], v[206:209], v[14:17]
	v_mfma_i32_16x16x64_i8 v[10:13], v[182:185], v[206:209], v[10:13]
	v_mfma_i32_16x16x64_i8 v[6:9], v[174:177], v[214:217], v[6:9]
	v_mfma_i32_16x16x64_i8 v[2:5], v[182:185], v[214:217], v[2:5]
	s_barrier
	s_setprio 0
	s_add_u32 s36, s36, 0x100
	s_addc_u32 s37, s37, 0
	s_add_u32 s66, s66, 0x100
	s_addc_u32 s67, s67, 0
	s_cmp_ge_i32 s68, s52
	s_mov_b32 s38, s68
	s_cbranch_scc0 .LBB0_1751
	v_cvt_f32_i32_e32 v176, v126
	v_cvt_f32_i32_e32 v177, v127
	v_cvt_f32_i32_e32 v174, v128
	v_cvt_f32_i32_e32 v175, v129
	v_cvt_f32_i32_e32 v178, v122
	v_cvt_f32_i32_e32 v179, v123
	v_cvt_f32_i32_e32 v180, v124
	v_cvt_f32_i32_e32 v181, v125
	v_cvt_f32_i32_e32 v162, v110
	v_cvt_f32_i32_e32 v163, v111
	v_cvt_f32_i32_e32 v164, v112
	v_cvt_f32_i32_e32 v165, v113
	v_cvt_f32_i32_e32 v166, v102
	v_cvt_f32_i32_e32 v167, v103
	v_cvt_f32_i32_e32 v170, v104
	v_cvt_f32_i32_e32 v171, v105
	v_cvt_f32_i32_e32 v152, v118
	v_cvt_f32_i32_e32 v153, v119
	v_cvt_f32_i32_e32 v154, v120
	v_cvt_f32_i32_e32 v155, v121
	v_cvt_f32_i32_e32 v156, v114
	v_cvt_f32_i32_e32 v157, v115
	v_cvt_f32_i32_e32 v158, v116
	v_cvt_f32_i32_e32 v159, v117
	v_cvt_f32_i32_e32 v126, v94
	v_cvt_f32_i32_e32 v127, v95
	v_cvt_f32_i32_e32 v128, v96
	v_cvt_f32_i32_e32 v129, v97
	v_cvt_f32_i32_e32 v146, v86
	v_cvt_f32_i32_e32 v147, v87
	v_cvt_f32_i32_e32 v148, v88
	v_cvt_f32_i32_e32 v149, v89
	v_cvt_f32_i32_e32 v118, v106
	v_cvt_f32_i32_e32 v119, v107
	v_cvt_f32_i32_e32 v120, v108
	v_cvt_f32_i32_e32 v121, v109
	v_cvt_f32_i32_e32 v122, v98
	v_cvt_f32_i32_e32 v123, v99
	v_cvt_f32_i32_e32 v124, v100
	v_cvt_f32_i32_e32 v125, v101
	v_cvt_f32_i32_e32 v108, v78
	v_cvt_f32_i32_e32 v109, v79
	v_cvt_f32_i32_e32 v110, v80
	v_cvt_f32_i32_e32 v111, v81
	v_cvt_f32_i32_e32 v112, v74
	v_cvt_f32_i32_e32 v113, v75
	v_cvt_f32_i32_e32 v114, v76
	v_cvt_f32_i32_e32 v115, v77
	v_cvt_f32_i32_e32 v100, v90
	v_cvt_f32_i32_e32 v101, v91
	v_cvt_f32_i32_e32 v102, v92
	v_cvt_f32_i32_e32 v103, v93
	v_cvt_f32_i32_e32 v104, v82
	v_cvt_f32_i32_e32 v105, v83
	v_cvt_f32_i32_e32 v106, v84
	v_cvt_f32_i32_e32 v107, v85
	v_cvt_f32_i32_e32 v90, v70
	v_cvt_f32_i32_e32 v91, v71
	v_cvt_f32_i32_e32 v92, v72
	v_cvt_f32_i32_e32 v93, v73
	v_cvt_f32_i32_e32 v94, v66
	v_cvt_f32_i32_e32 v95, v67
	v_cvt_f32_i32_e32 v96, v68
	v_cvt_f32_i32_e32 v97, v69
	v_cvt_f32_i32_e32 v82, v62
	v_cvt_f32_i32_e32 v83, v63
	v_cvt_f32_i32_e32 v84, v64
	v_cvt_f32_i32_e32 v85, v65
	v_cvt_f32_i32_e32 v86, v58
	v_cvt_f32_i32_e32 v87, v59
	v_cvt_f32_i32_e32 v88, v60
	v_cvt_f32_i32_e32 v89, v61
	v_cvt_f32_i32_e32 v74, v46
	v_cvt_f32_i32_e32 v75, v47
	v_cvt_f32_i32_e32 v76, v48
	v_cvt_f32_i32_e32 v77, v49
	v_cvt_f32_i32_e32 v78, v38
	v_cvt_f32_i32_e32 v79, v39
	v_cvt_f32_i32_e32 v80, v40
	v_cvt_f32_i32_e32 v81, v41
	v_cvt_f32_i32_e32 v54, v54
	v_cvt_f32_i32_e32 v55, v55
	v_cvt_f32_i32_e32 v56, v56
	v_cvt_f32_i32_e32 v57, v57
	v_cvt_f32_i32_e32 v58, v50
	v_cvt_f32_i32_e32 v59, v51
	v_cvt_f32_i32_e32 v60, v52
	v_cvt_f32_i32_e32 v61, v53
	v_cvt_f32_i32_e32 v46, v30
	v_cvt_f32_i32_e32 v47, v31
	v_cvt_f32_i32_e32 v48, v32
	v_cvt_f32_i32_e32 v49, v33
	v_cvt_f32_i32_e32 v50, v22
	v_cvt_f32_i32_e32 v51, v23
	v_cvt_f32_i32_e32 v52, v24
	v_cvt_f32_i32_e32 v53, v25
	v_cvt_f32_i32_e32 v38, v42
	v_cvt_f32_i32_e32 v39, v43
	v_cvt_f32_i32_e32 v40, v44
	v_cvt_f32_i32_e32 v41, v45
	v_cvt_f32_i32_e32 v34, v34
	v_cvt_f32_i32_e32 v35, v35
	v_cvt_f32_i32_e32 v36, v36
	v_cvt_f32_i32_e32 v37, v37
	v_cvt_f32_i32_e32 v22, v14
	v_cvt_f32_i32_e32 v23, v15
	v_cvt_f32_i32_e32 v24, v16
	v_cvt_f32_i32_e32 v25, v17
	v_cvt_f32_i32_e32 v30, v10
	v_cvt_f32_i32_e32 v31, v11
	v_cvt_f32_i32_e32 v32, v12
	v_cvt_f32_i32_e32 v33, v13
	v_cvt_f32_i32_e32 v10, v26
	v_cvt_f32_i32_e32 v11, v27
	v_cvt_f32_i32_e32 v12, v28
	v_cvt_f32_i32_e32 v13, v29
	v_cvt_f32_i32_e32 v14, v18
	v_cvt_f32_i32_e32 v15, v19
	v_cvt_f32_i32_e32 v16, v20
	v_cvt_f32_i32_e32 v17, v21
	v_cvt_f32_i32_e32 v6, v6
	v_cvt_f32_i32_e32 v7, v7
	v_cvt_f32_i32_e32 v8, v8
	v_cvt_f32_i32_e32 v9, v9
	v_cvt_f32_i32_e32 v2, v2
	v_cvt_f32_i32_e32 v3, v3
	v_cvt_f32_i32_e32 v4, v4
	v_cvt_f32_i32_e32 v5, v5

.LBB0_1896:
	v_add_u32_e32 v150, s67, v1
	ds_read_b128 v[146:149], v150
	ds_read_b128 v[152:155], v150 offset:1024
	ds_read_b128 v[156:159], v150 offset:2048
	ds_read_b128 v[160:163], v150 offset:3072
	v_add_u32_e32 v150, s68, v1
	ds_read_b128 v[164:167], v150
	ds_read_b128 v[170:173], v150 offset:1024
	ds_read_b128 v[174:177], v150 offset:2048
	ds_read_b128 v[178:181], v150 offset:3072
	s_add_i32 s73, s38, 2
	s_add_u32 s74, s36, 0x80
	s_addc_u32 s39, s37, 0
	s_cmp_eq_u32 s63, s38
	s_cselect_b32 s38, s2, s74
	s_cselect_b32 s39, s3, s39
	s_cselect_b32 s75, s35, s72
	s_cselect_b32 s74, s34, s71
	v_lshl_add_u64 v[214:215], s[36:37], 0, v[138:139]
	s_add_i32 m0, s90, 0xc000
	ds_read_b128 v[182:185], v151
	ds_read_b128 v[186:189], v151 offset:1024
	ds_read_b128 v[190:193], v151 offset:2048
	ds_read_b128 v[194:197], v151 offset:3072
	ds_read_b128 v[198:201], v151 offset:4096
	ds_read_b128 v[202:205], v151 offset:5120
	ds_read_b128 v[206:209], v151 offset:6144
	ds_read_b128 v[210:213], v151 offset:7168
	global_load_lds_dwordx4 v[214:215], off
	v_lshl_add_u64 v[214:215], s[36:37], 0, v[140:141]
	s_add_i32 m0, s90, 0xe000
	s_nop 0
	global_load_lds_dwordx4 v[214:215], off
	s_waitcnt vmcnt(8)
	s_waitcnt lgkmcnt(0)
	s_barrier
	s_setprio 1
	v_mfma_i32_16x16x64_i8 v[126:129], v[146:149], v[182:185], v[126:129]
	v_mfma_i32_16x16x64_i8 v[122:125], v[156:159], v[182:185], v[122:125]
	v_mfma_i32_16x16x64_i8 v[118:121], v[146:149], v[190:193], v[118:121]
	v_mfma_i32_16x16x64_i8 v[114:117], v[156:159], v[190:193], v[114:117]
	v_mfma_i32_16x16x64_i8 v[106:109], v[146:149], v[198:201], v[106:109]
	v_mfma_i32_16x16x64_i8 v[98:101], v[156:159], v[198:201], v[98:101]
	v_mfma_i32_16x16x64_i8 v[90:93], v[146:149], v[206:209], v[90:93]
	v_mfma_i32_16x16x64_i8 v[82:85], v[156:159], v[206:209], v[82:85]
	v_mfma_i32_16x16x64_i8 v[126:129], v[152:155], v[186:189], v[126:129]
	v_mfma_i32_16x16x64_i8 v[122:125], v[160:163], v[186:189], v[122:125]
	v_mfma_i32_16x16x64_i8 v[118:121], v[152:155], v[194:197], v[118:121]
	v_mfma_i32_16x16x64_i8 v[114:117], v[160:163], v[194:197], v[114:117]
	v_mfma_i32_16x16x64_i8 v[106:109], v[152:155], v[202:205], v[106:109]
	v_mfma_i32_16x16x64_i8 v[98:101], v[160:163], v[202:205], v[98:101]
	v_mfma_i32_16x16x64_i8 v[90:93], v[152:155], v[210:213], v[90:93]
	v_mfma_i32_16x16x64_i8 v[82:85], v[160:163], v[210:213], v[82:85]
	v_mfma_i32_16x16x64_i8 v[110:113], v[164:167], v[182:185], v[110:113]
	v_mfma_i32_16x16x64_i8 v[102:105], v[174:177], v[182:185], v[102:105]
	v_mfma_i32_16x16x64_i8 v[94:97], v[164:167], v[190:193], v[94:97]
	v_mfma_i32_16x16x64_i8 v[86:89], v[174:177], v[190:193], v[86:89]
	v_mfma_i32_16x16x64_i8 v[78:81], v[164:167], v[198:201], v[78:81]
	v_mfma_i32_16x16x64_i8 v[74:77], v[174:177], v[198:201], v[74:77]
	v_mfma_i32_16x16x64_i8 v[70:73], v[164:167], v[206:209], v[70:73]
	v_mfma_i32_16x16x64_i8 v[66:69], v[174:177], v[206:209], v[66:69]
	v_mfma_i32_16x16x64_i8 v[110:113], v[170:173], v[186:189], v[110:113]
	v_mfma_i32_16x16x64_i8 v[102:105], v[178:181], v[186:189], v[102:105]
	v_mfma_i32_16x16x64_i8 v[94:97], v[170:173], v[194:197], v[94:97]
	v_mfma_i32_16x16x64_i8 v[86:89], v[178:181], v[194:197], v[86:89]
	v_mfma_i32_16x16x64_i8 v[78:81], v[170:173], v[202:205], v[78:81]
	v_mfma_i32_16x16x64_i8 v[74:77], v[178:181], v[202:205], v[74:77]
	v_mfma_i32_16x16x64_i8 v[70:73], v[170:173], v[210:213], v[70:73]
	v_mfma_i32_16x16x64_i8 v[66:69], v[178:181], v[210:213], v[66:69]
	s_barrier
	s_setprio 0
	s_add_i32 s76, s67, s85
	v_lshl_add_u64 v[214:215], s[74:75], 0, v[134:135]
	s_mov_b32 m0, s76
	ds_read_b128 v[182:185], v151 offset:16384
	ds_read_b128 v[186:189], v151 offset:17408
	ds_read_b128 v[190:193], v151 offset:18432
	ds_read_b128 v[194:197], v151 offset:19456
	ds_read_b128 v[198:201], v151 offset:20480
	ds_read_b128 v[202:205], v151 offset:21504
	ds_read_b128 v[206:209], v151 offset:22528
	ds_read_b128 v[210:213], v151 offset:23552
	global_load_lds_dwordx4 v[214:215], off
	s_add_i32 m0, s76, 0x2000
	v_lshl_add_u64 v[216:217], s[74:75], 0, v[130:131]
	s_add_u32 s74, s74, s6
	s_addc_u32 s75, s75, s7
	s_add_i32 s76, s68, s85
	global_load_lds_dwordx4 v[216:217], off
	v_lshl_add_u64 v[218:219], s[74:75], 0, v[134:135]
	s_mov_b32 m0, s76
	v_lshl_add_u64 v[220:221], s[74:75], 0, v[130:131]
	global_load_lds_dwordx4 v[218:219], off
	s_add_i32 m0, s76, 0x2000
	v_lshl_add_u64 v[222:223], s[38:39], 0, v[136:137]
	global_load_lds_dwordx4 v[220:221], off
	s_mov_b32 m0, s90
	v_lshl_add_u64 v[224:225], s[38:39], 0, v[132:133]
	global_load_lds_dwordx4 v[222:223], off
	s_mov_b32 m0, s91
	s_nop 0
	global_load_lds_dwordx4 v[224:225], off
	s_waitcnt vmcnt(8)
	s_waitcnt lgkmcnt(0)
	s_barrier
	s_setprio 1
	v_mfma_i32_16x16x64_i8 v[62:65], v[146:149], v[182:185], v[62:65]
	v_mfma_i32_16x16x64_i8 v[58:61], v[156:159], v[182:185], v[58:61]
	v_mfma_i32_16x16x64_i8 v[54:57], v[146:149], v[190:193], v[54:57]
	v_mfma_i32_16x16x64_i8 v[50:53], v[156:159], v[190:193], v[50:53]
	v_mfma_i32_16x16x64_i8 v[42:45], v[146:149], v[198:201], v[42:45]
	v_mfma_i32_16x16x64_i8 v[34:37], v[156:159], v[198:201], v[34:37]
	v_mfma_i32_16x16x64_i8 v[26:29], v[146:149], v[206:209], v[26:29]
	v_mfma_i32_16x16x64_i8 v[18:21], v[156:159], v[206:209], v[18:21]
	v_mfma_i32_16x16x64_i8 v[62:65], v[152:155], v[186:189], v[62:65]
	v_mfma_i32_16x16x64_i8 v[58:61], v[160:163], v[186:189], v[58:61]
	v_mfma_i32_16x16x64_i8 v[54:57], v[152:155], v[194:197], v[54:57]
	v_mfma_i32_16x16x64_i8 v[50:53], v[160:163], v[194:197], v[50:53]
	v_mfma_i32_16x16x64_i8 v[42:45], v[152:155], v[202:205], v[42:45]
	v_mfma_i32_16x16x64_i8 v[34:37], v[160:163], v[202:205], v[34:37]
	v_mfma_i32_16x16x64_i8 v[26:29], v[152:155], v[210:213], v[26:29]
	v_mfma_i32_16x16x64_i8 v[18:21], v[160:163], v[210:213], v[18:21]
	v_mfma_i32_16x16x64_i8 v[46:49], v[164:167], v[182:185], v[46:49]
	v_mfma_i32_16x16x64_i8 v[38:41], v[174:177], v[182:185], v[38:41]
	v_mfma_i32_16x16x64_i8 v[30:33], v[164:167], v[190:193], v[30:33]
	v_mfma_i32_16x16x64_i8 v[22:25], v[174:177], v[190:193], v[22:25]
	v_mfma_i32_16x16x64_i8 v[14:17], v[164:167], v[198:201], v[14:17]
	v_mfma_i32_16x16x64_i8 v[10:13], v[174:177], v[198:201], v[10:13]
	v_mfma_i32_16x16x64_i8 v[6:9], v[164:167], v[206:209], v[6:9]
	v_mfma_i32_16x16x64_i8 v[2:5], v[174:177], v[206:209], v[2:5]
	v_mfma_i32_16x16x64_i8 v[46:49], v[170:173], v[186:189], v[46:49]
	v_mfma_i32_16x16x64_i8 v[38:41], v[178:181], v[186:189], v[38:41]
	v_mfma_i32_16x16x64_i8 v[30:33], v[170:173], v[194:197], v[30:33]
	v_mfma_i32_16x16x64_i8 v[22:25], v[178:181], v[194:197], v[22:25]
	v_mfma_i32_16x16x64_i8 v[14:17], v[170:173], v[202:205], v[14:17]
	v_mfma_i32_16x16x64_i8 v[10:13], v[178:181], v[202:205], v[10:13]
	v_mfma_i32_16x16x64_i8 v[6:9], v[170:173], v[210:213], v[6:9]
	v_mfma_i32_16x16x64_i8 v[2:5], v[178:181], v[210:213], v[2:5]
	s_barrier
	s_setprio 0
	s_add_i32 s74, 0, 0x18000
	v_add_u32_e32 v150, s74, v1
	s_add_i32 s75, 0, 0x1c000
	ds_read_b128 v[146:149], v150
	ds_read_b128 v[152:155], v150 offset:1024
	ds_read_b128 v[156:159], v150 offset:2048
	ds_read_b128 v[160:163], v150 offset:3072
	v_add_u32_e32 v150, s75, v1
	ds_read_b128 v[164:167], v150
	ds_read_b128 v[170:173], v150 offset:1024
	ds_read_b128 v[174:177], v150 offset:2048
	ds_read_b128 v[178:181], v150 offset:3072
	s_add_u32 s38, s38, s6
	s_addc_u32 s39, s39, s7
	s_mov_b32 m0, s96
	v_lshl_add_u64 v[226:227], s[38:39], 0, v[136:137]
	ds_read_b128 v[182:185], v151 offset:32768
	ds_read_b128 v[186:189], v151 offset:33792
	ds_read_b128 v[190:193], v151 offset:34816
	ds_read_b128 v[194:197], v151 offset:35840
	ds_read_b128 v[198:201], v151 offset:36864
	ds_read_b128 v[202:205], v151 offset:37888
	ds_read_b128 v[206:209], v151 offset:38912
	ds_read_b128 v[210:213], v151 offset:39936
	global_load_lds_dwordx4 v[226:227], off
	v_lshl_add_u64 v[226:227], s[38:39], 0, v[132:133]
	s_mov_b32 m0, s52
	s_nop 0
	global_load_lds_dwordx4 v[226:227], off
	s_waitcnt vmcnt(8)
	s_waitcnt lgkmcnt(0)
	s_barrier
	s_setprio 1
	v_mfma_i32_16x16x64_i8 v[126:129], v[146:149], v[182:185], v[126:129]
	v_mfma_i32_16x16x64_i8 v[122:125], v[156:159], v[182:185], v[122:125]
	v_mfma_i32_16x16x64_i8 v[118:121], v[146:149], v[190:193], v[118:121]
	v_mfma_i32_16x16x64_i8 v[114:117], v[156:159], v[190:193], v[114:117]
	v_mfma_i32_16x16x64_i8 v[106:109], v[146:149], v[198:201], v[106:109]
	v_mfma_i32_16x16x64_i8 v[98:101], v[156:159], v[198:201], v[98:101]
	v_mfma_i32_16x16x64_i8 v[90:93], v[146:149], v[206:209], v[90:93]
	v_mfma_i32_16x16x64_i8 v[82:85], v[156:159], v[206:209], v[82:85]
	v_mfma_i32_16x16x64_i8 v[126:129], v[152:155], v[186:189], v[126:129]
	v_mfma_i32_16x16x64_i8 v[122:125], v[160:163], v[186:189], v[122:125]
	v_mfma_i32_16x16x64_i8 v[118:121], v[152:155], v[194:197], v[118:121]
	v_mfma_i32_16x16x64_i8 v[114:117], v[160:163], v[194:197], v[114:117]
	v_mfma_i32_16x16x64_i8 v[106:109], v[152:155], v[202:205], v[106:109]
	v_mfma_i32_16x16x64_i8 v[98:101], v[160:163], v[202:205], v[98:101]
	v_mfma_i32_16x16x64_i8 v[90:93], v[152:155], v[210:213], v[90:93]
	v_mfma_i32_16x16x64_i8 v[82:85], v[160:163], v[210:213], v[82:85]
	v_mfma_i32_16x16x64_i8 v[110:113], v[164:167], v[182:185], v[110:113]
	v_mfma_i32_16x16x64_i8 v[102:105], v[174:177], v[182:185], v[102:105]
	v_mfma_i32_16x16x64_i8 v[94:97], v[164:167], v[190:193], v[94:97]
	v_mfma_i32_16x16x64_i8 v[86:89], v[174:177], v[190:193], v[86:89]
	v_mfma_i32_16x16x64_i8 v[78:81], v[164:167], v[198:201], v[78:81]
	v_mfma_i32_16x16x64_i8 v[74:77], v[174:177], v[198:201], v[74:77]
	v_mfma_i32_16x16x64_i8 v[70:73], v[164:167], v[206:209], v[70:73]
	v_mfma_i32_16x16x64_i8 v[66:69], v[174:177], v[206:209], v[66:69]
	v_mfma_i32_16x16x64_i8 v[110:113], v[170:173], v[186:189], v[110:113]
	v_mfma_i32_16x16x64_i8 v[102:105], v[178:181], v[186:189], v[102:105]
	v_mfma_i32_16x16x64_i8 v[94:97], v[170:173], v[194:197], v[94:97]
	v_mfma_i32_16x16x64_i8 v[86:89], v[178:181], v[194:197], v[86:89]
	v_mfma_i32_16x16x64_i8 v[78:81], v[170:173], v[202:205], v[78:81]
	v_mfma_i32_16x16x64_i8 v[74:77], v[178:181], v[202:205], v[74:77]
	v_mfma_i32_16x16x64_i8 v[70:73], v[170:173], v[210:213], v[70:73]
	v_mfma_i32_16x16x64_i8 v[66:69], v[178:181], v[210:213], v[66:69]
	s_barrier
	s_setprio 0
	s_add_i32 s38, s74, s85
	v_lshl_add_u64 v[214:215], v[214:215], 0, s[16:17]
	s_mov_b32 m0, s38
	ds_read_b128 v[182:185], v151 offset:49152
	ds_read_b128 v[186:189], v151 offset:50176
	ds_read_b128 v[190:193], v151 offset:51200
	ds_read_b128 v[194:197], v151 offset:52224
	ds_read_b128 v[198:201], v151 offset:53248
	ds_read_b128 v[202:205], v151 offset:54272
	ds_read_b128 v[206:209], v151 offset:55296
	ds_read_b128 v[210:213], v151 offset:56320
	global_load_lds_dwordx4 v[214:215], off
	v_lshl_add_u64 v[214:215], v[216:217], 0, s[16:17]
	s_add_i32 m0, s38, 0x2000
	s_add_i32 s38, s75, s85
	global_load_lds_dwordx4 v[214:215], off
	v_lshl_add_u64 v[214:215], v[218:219], 0, s[16:17]
	s_mov_b32 m0, s38
	s_nop 0
	global_load_lds_dwordx4 v[214:215], off
	v_lshl_add_u64 v[214:215], v[220:221], 0, s[16:17]
	s_add_i32 m0, s38, 0x2000
	s_nop 0
	global_load_lds_dwordx4 v[214:215], off
	v_lshl_add_u64 v[214:215], v[222:223], 0, s[16:17]
	s_mov_b32 m0, s57
	s_nop 0
	global_load_lds_dwordx4 v[214:215], off
	v_lshl_add_u64 v[214:215], v[224:225], 0, s[16:17]
	s_mov_b32 m0, s58
	s_nop 0
	global_load_lds_dwordx4 v[214:215], off
	s_waitcnt vmcnt(8)
	s_waitcnt lgkmcnt(0)
	s_barrier
	s_setprio 1
	v_mfma_i32_16x16x64_i8 v[62:65], v[146:149], v[182:185], v[62:65]
	v_mfma_i32_16x16x64_i8 v[58:61], v[156:159], v[182:185], v[58:61]
	v_mfma_i32_16x16x64_i8 v[54:57], v[146:149], v[190:193], v[54:57]
	v_mfma_i32_16x16x64_i8 v[50:53], v[156:159], v[190:193], v[50:53]
	v_mfma_i32_16x16x64_i8 v[42:45], v[146:149], v[198:201], v[42:45]
	v_mfma_i32_16x16x64_i8 v[34:37], v[156:159], v[198:201], v[34:37]
	v_mfma_i32_16x16x64_i8 v[26:29], v[146:149], v[206:209], v[26:29]
	v_mfma_i32_16x16x64_i8 v[18:21], v[156:159], v[206:209], v[18:21]
	v_mfma_i32_16x16x64_i8 v[62:65], v[152:155], v[186:189], v[62:65]
	v_mfma_i32_16x16x64_i8 v[58:61], v[160:163], v[186:189], v[58:61]
	v_mfma_i32_16x16x64_i8 v[54:57], v[152:155], v[194:197], v[54:57]
	v_mfma_i32_16x16x64_i8 v[50:53], v[160:163], v[194:197], v[50:53]
	v_mfma_i32_16x16x64_i8 v[42:45], v[152:155], v[202:205], v[42:45]
	v_mfma_i32_16x16x64_i8 v[34:37], v[160:163], v[202:205], v[34:37]
	v_mfma_i32_16x16x64_i8 v[26:29], v[152:155], v[210:213], v[26:29]
	v_mfma_i32_16x16x64_i8 v[18:21], v[160:163], v[210:213], v[18:21]
	v_mfma_i32_16x16x64_i8 v[46:49], v[164:167], v[182:185], v[46:49]
	v_mfma_i32_16x16x64_i8 v[38:41], v[174:177], v[182:185], v[38:41]
	v_mfma_i32_16x16x64_i8 v[30:33], v[164:167], v[190:193], v[30:33]
	v_mfma_i32_16x16x64_i8 v[22:25], v[174:177], v[190:193], v[22:25]
	v_mfma_i32_16x16x64_i8 v[14:17], v[164:167], v[198:201], v[14:17]
	v_mfma_i32_16x16x64_i8 v[10:13], v[174:177], v[198:201], v[10:13]
	v_mfma_i32_16x16x64_i8 v[6:9], v[164:167], v[206:209], v[6:9]
	v_mfma_i32_16x16x64_i8 v[2:5], v[174:177], v[206:209], v[2:5]
	v_mfma_i32_16x16x64_i8 v[46:49], v[170:173], v[186:189], v[46:49]
	v_mfma_i32_16x16x64_i8 v[38:41], v[178:181], v[186:189], v[38:41]
	v_mfma_i32_16x16x64_i8 v[30:33], v[170:173], v[194:197], v[30:33]
	v_mfma_i32_16x16x64_i8 v[22:25], v[178:181], v[194:197], v[22:25]
	v_mfma_i32_16x16x64_i8 v[14:17], v[170:173], v[202:205], v[14:17]
	v_mfma_i32_16x16x64_i8 v[10:13], v[178:181], v[202:205], v[10:13]
	v_mfma_i32_16x16x64_i8 v[6:9], v[170:173], v[210:213], v[6:9]
	v_mfma_i32_16x16x64_i8 v[2:5], v[178:181], v[210:213], v[2:5]
	s_barrier
	s_setprio 0
	s_add_u32 s36, s36, 0x100
	s_addc_u32 s37, s37, 0
	s_add_u32 s71, s71, 0x100
	s_addc_u32 s72, s72, 0
	s_cmp_ge_i32 s73, s59
	s_mov_b32 s38, s73
	s_cbranch_scc0 .LBB0_1896
	v_cvt_f32_i32_e32 v154, v126
	v_cvt_f32_i32_e32 v155, v127
	v_cvt_f32_i32_e32 v152, v128
	v_cvt_f32_i32_e32 v153, v129
	v_cvt_f32_i32_e32 v158, v122
	v_cvt_f32_i32_e32 v159, v123
	v_cvt_f32_i32_e32 v156, v124
	v_cvt_f32_i32_e32 v157, v125
	v_cvt_f32_i32_e32 v128, v110
	v_cvt_f32_i32_e32 v129, v111
	v_cvt_f32_i32_e32 v126, v112
	v_cvt_f32_i32_e32 v127, v113
	v_cvt_f32_i32_e32 v148, v102
	v_cvt_f32_i32_e32 v149, v103
	v_cvt_f32_i32_e32 v146, v104
	v_cvt_f32_i32_e32 v147, v105
	v_cvt_f32_i32_e32 v122, v118
	v_cvt_f32_i32_e32 v123, v119
	v_cvt_f32_i32_e32 v118, v120
	v_cvt_f32_i32_e32 v119, v121
	v_cvt_f32_i32_e32 v124, v114
	v_cvt_f32_i32_e32 v125, v115
	v_cvt_f32_i32_e32 v120, v116
	v_cvt_f32_i32_e32 v121, v117
	v_cvt_f32_i32_e32 v112, v94
	v_cvt_f32_i32_e32 v113, v95
	v_cvt_f32_i32_e32 v110, v96
	v_cvt_f32_i32_e32 v111, v97
	v_cvt_f32_i32_e32 v116, v86
	v_cvt_f32_i32_e32 v117, v87
	v_cvt_f32_i32_e32 v114, v88
	v_cvt_f32_i32_e32 v115, v89
	v_cvt_f32_i32_e32 v104, v106
	v_cvt_f32_i32_e32 v105, v107
	v_cvt_f32_i32_e32 v102, v108
	v_cvt_f32_i32_e32 v103, v109
	v_cvt_f32_i32_e32 v108, v98
	v_cvt_f32_i32_e32 v109, v99
	v_cvt_f32_i32_e32 v106, v100
	v_cvt_f32_i32_e32 v107, v101
	v_cvt_f32_i32_e32 v96, v78
	v_cvt_f32_i32_e32 v97, v79
	v_cvt_f32_i32_e32 v94, v80
	v_cvt_f32_i32_e32 v95, v81
	v_cvt_f32_i32_e32 v100, v74
	v_cvt_f32_i32_e32 v101, v75
	v_cvt_f32_i32_e32 v98, v76
	v_cvt_f32_i32_e32 v99, v77
	v_cvt_f32_i32_e32 v88, v90
	v_cvt_f32_i32_e32 v89, v91
	v_cvt_f32_i32_e32 v86, v92
	v_cvt_f32_i32_e32 v87, v93
	v_cvt_f32_i32_e32 v92, v82
	v_cvt_f32_i32_e32 v93, v83
	v_cvt_f32_i32_e32 v90, v84
	v_cvt_f32_i32_e32 v91, v85
	v_cvt_f32_i32_e32 v80, v70
	v_cvt_f32_i32_e32 v81, v71
	v_cvt_f32_i32_e32 v78, v72
	v_cvt_f32_i32_e32 v79, v73
	v_cvt_f32_i32_e32 v84, v66
	v_cvt_f32_i32_e32 v85, v67
	v_cvt_f32_i32_e32 v82, v68
	v_cvt_f32_i32_e32 v83, v69
	v_cvt_f32_i32_e32 v72, v62
	v_cvt_f32_i32_e32 v73, v63
	v_cvt_f32_i32_e32 v70, v64
	v_cvt_f32_i32_e32 v71, v65
	v_cvt_f32_i32_e32 v76, v58
	v_cvt_f32_i32_e32 v77, v59
	v_cvt_f32_i32_e32 v74, v60
	v_cvt_f32_i32_e32 v75, v61
	v_cvt_f32_i32_e32 v64, v46
	v_cvt_f32_i32_e32 v65, v47
	v_cvt_f32_i32_e32 v62, v48
	v_cvt_f32_i32_e32 v63, v49
	v_cvt_f32_i32_e32 v68, v38
	v_cvt_f32_i32_e32 v69, v39
	v_cvt_f32_i32_e32 v66, v40
	v_cvt_f32_i32_e32 v67, v41
	v_cvt_f32_i32_e32 v58, v54
	v_cvt_f32_i32_e32 v59, v55
	v_cvt_f32_i32_e32 v54, v56
	v_cvt_f32_i32_e32 v55, v57
	v_cvt_f32_i32_e32 v60, v50
	v_cvt_f32_i32_e32 v61, v51
	v_cvt_f32_i32_e32 v56, v52
	v_cvt_f32_i32_e32 v57, v53
	v_cvt_f32_i32_e32 v48, v30
	v_cvt_f32_i32_e32 v49, v31
	v_cvt_f32_i32_e32 v46, v32
	v_cvt_f32_i32_e32 v47, v33
	v_cvt_f32_i32_e32 v52, v22
	v_cvt_f32_i32_e32 v53, v23
	v_cvt_f32_i32_e32 v50, v24
	v_cvt_f32_i32_e32 v51, v25
	v_cvt_f32_i32_e32 v40, v42
	v_cvt_f32_i32_e32 v41, v43
	v_cvt_f32_i32_e32 v38, v44
	v_cvt_f32_i32_e32 v39, v45
	v_cvt_f32_i32_e32 v42, v34
	v_cvt_f32_i32_e32 v43, v35
	v_cvt_f32_i32_e32 v34, v36
	v_cvt_f32_i32_e32 v35, v37
	v_cvt_f32_i32_e32 v24, v14
	v_cvt_f32_i32_e32 v25, v15
	v_cvt_f32_i32_e32 v22, v16
	v_cvt_f32_i32_e32 v23, v17
	v_cvt_f32_i32_e32 v32, v10
	v_cvt_f32_i32_e32 v33, v11
	v_cvt_f32_i32_e32 v30, v12
	v_cvt_f32_i32_e32 v31, v13
	v_cvt_f32_i32_e32 v14, v26
	v_cvt_f32_i32_e32 v15, v27
	v_cvt_f32_i32_e32 v12, v28
	v_cvt_f32_i32_e32 v13, v29
	v_cvt_f32_i32_e32 v18, v18
	v_cvt_f32_i32_e32 v19, v19
	v_cvt_f32_i32_e32 v16, v20
	v_cvt_f32_i32_e32 v17, v21
	v_cvt_f32_i32_e32 v10, v6
	v_cvt_f32_i32_e32 v11, v7
	v_cvt_f32_i32_e32 v6, v8
	v_cvt_f32_i32_e32 v7, v9
	v_cvt_f32_i32_e32 v8, v2
	v_cvt_f32_i32_e32 v9, v3
	v_cvt_f32_i32_e32 v2, v4
	v_cvt_f32_i32_e32 v3, v5

.LBB0_2025:
	v_add_u32_e32 v138, s56, v1
	ds_read_b128 v[148:151], v138
	ds_read_b128 v[156:159], v138 offset:1024
	ds_read_b128 v[160:163], v138 offset:2048
	ds_read_b128 v[164:167], v138 offset:3072
	v_add_u32_e32 v138, s57, v1
	ds_read_b128 v[168:171], v138
	ds_read_b128 v[172:175], v138 offset:1024
	ds_read_b128 v[176:179], v138 offset:2048
	ds_read_b128 v[180:183], v138 offset:3072
	s_add_i32 s65, s30, 2
	s_add_u32 s66, s28, 0x80
	s_addc_u32 s31, s29, 0
	s_cmp_eq_u32 s54, s30
	s_cselect_b32 s30, s2, s66
	s_cselect_b32 s31, s3, s31
	s_cselect_b32 s67, s27, s64
	s_cselect_b32 s66, s26, s63
	v_lshl_add_u64 v[152:153], s[28:29], 0, v[140:141]
	s_add_i32 m0, s41, 0xc000
	ds_read_b128 v[184:187], v155
	ds_read_b128 v[188:191], v155 offset:1024
	ds_read_b128 v[192:195], v155 offset:2048
	ds_read_b128 v[196:199], v155 offset:3072
	ds_read_b128 v[200:203], v155 offset:4096
	ds_read_b128 v[204:207], v155 offset:5120
	ds_read_b128 v[208:211], v155 offset:6144
	ds_read_b128 v[212:215], v155 offset:7168
	global_load_lds_dwordx4 v[152:153], off
	v_lshl_add_u64 v[152:153], s[28:29], 0, v[142:143]
	s_add_i32 m0, s41, 0xe000
	s_nop 0
	global_load_lds_dwordx4 v[152:153], off
	s_waitcnt vmcnt(8)
	s_waitcnt lgkmcnt(0)
	s_barrier
	s_setprio 1
	v_mfma_i32_16x16x64_i8 v[126:129], v[148:151], v[184:187], v[126:129]
	v_mfma_i32_16x16x64_i8 v[122:125], v[160:163], v[184:187], v[122:125]
	v_mfma_i32_16x16x64_i8 v[118:121], v[148:151], v[192:195], v[118:121]
	v_mfma_i32_16x16x64_i8 v[114:117], v[160:163], v[192:195], v[114:117]
	v_mfma_i32_16x16x64_i8 v[106:109], v[148:151], v[200:203], v[106:109]
	v_mfma_i32_16x16x64_i8 v[98:101], v[160:163], v[200:203], v[98:101]
	v_mfma_i32_16x16x64_i8 v[90:93], v[148:151], v[208:211], v[90:93]
	v_mfma_i32_16x16x64_i8 v[82:85], v[160:163], v[208:211], v[82:85]
	v_mfma_i32_16x16x64_i8 v[126:129], v[156:159], v[188:191], v[126:129]
	v_mfma_i32_16x16x64_i8 v[122:125], v[164:167], v[188:191], v[122:125]
	v_mfma_i32_16x16x64_i8 v[118:121], v[156:159], v[196:199], v[118:121]
	v_mfma_i32_16x16x64_i8 v[114:117], v[164:167], v[196:199], v[114:117]
	v_mfma_i32_16x16x64_i8 v[106:109], v[156:159], v[204:207], v[106:109]
	v_mfma_i32_16x16x64_i8 v[98:101], v[164:167], v[204:207], v[98:101]
	v_mfma_i32_16x16x64_i8 v[90:93], v[156:159], v[212:215], v[90:93]
	v_mfma_i32_16x16x64_i8 v[82:85], v[164:167], v[212:215], v[82:85]
	v_mfma_i32_16x16x64_i8 v[110:113], v[168:171], v[184:187], v[110:113]
	v_mfma_i32_16x16x64_i8 v[102:105], v[176:179], v[184:187], v[102:105]
	v_mfma_i32_16x16x64_i8 v[94:97], v[168:171], v[192:195], v[94:97]
	v_mfma_i32_16x16x64_i8 v[86:89], v[176:179], v[192:195], v[86:89]
	v_mfma_i32_16x16x64_i8 v[78:81], v[168:171], v[200:203], v[78:81]
	v_mfma_i32_16x16x64_i8 v[74:77], v[176:179], v[200:203], v[74:77]
	v_mfma_i32_16x16x64_i8 v[70:73], v[168:171], v[208:211], v[70:73]
	v_mfma_i32_16x16x64_i8 v[66:69], v[176:179], v[208:211], v[66:69]
	v_mfma_i32_16x16x64_i8 v[110:113], v[172:175], v[188:191], v[110:113]
	v_mfma_i32_16x16x64_i8 v[102:105], v[180:183], v[188:191], v[102:105]
	v_mfma_i32_16x16x64_i8 v[94:97], v[172:175], v[196:199], v[94:97]
	v_mfma_i32_16x16x64_i8 v[86:89], v[180:183], v[196:199], v[86:89]
	v_mfma_i32_16x16x64_i8 v[78:81], v[172:175], v[204:207], v[78:81]
	v_mfma_i32_16x16x64_i8 v[74:77], v[180:183], v[204:207], v[74:77]
	v_mfma_i32_16x16x64_i8 v[70:73], v[172:175], v[212:215], v[70:73]
	v_mfma_i32_16x16x64_i8 v[66:69], v[180:183], v[212:215], v[66:69]
	s_barrier
	s_setprio 0
	s_add_i32 s68, s56, s38
	v_lshl_add_u64 v[152:153], s[66:67], 0, v[134:135]
	s_mov_b32 m0, s68
	ds_read_b128 v[184:187], v155 offset:16384
	ds_read_b128 v[188:191], v155 offset:17408
	ds_read_b128 v[192:195], v155 offset:18432
	ds_read_b128 v[196:199], v155 offset:19456
	ds_read_b128 v[200:203], v155 offset:20480
	ds_read_b128 v[204:207], v155 offset:21504
	ds_read_b128 v[208:211], v155 offset:22528
	ds_read_b128 v[212:215], v155 offset:23552
	global_load_lds_dwordx4 v[152:153], off
	s_add_i32 m0, s68, 0x2000
	v_lshl_add_u64 v[216:217], s[66:67], 0, v[130:131]
	s_add_u32 s66, s66, s6
	s_addc_u32 s67, s67, s7
	s_add_i32 s68, s57, s38
	global_load_lds_dwordx4 v[216:217], off
	v_lshl_add_u64 v[218:219], s[66:67], 0, v[134:135]
	s_mov_b32 m0, s68
	v_lshl_add_u64 v[220:221], s[66:67], 0, v[130:131]
	global_load_lds_dwordx4 v[218:219], off
	s_add_i32 m0, s68, 0x2000
	v_lshl_add_u64 v[222:223], s[30:31], 0, v[136:137]
	global_load_lds_dwordx4 v[220:221], off
	s_mov_b32 m0, s41
	v_lshl_add_u64 v[224:225], s[30:31], 0, v[132:133]
	global_load_lds_dwordx4 v[222:223], off
	s_mov_b32 m0, s42
	s_nop 0
	global_load_lds_dwordx4 v[224:225], off
	s_waitcnt vmcnt(8)
	s_waitcnt lgkmcnt(0)
	s_barrier
	s_setprio 1
	v_mfma_i32_16x16x64_i8 v[62:65], v[148:151], v[184:187], v[62:65]
	v_mfma_i32_16x16x64_i8 v[58:61], v[160:163], v[184:187], v[58:61]
	v_mfma_i32_16x16x64_i8 v[54:57], v[148:151], v[192:195], v[54:57]
	v_mfma_i32_16x16x64_i8 v[50:53], v[160:163], v[192:195], v[50:53]
	v_mfma_i32_16x16x64_i8 v[42:45], v[148:151], v[200:203], v[42:45]
	v_mfma_i32_16x16x64_i8 v[34:37], v[160:163], v[200:203], v[34:37]
	v_mfma_i32_16x16x64_i8 v[26:29], v[148:151], v[208:211], v[26:29]
	v_mfma_i32_16x16x64_i8 v[18:21], v[160:163], v[208:211], v[18:21]
	v_mfma_i32_16x16x64_i8 v[62:65], v[156:159], v[188:191], v[62:65]
	v_mfma_i32_16x16x64_i8 v[58:61], v[164:167], v[188:191], v[58:61]
	v_mfma_i32_16x16x64_i8 v[54:57], v[156:159], v[196:199], v[54:57]
	v_mfma_i32_16x16x64_i8 v[50:53], v[164:167], v[196:199], v[50:53]
	v_mfma_i32_16x16x64_i8 v[42:45], v[156:159], v[204:207], v[42:45]
	v_mfma_i32_16x16x64_i8 v[34:37], v[164:167], v[204:207], v[34:37]
	v_mfma_i32_16x16x64_i8 v[26:29], v[156:159], v[212:215], v[26:29]
	v_mfma_i32_16x16x64_i8 v[18:21], v[164:167], v[212:215], v[18:21]
	v_mfma_i32_16x16x64_i8 v[46:49], v[168:171], v[184:187], v[46:49]
	v_mfma_i32_16x16x64_i8 v[38:41], v[176:179], v[184:187], v[38:41]
	v_mfma_i32_16x16x64_i8 v[30:33], v[168:171], v[192:195], v[30:33]
	v_mfma_i32_16x16x64_i8 v[22:25], v[176:179], v[192:195], v[22:25]
	v_mfma_i32_16x16x64_i8 v[14:17], v[168:171], v[200:203], v[14:17]
	v_mfma_i32_16x16x64_i8 v[10:13], v[176:179], v[200:203], v[10:13]
	v_mfma_i32_16x16x64_i8 v[6:9], v[168:171], v[208:211], v[6:9]
	v_mfma_i32_16x16x64_i8 v[2:5], v[176:179], v[208:211], v[2:5]
	v_mfma_i32_16x16x64_i8 v[46:49], v[172:175], v[188:191], v[46:49]
	v_mfma_i32_16x16x64_i8 v[38:41], v[180:183], v[188:191], v[38:41]
	v_mfma_i32_16x16x64_i8 v[30:33], v[172:175], v[196:199], v[30:33]
	v_mfma_i32_16x16x64_i8 v[22:25], v[180:183], v[196:199], v[22:25]
	v_mfma_i32_16x16x64_i8 v[14:17], v[172:175], v[204:207], v[14:17]
	v_mfma_i32_16x16x64_i8 v[10:13], v[180:183], v[204:207], v[10:13]
	v_mfma_i32_16x16x64_i8 v[6:9], v[172:175], v[212:215], v[6:9]
	v_mfma_i32_16x16x64_i8 v[2:5], v[180:183], v[212:215], v[2:5]
	s_barrier
	s_setprio 0
	s_add_i32 s66, 0, 0x18000
	v_add_u32_e32 v138, s66, v1
	s_add_i32 s67, 0, 0x1c000
	ds_read_b128 v[148:151], v138
	ds_read_b128 v[156:159], v138 offset:1024
	ds_read_b128 v[160:163], v138 offset:2048
	ds_read_b128 v[164:167], v138 offset:3072
	v_add_u32_e32 v138, s67, v1
	ds_read_b128 v[168:171], v138
	ds_read_b128 v[172:175], v138 offset:1024
	ds_read_b128 v[176:179], v138 offset:2048
	ds_read_b128 v[180:183], v138 offset:3072
	s_add_u32 s30, s30, s6
	s_addc_u32 s31, s31, s7
	s_mov_b32 m0, s43
	v_lshl_add_u64 v[226:227], s[30:31], 0, v[136:137]
	ds_read_b128 v[184:187], v155 offset:32768
	ds_read_b128 v[188:191], v155 offset:33792
	ds_read_b128 v[192:195], v155 offset:34816
	ds_read_b128 v[196:199], v155 offset:35840
	ds_read_b128 v[200:203], v155 offset:36864
	ds_read_b128 v[204:207], v155 offset:37888
	ds_read_b128 v[208:211], v155 offset:38912
	ds_read_b128 v[212:215], v155 offset:39936
	global_load_lds_dwordx4 v[226:227], off
	v_lshl_add_u64 v[226:227], s[30:31], 0, v[132:133]
	s_mov_b32 m0, s44
	s_nop 0
	global_load_lds_dwordx4 v[226:227], off
	s_waitcnt vmcnt(8)
	s_waitcnt lgkmcnt(0)
	s_barrier
	s_setprio 1
	v_mfma_i32_16x16x64_i8 v[126:129], v[148:151], v[184:187], v[126:129]
	v_mfma_i32_16x16x64_i8 v[122:125], v[160:163], v[184:187], v[122:125]
	v_mfma_i32_16x16x64_i8 v[118:121], v[148:151], v[192:195], v[118:121]
	v_mfma_i32_16x16x64_i8 v[114:117], v[160:163], v[192:195], v[114:117]
	v_mfma_i32_16x16x64_i8 v[106:109], v[148:151], v[200:203], v[106:109]
	v_mfma_i32_16x16x64_i8 v[98:101], v[160:163], v[200:203], v[98:101]
	v_mfma_i32_16x16x64_i8 v[90:93], v[148:151], v[208:211], v[90:93]
	v_mfma_i32_16x16x64_i8 v[82:85], v[160:163], v[208:211], v[82:85]
	v_mfma_i32_16x16x64_i8 v[126:129], v[156:159], v[188:191], v[126:129]
	v_mfma_i32_16x16x64_i8 v[122:125], v[164:167], v[188:191], v[122:125]
	v_mfma_i32_16x16x64_i8 v[118:121], v[156:159], v[196:199], v[118:121]
	v_mfma_i32_16x16x64_i8 v[114:117], v[164:167], v[196:199], v[114:117]
	v_mfma_i32_16x16x64_i8 v[106:109], v[156:159], v[204:207], v[106:109]
	v_mfma_i32_16x16x64_i8 v[98:101], v[164:167], v[204:207], v[98:101]
	v_mfma_i32_16x16x64_i8 v[90:93], v[156:159], v[212:215], v[90:93]
	v_mfma_i32_16x16x64_i8 v[82:85], v[164:167], v[212:215], v[82:85]
	v_mfma_i32_16x16x64_i8 v[110:113], v[168:171], v[184:187], v[110:113]
	v_mfma_i32_16x16x64_i8 v[102:105], v[176:179], v[184:187], v[102:105]
	v_mfma_i32_16x16x64_i8 v[94:97], v[168:171], v[192:195], v[94:97]
	v_mfma_i32_16x16x64_i8 v[86:89], v[176:179], v[192:195], v[86:89]
	v_mfma_i32_16x16x64_i8 v[78:81], v[168:171], v[200:203], v[78:81]
	v_mfma_i32_16x16x64_i8 v[74:77], v[176:179], v[200:203], v[74:77]
	v_mfma_i32_16x16x64_i8 v[70:73], v[168:171], v[208:211], v[70:73]
	v_mfma_i32_16x16x64_i8 v[66:69], v[176:179], v[208:211], v[66:69]
	v_mfma_i32_16x16x64_i8 v[110:113], v[172:175], v[188:191], v[110:113]
	v_mfma_i32_16x16x64_i8 v[102:105], v[180:183], v[188:191], v[102:105]
	v_mfma_i32_16x16x64_i8 v[94:97], v[172:175], v[196:199], v[94:97]
	v_mfma_i32_16x16x64_i8 v[86:89], v[180:183], v[196:199], v[86:89]
	v_mfma_i32_16x16x64_i8 v[78:81], v[172:175], v[204:207], v[78:81]
	v_mfma_i32_16x16x64_i8 v[74:77], v[180:183], v[204:207], v[74:77]
	v_mfma_i32_16x16x64_i8 v[70:73], v[172:175], v[212:215], v[70:73]
	v_mfma_i32_16x16x64_i8 v[66:69], v[180:183], v[212:215], v[66:69]
	s_barrier
	s_setprio 0
	s_add_i32 s30, s66, s38
	v_lshl_add_u64 v[152:153], v[152:153], 0, s[16:17]
	s_mov_b32 m0, s30
	ds_read_b128 v[184:187], v155 offset:49152
	ds_read_b128 v[188:191], v155 offset:50176
	ds_read_b128 v[192:195], v155 offset:51200
	ds_read_b128 v[196:199], v155 offset:52224
	ds_read_b128 v[200:203], v155 offset:53248
	ds_read_b128 v[204:207], v155 offset:54272
	ds_read_b128 v[208:211], v155 offset:55296
	ds_read_b128 v[212:215], v155 offset:56320
	global_load_lds_dwordx4 v[152:153], off
	v_lshl_add_u64 v[152:153], v[216:217], 0, s[16:17]
	s_add_i32 m0, s30, 0x2000
	s_add_i32 s30, s67, s38
	global_load_lds_dwordx4 v[152:153], off
	v_lshl_add_u64 v[152:153], v[218:219], 0, s[16:17]
	s_mov_b32 m0, s30
	s_nop 0
	global_load_lds_dwordx4 v[152:153], off
	v_lshl_add_u64 v[152:153], v[220:221], 0, s[16:17]
	s_add_i32 m0, s30, 0x2000
	s_nop 0
	global_load_lds_dwordx4 v[152:153], off
	v_lshl_add_u64 v[152:153], v[222:223], 0, s[16:17]
	s_mov_b32 m0, s47
	s_nop 0
	global_load_lds_dwordx4 v[152:153], off
	v_lshl_add_u64 v[152:153], v[224:225], 0, s[16:17]
	s_mov_b32 m0, s48
	s_nop 0
	global_load_lds_dwordx4 v[152:153], off
	s_waitcnt vmcnt(8)
	s_waitcnt lgkmcnt(0)
	s_barrier
	s_setprio 1
	v_mfma_i32_16x16x64_i8 v[62:65], v[148:151], v[184:187], v[62:65]
	v_mfma_i32_16x16x64_i8 v[58:61], v[160:163], v[184:187], v[58:61]
	v_mfma_i32_16x16x64_i8 v[54:57], v[148:151], v[192:195], v[54:57]
	v_mfma_i32_16x16x64_i8 v[50:53], v[160:163], v[192:195], v[50:53]
	v_mfma_i32_16x16x64_i8 v[42:45], v[148:151], v[200:203], v[42:45]
	v_mfma_i32_16x16x64_i8 v[34:37], v[160:163], v[200:203], v[34:37]
	v_mfma_i32_16x16x64_i8 v[26:29], v[148:151], v[208:211], v[26:29]
	v_mfma_i32_16x16x64_i8 v[18:21], v[160:163], v[208:211], v[18:21]
	v_mfma_i32_16x16x64_i8 v[62:65], v[156:159], v[188:191], v[62:65]
	v_mfma_i32_16x16x64_i8 v[58:61], v[164:167], v[188:191], v[58:61]
	v_mfma_i32_16x16x64_i8 v[54:57], v[156:159], v[196:199], v[54:57]
	v_mfma_i32_16x16x64_i8 v[50:53], v[164:167], v[196:199], v[50:53]
	v_mfma_i32_16x16x64_i8 v[42:45], v[156:159], v[204:207], v[42:45]
	v_mfma_i32_16x16x64_i8 v[34:37], v[164:167], v[204:207], v[34:37]
	v_mfma_i32_16x16x64_i8 v[26:29], v[156:159], v[212:215], v[26:29]
	v_mfma_i32_16x16x64_i8 v[18:21], v[164:167], v[212:215], v[18:21]
	v_mfma_i32_16x16x64_i8 v[46:49], v[168:171], v[184:187], v[46:49]
	v_mfma_i32_16x16x64_i8 v[38:41], v[176:179], v[184:187], v[38:41]
	v_mfma_i32_16x16x64_i8 v[30:33], v[168:171], v[192:195], v[30:33]
	v_mfma_i32_16x16x64_i8 v[22:25], v[176:179], v[192:195], v[22:25]
	v_mfma_i32_16x16x64_i8 v[14:17], v[168:171], v[200:203], v[14:17]
	v_mfma_i32_16x16x64_i8 v[10:13], v[176:179], v[200:203], v[10:13]
	v_mfma_i32_16x16x64_i8 v[6:9], v[168:171], v[208:211], v[6:9]
	v_mfma_i32_16x16x64_i8 v[2:5], v[176:179], v[208:211], v[2:5]
	v_mfma_i32_16x16x64_i8 v[46:49], v[172:175], v[188:191], v[46:49]
	v_mfma_i32_16x16x64_i8 v[38:41], v[180:183], v[188:191], v[38:41]
	v_mfma_i32_16x16x64_i8 v[30:33], v[172:175], v[196:199], v[30:33]
	v_mfma_i32_16x16x64_i8 v[22:25], v[180:183], v[196:199], v[22:25]
	v_mfma_i32_16x16x64_i8 v[14:17], v[172:175], v[204:207], v[14:17]
	v_mfma_i32_16x16x64_i8 v[10:13], v[180:183], v[204:207], v[10:13]
	v_mfma_i32_16x16x64_i8 v[6:9], v[172:175], v[212:215], v[6:9]
	v_mfma_i32_16x16x64_i8 v[2:5], v[180:183], v[212:215], v[2:5]
	s_barrier
	s_setprio 0
	s_add_u32 s28, s28, 0x100
	s_addc_u32 s29, s29, 0
	s_add_u32 s63, s63, 0x100
	s_addc_u32 s64, s64, 0
	s_cmp_ge_i32 s65, s49
	s_mov_b32 s30, s65
	s_cbranch_scc0 .LBB0_2025
	v_cvt_f32_i32_e32 v158, v126
	v_cvt_f32_i32_e32 v159, v127
	v_cvt_f32_i32_e32 v160, v128
	v_cvt_f32_i32_e32 v161, v129
	v_cvt_f32_i32_e32 v156, v122
	v_cvt_f32_i32_e32 v157, v123
	v_cvt_f32_i32_e32 v162, v124
	v_cvt_f32_i32_e32 v163, v125
	v_cvt_f32_i32_e32 v166, v110
	v_cvt_f32_i32_e32 v167, v111
	v_cvt_f32_i32_e32 v170, v112
	v_cvt_f32_i32_e32 v171, v113
	v_cvt_f32_i32_e32 v164, v102
	v_cvt_f32_i32_e32 v165, v103
	v_cvt_f32_i32_e32 v168, v104
	v_cvt_f32_i32_e32 v169, v105
	v_cvt_f32_i32_e32 v122, v118
	v_cvt_f32_i32_e32 v123, v119
	v_cvt_f32_i32_e32 v126, v120
	v_cvt_f32_i32_e32 v127, v121
	v_cvt_f32_i32_e32 v120, v114
	v_cvt_f32_i32_e32 v121, v115
	v_cvt_f32_i32_e32 v124, v116
	v_cvt_f32_i32_e32 v125, v117
	v_cvt_f32_i32_e32 v148, v94
	v_cvt_f32_i32_e32 v149, v95
	v_cvt_f32_i32_e32 v152, v96
	v_cvt_f32_i32_e32 v153, v97
	v_cvt_f32_i32_e32 v128, v86
	v_cvt_f32_i32_e32 v129, v87
	v_cvt_f32_i32_e32 v150, v88
	v_cvt_f32_i32_e32 v151, v89
	v_cvt_f32_i32_e32 v96, v106
	v_cvt_f32_i32_e32 v97, v107
	v_cvt_f32_i32_e32 v102, v108
	v_cvt_f32_i32_e32 v103, v109
	v_cvt_f32_i32_e32 v94, v98
	v_cvt_f32_i32_e32 v95, v99
	v_cvt_f32_i32_e32 v98, v100
	v_cvt_f32_i32_e32 v99, v101
	v_cvt_f32_i32_e32 v110, v78
	v_cvt_f32_i32_e32 v111, v79
	v_cvt_f32_i32_e32 v114, v80
	v_cvt_f32_i32_e32 v115, v81
	v_cvt_f32_i32_e32 v108, v74
	v_cvt_f32_i32_e32 v109, v75
	v_cvt_f32_i32_e32 v112, v76
	v_cvt_f32_i32_e32 v113, v77
	v_cvt_f32_i32_e32 v80, v90
	v_cvt_f32_i32_e32 v81, v91
	v_cvt_f32_i32_e32 v86, v92
	v_cvt_f32_i32_e32 v87, v93
	v_cvt_f32_i32_e32 v78, v82
	v_cvt_f32_i32_e32 v79, v83
	v_cvt_f32_i32_e32 v82, v84
	v_cvt_f32_i32_e32 v83, v85
	v_cvt_f32_i32_e32 v88, v70
	v_cvt_f32_i32_e32 v89, v71
	v_cvt_f32_i32_e32 v92, v72
	v_cvt_f32_i32_e32 v93, v73
	v_cvt_f32_i32_e32 v84, v66
	v_cvt_f32_i32_e32 v85, v67
	v_cvt_f32_i32_e32 v90, v68
	v_cvt_f32_i32_e32 v91, v69
	v_cvt_f32_i32_e32 v66, v62
	v_cvt_f32_i32_e32 v67, v63
	v_cvt_f32_i32_e32 v68, v64
	v_cvt_f32_i32_e32 v69, v65
	v_cvt_f32_i32_e32 v62, v58
	v_cvt_f32_i32_e32 v63, v59
	v_cvt_f32_i32_e32 v64, v60
	v_cvt_f32_i32_e32 v65, v61
	v_cvt_f32_i32_e32 v72, v46
	v_cvt_f32_i32_e32 v73, v47
	v_cvt_f32_i32_e32 v76, v48
	v_cvt_f32_i32_e32 v77, v49
	v_cvt_f32_i32_e32 v70, v38
	v_cvt_f32_i32_e32 v71, v39
	v_cvt_f32_i32_e32 v74, v40
	v_cvt_f32_i32_e32 v75, v41
	v_cvt_f32_i32_e32 v48, v54
	v_cvt_f32_i32_e32 v49, v55
	v_cvt_f32_i32_e32 v54, v56
	v_cvt_f32_i32_e32 v55, v57
	v_cvt_f32_i32_e32 v46, v50
	v_cvt_f32_i32_e32 v47, v51
	v_cvt_f32_i32_e32 v50, v52
	v_cvt_f32_i32_e32 v51, v53
	v_cvt_f32_i32_e32 v56, v30
	v_cvt_f32_i32_e32 v57, v31
	v_cvt_f32_i32_e32 v60, v32
	v_cvt_f32_i32_e32 v61, v33
	v_cvt_f32_i32_e32 v52, v22
	v_cvt_f32_i32_e32 v53, v23
	v_cvt_f32_i32_e32 v58, v24
	v_cvt_f32_i32_e32 v59, v25
	v_cvt_f32_i32_e32 v24, v42
	v_cvt_f32_i32_e32 v25, v43
	v_cvt_f32_i32_e32 v32, v44
	v_cvt_f32_i32_e32 v33, v45
	v_cvt_f32_i32_e32 v22, v34
	v_cvt_f32_i32_e32 v23, v35
	v_cvt_f32_i32_e32 v30, v36
	v_cvt_f32_i32_e32 v31, v37
	v_cvt_f32_i32_e32 v36, v14
	v_cvt_f32_i32_e32 v37, v15
	v_cvt_f32_i32_e32 v40, v16
	v_cvt_f32_i32_e32 v41, v17
	v_cvt_f32_i32_e32 v34, v10
	v_cvt_f32_i32_e32 v35, v11
	v_cvt_f32_i32_e32 v38, v12
	v_cvt_f32_i32_e32 v39, v13
	v_cvt_f32_i32_e32 v12, v26
	v_cvt_f32_i32_e32 v13, v27
	v_cvt_f32_i32_e32 v16, v28
	v_cvt_f32_i32_e32 v17, v29
	v_cvt_f32_i32_e32 v10, v18
	v_cvt_f32_i32_e32 v11, v19
	v_cvt_f32_i32_e32 v14, v20
	v_cvt_f32_i32_e32 v15, v21
	v_cvt_f32_i32_e32 v6, v6
	v_cvt_f32_i32_e32 v7, v7
	v_cvt_f32_i32_e32 v8, v8
	v_cvt_f32_i32_e32 v9, v9
	v_cvt_f32_i32_e32 v2, v2
	v_cvt_f32_i32_e32 v3, v3
	v_cvt_f32_i32_e32 v4, v4
	v_cvt_f32_i32_e32 v5, v5
